# new k-loop on all 16 loop-form GEMM phases (RES_MIX, RES_FFN, LRU_IN, MLA_IN, DIFF_IN, GQA_IN added)
# speedup vs baseline: 1.3208x; 1.0278x over previous
.LBB0_258:
	s_mul_hi_i32 s4, s3, 0x2aaaaaab
	s_lshr_b32 s5, s4, 31
	s_ashr_i32 s4, s4, 3
	s_add_i32 s4, s4, s5
	s_mul_i32 s95, s4, 0xffffffd0
	s_add_i32 s95, s95, s3
	s_lshl_b32 s5, s4, 3
	s_ashr_i32 s4, s95, 31
	s_lshr_b32 s4, s4, 29
	s_add_i32 s4, s95, s4
	s_ashr_i32 s10, s4, 3
	s_and_b32 s4, s4, -8
	s_sub_i32 s8, s95, s4
	s_add_i32 s8, s8, s5
	s_lshl_b32 s76, s8, 7
	s_ashr_i32 s77, s76, 31
	s_lshl_b32 s78, s10, 7
	s_lshl_b64 s[4:5], s[76:77], 11
	s_ashr_i32 s79, s78, 31
	s_lshl_b32 s56, s76, 11
	s_add_u32 s38, s14, s56
	s_addc_u32 s39, s15, 0
	s_add_u32 s38, s38, 0x679f000
	s_addc_u32 s39, s39, 0
	s_add_u32 s40, s38, 0x10000
	s_addc_u32 s41, s39, 0
	s_add_u32 s42, s40, 0x10000
	s_addc_u32 s43, s41, 0
	s_add_u32 s44, s42, 0x10000
	s_addc_u32 s45, s43, 0
	s_lshl_b32 s56, s78, 11
	s_add_u32 s46, s14, s56
	s_addc_u32 s47, s15, 0
	s_add_u32 s46, s46, 0x0
	s_addc_u32 s47, s47, 0
	s_add_u32 s48, s46, 0x10000
	s_addc_u32 s49, s47, 0
	s_add_u32 s50, s48, 0x10000
	s_addc_u32 s51, s49, 0
	s_add_u32 s52, s50, 0x10000
	s_addc_u32 s53, s51, 0
	v_add_u32_e32 v221, v169, v168
	v_add_u32_e32 v226, v167, v170
	v_add_u32_e32 v227, v169, v170
	v_add_u32_e32 v229, v167, v171
	v_add_u32_e32 v255, v169, v171
	v_add_u32_e32 v162, v167, v172
	v_add_u32_e32 v163, v169, v172
	v_readfirstlane_b32 s54, v192
	v_mov_b32_e32 v254, v158
	s_mov_b32 m0, s54
	s_nop 0
	global_load_lds_dwordx4 v254, s[38:39]
	s_add_u32 m0, m0, 0x1000
	s_nop 0
	global_load_lds_dwordx4 v254, s[40:41]
	s_add_u32 m0, m0, 0x1000
	s_nop 0
	global_load_lds_dwordx4 v254, s[42:43]
	s_add_u32 m0, m0, 0x1000
	s_nop 0
	global_load_lds_dwordx4 v254, s[44:45]
	s_add_u32 m0, m0, 0x1000
	s_nop 0
	global_load_lds_dwordx4 v254, s[46:47]
	s_add_u32 m0, m0, 0x1000
	s_nop 0
	global_load_lds_dwordx4 v254, s[48:49]
	s_add_u32 m0, m0, 0x1000
	s_nop 0
	global_load_lds_dwordx4 v254, s[50:51]
	s_add_u32 m0, m0, 0x1000
	s_nop 0
	global_load_lds_dwordx4 v254, s[52:53]
	v_add_u32_e32 v254, 0x80, v254
	s_add_u32 m0, s54, 0x8000
	s_nop 0
	global_load_lds_dwordx4 v254, s[38:39]
	s_add_u32 m0, m0, 0x1000
	s_nop 0
	global_load_lds_dwordx4 v254, s[40:41]
	s_add_u32 m0, m0, 0x1000
	s_nop 0
	global_load_lds_dwordx4 v254, s[42:43]
	s_add_u32 m0, m0, 0x1000
	s_nop 0
	global_load_lds_dwordx4 v254, s[44:45]
	s_add_u32 m0, m0, 0x1000
	s_nop 0
	global_load_lds_dwordx4 v254, s[46:47]
	s_add_u32 m0, m0, 0x1000
	s_nop 0
	global_load_lds_dwordx4 v254, s[48:49]
	s_add_u32 m0, m0, 0x1000
	s_nop 0
	global_load_lds_dwordx4 v254, s[50:51]
	s_add_u32 m0, m0, 0x1000
	s_nop 0
	global_load_lds_dwordx4 v254, s[52:53]
	v_add_u32_e32 v254, 0x80, v254
	v_mov_b32_e32 v48, 0
	v_mov_b32_e32 v49, 0
	v_mov_b32_e32 v50, 0
	v_mov_b32_e32 v51, 0
	v_mov_b32_e32 v52, 0
	v_mov_b32_e32 v53, 0
	v_mov_b32_e32 v54, 0
	v_mov_b32_e32 v55, 0
	v_mov_b32_e32 v56, 0
	v_mov_b32_e32 v57, 0
	v_mov_b32_e32 v58, 0
	v_mov_b32_e32 v59, 0
	v_mov_b32_e32 v60, 0
	v_mov_b32_e32 v61, 0
	v_mov_b32_e32 v62, 0
	v_mov_b32_e32 v63, 0
	v_mov_b32_e32 v32, 0
	v_mov_b32_e32 v33, 0
	v_mov_b32_e32 v34, 0
	v_mov_b32_e32 v35, 0
	v_mov_b32_e32 v36, 0
	v_mov_b32_e32 v37, 0
	v_mov_b32_e32 v38, 0
	v_mov_b32_e32 v39, 0
	v_mov_b32_e32 v40, 0
	v_mov_b32_e32 v41, 0
	v_mov_b32_e32 v42, 0
	v_mov_b32_e32 v43, 0
	v_mov_b32_e32 v44, 0
	v_mov_b32_e32 v45, 0
	v_mov_b32_e32 v46, 0
	v_mov_b32_e32 v47, 0
	v_mov_b32_e32 v16, 0
	v_mov_b32_e32 v17, 0
	v_mov_b32_e32 v18, 0
	v_mov_b32_e32 v19, 0
	v_mov_b32_e32 v20, 0
	v_mov_b32_e32 v21, 0
	v_mov_b32_e32 v22, 0
	v_mov_b32_e32 v23, 0
	v_mov_b32_e32 v24, 0
	v_mov_b32_e32 v25, 0
	v_mov_b32_e32 v26, 0
	v_mov_b32_e32 v27, 0
	v_mov_b32_e32 v28, 0
	v_mov_b32_e32 v29, 0
	v_mov_b32_e32 v30, 0
	v_mov_b32_e32 v31, 0
	v_mov_b32_e32 v0, 0
	v_mov_b32_e32 v1, 0
	v_mov_b32_e32 v2, 0
	v_mov_b32_e32 v3, 0
	v_mov_b32_e32 v4, 0
	v_mov_b32_e32 v5, 0
	v_mov_b32_e32 v6, 0
	v_mov_b32_e32 v7, 0
	v_mov_b32_e32 v8, 0
	v_mov_b32_e32 v9, 0
	v_mov_b32_e32 v10, 0
	v_mov_b32_e32 v11, 0
	v_mov_b32_e32 v12, 0
	v_mov_b32_e32 v13, 0
	v_mov_b32_e32 v14, 0
	v_mov_b32_e32 v15, 0
	s_mov_b32 s55, 7
.Lgk_loop_p2:
	s_waitcnt vmcnt(8)
	s_barrier
	ds_read_b128 v[64:67], v213
	ds_read_b128 v[76:79], v221 offset:16384
	ds_read_b128 v[80:83], v221 offset:20480
	ds_read_b128 v[84:87], v221 offset:24576
	ds_read_b128 v[88:91], v221 offset:28672
	ds_read_b128 v[92:95], v226
	ds_read_b128 v[96:99], v227 offset:16384
	ds_read_b128 v[100:103], v227 offset:20480
	ds_read_b128 v[104:107], v227 offset:24576
	ds_read_b128 v[108:111], v227 offset:28672
	ds_read_b128 v[112:115], v229
	ds_read_b128 v[222:225], v255 offset:16384
	ds_read_b128 v[230:233], v255 offset:20480
	ds_read_b128 v[234:237], v255 offset:24576
	ds_read_b128 v[238:241], v255 offset:28672
	ds_read_b128 v[242:245], v162
	ds_read_b128 v[246:249], v163 offset:16384
	ds_read_b128 v[250:253], v163 offset:20480
	ds_read_b128 v[194:197], v163 offset:24576
	ds_read_b128 v[202:205], v163 offset:28672
	s_waitcnt lgkmcnt(0)
	s_barrier
	s_mov_b32 m0, s54
	s_setprio 1
	v_mfma_f32_32x32x16_bf16 v[48:63], v[64:67], v[76:79], v[48:63]
	v_mfma_f32_32x32x16_bf16 v[32:47], v[64:67], v[80:83], v[32:47]
	global_load_lds_dwordx4 v254, s[38:39]
	s_add_u32 m0, m0, 0x1000
	v_mfma_f32_32x32x16_bf16 v[16:31], v[64:67], v[84:87], v[16:31]
	v_mfma_f32_32x32x16_bf16 v[0:15], v[64:67], v[88:91], v[0:15]
	global_load_lds_dwordx4 v254, s[40:41]
	s_add_u32 m0, m0, 0x1000
	v_mfma_f32_32x32x16_bf16 v[48:63], v[92:95], v[96:99], v[48:63]
	v_mfma_f32_32x32x16_bf16 v[32:47], v[92:95], v[100:103], v[32:47]
	global_load_lds_dwordx4 v254, s[42:43]
	s_add_u32 m0, m0, 0x1000
	v_mfma_f32_32x32x16_bf16 v[16:31], v[92:95], v[104:107], v[16:31]
	v_mfma_f32_32x32x16_bf16 v[0:15], v[92:95], v[108:111], v[0:15]
	global_load_lds_dwordx4 v254, s[44:45]
	s_add_u32 m0, m0, 0x1000
	v_mfma_f32_32x32x16_bf16 v[48:63], v[112:115], v[222:225], v[48:63]
	v_mfma_f32_32x32x16_bf16 v[32:47], v[112:115], v[230:233], v[32:47]
	global_load_lds_dwordx4 v254, s[46:47]
	s_add_u32 m0, m0, 0x1000
	v_mfma_f32_32x32x16_bf16 v[16:31], v[112:115], v[234:237], v[16:31]
	v_mfma_f32_32x32x16_bf16 v[0:15], v[112:115], v[238:241], v[0:15]
	global_load_lds_dwordx4 v254, s[48:49]
	s_add_u32 m0, m0, 0x1000
	v_mfma_f32_32x32x16_bf16 v[48:63], v[242:245], v[246:249], v[48:63]
	v_mfma_f32_32x32x16_bf16 v[32:47], v[242:245], v[250:253], v[32:47]
	global_load_lds_dwordx4 v254, s[50:51]
	s_add_u32 m0, m0, 0x1000
	v_mfma_f32_32x32x16_bf16 v[16:31], v[242:245], v[194:197], v[16:31]
	v_mfma_f32_32x32x16_bf16 v[0:15], v[242:245], v[202:205], v[0:15]
	global_load_lds_dwordx4 v254, s[52:53]
	s_setprio 0
	v_add_u32_e32 v254, 0x80, v254
	s_waitcnt vmcnt(8)
	s_barrier
	ds_read_b128 v[64:67], v213 offset:32768
	ds_read_b128 v[76:79], v221 offset:49152
	ds_read_b128 v[80:83], v221 offset:53248
	ds_read_b128 v[84:87], v221 offset:57344
	ds_read_b128 v[88:91], v221 offset:61440
	ds_read_b128 v[92:95], v226 offset:32768
	ds_read_b128 v[96:99], v227 offset:49152
	ds_read_b128 v[100:103], v227 offset:53248
	ds_read_b128 v[104:107], v227 offset:57344
	ds_read_b128 v[108:111], v227 offset:61440
	ds_read_b128 v[112:115], v229 offset:32768
	ds_read_b128 v[222:225], v255 offset:49152
	ds_read_b128 v[230:233], v255 offset:53248
	ds_read_b128 v[234:237], v255 offset:57344
	ds_read_b128 v[238:241], v255 offset:61440
	ds_read_b128 v[242:245], v162 offset:32768
	ds_read_b128 v[246:249], v163 offset:49152
	ds_read_b128 v[250:253], v163 offset:53248
	ds_read_b128 v[194:197], v163 offset:57344
	ds_read_b128 v[202:205], v163 offset:61440
	s_waitcnt lgkmcnt(0)
	s_barrier
	s_add_u32 m0, s54, 0x8000
	s_setprio 1
	v_mfma_f32_32x32x16_bf16 v[48:63], v[64:67], v[76:79], v[48:63]
	v_mfma_f32_32x32x16_bf16 v[32:47], v[64:67], v[80:83], v[32:47]
	global_load_lds_dwordx4 v254, s[38:39]
	s_add_u32 m0, m0, 0x1000
	v_mfma_f32_32x32x16_bf16 v[16:31], v[64:67], v[84:87], v[16:31]
	v_mfma_f32_32x32x16_bf16 v[0:15], v[64:67], v[88:91], v[0:15]
	global_load_lds_dwordx4 v254, s[40:41]
	s_add_u32 m0, m0, 0x1000
	v_mfma_f32_32x32x16_bf16 v[48:63], v[92:95], v[96:99], v[48:63]
	v_mfma_f32_32x32x16_bf16 v[32:47], v[92:95], v[100:103], v[32:47]
	global_load_lds_dwordx4 v254, s[42:43]
	s_add_u32 m0, m0, 0x1000
	v_mfma_f32_32x32x16_bf16 v[16:31], v[92:95], v[104:107], v[16:31]
	v_mfma_f32_32x32x16_bf16 v[0:15], v[92:95], v[108:111], v[0:15]
	global_load_lds_dwordx4 v254, s[44:45]
	s_add_u32 m0, m0, 0x1000
	v_mfma_f32_32x32x16_bf16 v[48:63], v[112:115], v[222:225], v[48:63]
	v_mfma_f32_32x32x16_bf16 v[32:47], v[112:115], v[230:233], v[32:47]
	global_load_lds_dwordx4 v254, s[46:47]
	s_add_u32 m0, m0, 0x1000
	v_mfma_f32_32x32x16_bf16 v[16:31], v[112:115], v[234:237], v[16:31]
	v_mfma_f32_32x32x16_bf16 v[0:15], v[112:115], v[238:241], v[0:15]
	global_load_lds_dwordx4 v254, s[48:49]
	s_add_u32 m0, m0, 0x1000
	v_mfma_f32_32x32x16_bf16 v[48:63], v[242:245], v[246:249], v[48:63]
	v_mfma_f32_32x32x16_bf16 v[32:47], v[242:245], v[250:253], v[32:47]
	global_load_lds_dwordx4 v254, s[50:51]
	s_add_u32 m0, m0, 0x1000
	v_mfma_f32_32x32x16_bf16 v[16:31], v[242:245], v[194:197], v[16:31]
	v_mfma_f32_32x32x16_bf16 v[0:15], v[242:245], v[202:205], v[0:15]
	global_load_lds_dwordx4 v254, s[52:53]
	s_setprio 0
	v_add_u32_e32 v254, 0x80, v254
	s_sub_u32 s55, s55, 1
	s_cmp_lg_u32 s55, 0
	s_cbranch_scc1 .Lgk_loop_p2
	s_waitcnt vmcnt(8)
	s_barrier
	ds_read_b128 v[64:67], v213
	ds_read_b128 v[76:79], v221 offset:16384
	ds_read_b128 v[80:83], v221 offset:20480
	ds_read_b128 v[84:87], v221 offset:24576
	ds_read_b128 v[88:91], v221 offset:28672
	ds_read_b128 v[92:95], v226
	ds_read_b128 v[96:99], v227 offset:16384
	ds_read_b128 v[100:103], v227 offset:20480
	ds_read_b128 v[104:107], v227 offset:24576
	ds_read_b128 v[108:111], v227 offset:28672
	ds_read_b128 v[112:115], v229
	ds_read_b128 v[222:225], v255 offset:16384
	ds_read_b128 v[230:233], v255 offset:20480
	ds_read_b128 v[234:237], v255 offset:24576
	ds_read_b128 v[238:241], v255 offset:28672
	ds_read_b128 v[242:245], v162
	ds_read_b128 v[246:249], v163 offset:16384
	ds_read_b128 v[250:253], v163 offset:20480
	ds_read_b128 v[194:197], v163 offset:24576
	ds_read_b128 v[202:205], v163 offset:28672
	s_waitcnt lgkmcnt(0)
	s_barrier
	s_setprio 1
	v_mfma_f32_32x32x16_bf16 v[48:63], v[64:67], v[76:79], v[48:63]
	v_mfma_f32_32x32x16_bf16 v[32:47], v[64:67], v[80:83], v[32:47]
	v_mfma_f32_32x32x16_bf16 v[16:31], v[64:67], v[84:87], v[16:31]
	v_mfma_f32_32x32x16_bf16 v[0:15], v[64:67], v[88:91], v[0:15]
	v_mfma_f32_32x32x16_bf16 v[48:63], v[92:95], v[96:99], v[48:63]
	v_mfma_f32_32x32x16_bf16 v[32:47], v[92:95], v[100:103], v[32:47]
	v_mfma_f32_32x32x16_bf16 v[16:31], v[92:95], v[104:107], v[16:31]
	v_mfma_f32_32x32x16_bf16 v[0:15], v[92:95], v[108:111], v[0:15]
	v_mfma_f32_32x32x16_bf16 v[48:63], v[112:115], v[222:225], v[48:63]
	v_mfma_f32_32x32x16_bf16 v[32:47], v[112:115], v[230:233], v[32:47]
	v_mfma_f32_32x32x16_bf16 v[16:31], v[112:115], v[234:237], v[16:31]
	v_mfma_f32_32x32x16_bf16 v[0:15], v[112:115], v[238:241], v[0:15]
	v_mfma_f32_32x32x16_bf16 v[48:63], v[242:245], v[246:249], v[48:63]
	v_mfma_f32_32x32x16_bf16 v[32:47], v[242:245], v[250:253], v[32:47]
	v_mfma_f32_32x32x16_bf16 v[16:31], v[242:245], v[194:197], v[16:31]
	v_mfma_f32_32x32x16_bf16 v[0:15], v[242:245], v[202:205], v[0:15]
	s_setprio 0
	s_waitcnt vmcnt(0)
	s_barrier
	ds_read_b128 v[64:67], v213 offset:32768
	ds_read_b128 v[76:79], v221 offset:49152
	ds_read_b128 v[80:83], v221 offset:53248
	ds_read_b128 v[84:87], v221 offset:57344
	ds_read_b128 v[88:91], v221 offset:61440
	ds_read_b128 v[92:95], v226 offset:32768
	ds_read_b128 v[96:99], v227 offset:49152
	ds_read_b128 v[100:103], v227 offset:53248
	ds_read_b128 v[104:107], v227 offset:57344
	ds_read_b128 v[108:111], v227 offset:61440
	ds_read_b128 v[112:115], v229 offset:32768
	ds_read_b128 v[222:225], v255 offset:49152
	ds_read_b128 v[230:233], v255 offset:53248
	ds_read_b128 v[234:237], v255 offset:57344
	ds_read_b128 v[238:241], v255 offset:61440
	ds_read_b128 v[242:245], v162 offset:32768
	ds_read_b128 v[246:249], v163 offset:49152
	ds_read_b128 v[250:253], v163 offset:53248
	ds_read_b128 v[194:197], v163 offset:57344
	ds_read_b128 v[202:205], v163 offset:61440
	s_waitcnt lgkmcnt(0)
	s_barrier
	s_setprio 1
	v_mfma_f32_32x32x16_bf16 v[48:63], v[64:67], v[76:79], v[48:63]
	v_mfma_f32_32x32x16_bf16 v[32:47], v[64:67], v[80:83], v[32:47]
	v_mfma_f32_32x32x16_bf16 v[16:31], v[64:67], v[84:87], v[16:31]
	v_mfma_f32_32x32x16_bf16 v[0:15], v[64:67], v[88:91], v[0:15]
	v_mfma_f32_32x32x16_bf16 v[48:63], v[92:95], v[96:99], v[48:63]
	v_mfma_f32_32x32x16_bf16 v[32:47], v[92:95], v[100:103], v[32:47]
	v_mfma_f32_32x32x16_bf16 v[16:31], v[92:95], v[104:107], v[16:31]
	v_mfma_f32_32x32x16_bf16 v[0:15], v[92:95], v[108:111], v[0:15]
	v_mfma_f32_32x32x16_bf16 v[48:63], v[112:115], v[222:225], v[48:63]
	v_mfma_f32_32x32x16_bf16 v[32:47], v[112:115], v[230:233], v[32:47]
	v_mfma_f32_32x32x16_bf16 v[16:31], v[112:115], v[234:237], v[16:31]
	v_mfma_f32_32x32x16_bf16 v[0:15], v[112:115], v[238:241], v[0:15]
	v_mfma_f32_32x32x16_bf16 v[48:63], v[242:245], v[246:249], v[48:63]
	v_mfma_f32_32x32x16_bf16 v[32:47], v[242:245], v[250:253], v[32:47]
	v_mfma_f32_32x32x16_bf16 v[16:31], v[242:245], v[194:197], v[16:31]
	v_mfma_f32_32x32x16_bf16 v[0:15], v[242:245], v[202:205], v[0:15]
	s_setprio 0
	s_branch .LBB0_262

.LBB0_703:
	s_ashr_i32 s6, s3, 31
	s_lshr_b32 s6, s6, 26
	s_add_i32 s6, s3, s6
	s_ashr_i32 s58, s6, 6
	s_andn2_b32 s6, s6, 63
	s_sub_i32 s6, s3, s6
	s_ashr_i32 s59, s6, 31
	s_lshr_b32 s59, s59, 29
	s_add_i32 s59, s6, s59
	s_ashr_i32 s69, s59, 3
	s_and_b32 s59, s59, -8
	s_lshl_b32 s58, s58, 3
	s_sub_i32 s6, s6, s59
	s_add_i32 s6, s6, s58
	s_lshl_b32 s64, s6, 7
	s_ashr_i32 s65, s64, 31
	s_lshl_b32 s66, s69, 7
	s_lshl_b64 s[58:59], s[64:65], 11
	s_ashr_i32 s67, s66, 31
	s_lshl_b32 s38, s64, 11
	s_add_u32 s18, s14, s38
	s_addc_u32 s19, s15, 0
	s_add_u32 s18, s18, 0xb79f000
	s_addc_u32 s19, s19, 0
	s_add_u32 s20, s18, 0x10000
	s_addc_u32 s21, s19, 0
	s_add_u32 s22, s20, 0x10000
	s_addc_u32 s23, s21, 0
	s_add_u32 s24, s22, 0x10000
	s_addc_u32 s25, s23, 0
	s_lshl_b32 s38, s66, 11
	s_add_u32 s26, s14, s38
	s_addc_u32 s27, s15, 0
	s_add_u32 s26, s26, 0x3a0000
	s_addc_u32 s27, s27, 0
	s_add_u32 s28, s26, 0x10000
	s_addc_u32 s29, s27, 0
	s_add_u32 s30, s28, 0x10000
	s_addc_u32 s31, s29, 0
	s_add_u32 s34, s30, 0x10000
	s_addc_u32 s35, s31, 0
	v_readfirstlane_b32 s36, v142
	v_mov_b32_e32 v254, v64
	s_mov_b32 m0, s36
	s_nop 0
	global_load_lds_dwordx4 v254, s[18:19]
	s_add_u32 m0, m0, 0x1000
	s_nop 0
	global_load_lds_dwordx4 v254, s[20:21]
	s_add_u32 m0, m0, 0x1000
	s_nop 0
	global_load_lds_dwordx4 v254, s[22:23]
	s_add_u32 m0, m0, 0x1000
	s_nop 0
	global_load_lds_dwordx4 v254, s[24:25]
	s_add_u32 m0, m0, 0x1000
	s_nop 0
	global_load_lds_dwordx4 v254, s[26:27]
	s_add_u32 m0, m0, 0x1000
	s_nop 0
	global_load_lds_dwordx4 v254, s[28:29]
	s_add_u32 m0, m0, 0x1000
	s_nop 0
	global_load_lds_dwordx4 v254, s[30:31]
	s_add_u32 m0, m0, 0x1000
	s_nop 0
	global_load_lds_dwordx4 v254, s[34:35]
	v_add_u32_e32 v254, 0x80, v254
	s_add_u32 m0, s36, 0x8000
	s_nop 0
	global_load_lds_dwordx4 v254, s[18:19]
	s_add_u32 m0, m0, 0x1000
	s_nop 0
	global_load_lds_dwordx4 v254, s[20:21]
	s_add_u32 m0, m0, 0x1000
	s_nop 0
	global_load_lds_dwordx4 v254, s[22:23]
	s_add_u32 m0, m0, 0x1000
	s_nop 0
	global_load_lds_dwordx4 v254, s[24:25]
	s_add_u32 m0, m0, 0x1000
	s_nop 0
	global_load_lds_dwordx4 v254, s[26:27]
	s_add_u32 m0, m0, 0x1000
	s_nop 0
	global_load_lds_dwordx4 v254, s[28:29]
	s_add_u32 m0, m0, 0x1000
	s_nop 0
	global_load_lds_dwordx4 v254, s[30:31]
	s_add_u32 m0, m0, 0x1000
	s_nop 0
	global_load_lds_dwordx4 v254, s[34:35]
	v_add_u32_e32 v254, 0x80, v254
	v_mov_b32_e32 v48, 0
	v_mov_b32_e32 v49, 0
	v_mov_b32_e32 v50, 0
	v_mov_b32_e32 v51, 0
	v_mov_b32_e32 v52, 0
	v_mov_b32_e32 v53, 0
	v_mov_b32_e32 v54, 0
	v_mov_b32_e32 v55, 0
	v_mov_b32_e32 v56, 0
	v_mov_b32_e32 v57, 0
	v_mov_b32_e32 v58, 0
	v_mov_b32_e32 v59, 0
	v_mov_b32_e32 v60, 0
	v_mov_b32_e32 v61, 0
	v_mov_b32_e32 v62, 0
	v_mov_b32_e32 v63, 0
	v_mov_b32_e32 v32, 0
	v_mov_b32_e32 v33, 0
	v_mov_b32_e32 v34, 0
	v_mov_b32_e32 v35, 0
	v_mov_b32_e32 v36, 0
	v_mov_b32_e32 v37, 0
	v_mov_b32_e32 v38, 0
	v_mov_b32_e32 v39, 0
	v_mov_b32_e32 v40, 0
	v_mov_b32_e32 v41, 0
	v_mov_b32_e32 v42, 0
	v_mov_b32_e32 v43, 0
	v_mov_b32_e32 v44, 0
	v_mov_b32_e32 v45, 0
	v_mov_b32_e32 v46, 0
	v_mov_b32_e32 v47, 0
	v_mov_b32_e32 v16, 0
	v_mov_b32_e32 v17, 0
	v_mov_b32_e32 v18, 0
	v_mov_b32_e32 v19, 0
	v_mov_b32_e32 v20, 0
	v_mov_b32_e32 v21, 0
	v_mov_b32_e32 v22, 0
	v_mov_b32_e32 v23, 0
	v_mov_b32_e32 v24, 0
	v_mov_b32_e32 v25, 0
	v_mov_b32_e32 v26, 0
	v_mov_b32_e32 v27, 0
	v_mov_b32_e32 v28, 0
	v_mov_b32_e32 v29, 0
	v_mov_b32_e32 v30, 0
	v_mov_b32_e32 v31, 0
	v_mov_b32_e32 v0, 0
	v_mov_b32_e32 v1, 0
	v_mov_b32_e32 v2, 0
	v_mov_b32_e32 v3, 0
	v_mov_b32_e32 v4, 0
	v_mov_b32_e32 v5, 0
	v_mov_b32_e32 v6, 0
	v_mov_b32_e32 v7, 0
	v_mov_b32_e32 v8, 0
	v_mov_b32_e32 v9, 0
	v_mov_b32_e32 v10, 0
	v_mov_b32_e32 v11, 0
	v_mov_b32_e32 v12, 0
	v_mov_b32_e32 v13, 0
	v_mov_b32_e32 v14, 0
	v_mov_b32_e32 v15, 0
	s_mov_b32 s37, 7
.Lgk_loop_p6:
	s_waitcnt vmcnt(8)
	s_barrier
	ds_read_b128 v[70:73], v158
	ds_read_b128 v[74:77], v159 offset:16384
	ds_read_b128 v[78:81], v159 offset:20480
	ds_read_b128 v[82:85], v159 offset:24576
	ds_read_b128 v[86:89], v159 offset:28672
	ds_read_b128 v[90:93], v160
	ds_read_b128 v[94:97], v161 offset:16384
	ds_read_b128 v[98:101], v161 offset:20480
	ds_read_b128 v[102:105], v161 offset:24576
	ds_read_b128 v[106:109], v161 offset:28672
	ds_read_b128 v[110:113], v162
	ds_read_b128 v[206:209], v163 offset:16384
	ds_read_b128 v[210:213], v163 offset:20480
	ds_read_b128 v[214:217], v163 offset:24576
	ds_read_b128 v[218:221], v163 offset:28672
	ds_read_b128 v[222:225], v164
	ds_read_b128 v[226:229], v165 offset:16384
	ds_read_b128 v[230:233], v165 offset:20480
	ds_read_b128 v[234:237], v165 offset:24576
	ds_read_b128 v[238:241], v165 offset:28672
	s_waitcnt lgkmcnt(0)
	s_barrier
	s_mov_b32 m0, s36
	s_setprio 1
	v_mfma_f32_32x32x16_bf16 v[48:63], v[70:73], v[74:77], v[48:63]
	v_mfma_f32_32x32x16_bf16 v[32:47], v[70:73], v[78:81], v[32:47]
	global_load_lds_dwordx4 v254, s[18:19]
	s_add_u32 m0, m0, 0x1000
	v_mfma_f32_32x32x16_bf16 v[16:31], v[70:73], v[82:85], v[16:31]
	v_mfma_f32_32x32x16_bf16 v[0:15], v[70:73], v[86:89], v[0:15]
	global_load_lds_dwordx4 v254, s[20:21]
	s_add_u32 m0, m0, 0x1000
	v_mfma_f32_32x32x16_bf16 v[48:63], v[90:93], v[94:97], v[48:63]
	v_mfma_f32_32x32x16_bf16 v[32:47], v[90:93], v[98:101], v[32:47]
	global_load_lds_dwordx4 v254, s[22:23]
	s_add_u32 m0, m0, 0x1000
	v_mfma_f32_32x32x16_bf16 v[16:31], v[90:93], v[102:105], v[16:31]
	v_mfma_f32_32x32x16_bf16 v[0:15], v[90:93], v[106:109], v[0:15]
	global_load_lds_dwordx4 v254, s[24:25]
	s_add_u32 m0, m0, 0x1000
	v_mfma_f32_32x32x16_bf16 v[48:63], v[110:113], v[206:209], v[48:63]
	v_mfma_f32_32x32x16_bf16 v[32:47], v[110:113], v[210:213], v[32:47]
	global_load_lds_dwordx4 v254, s[26:27]
	s_add_u32 m0, m0, 0x1000
	v_mfma_f32_32x32x16_bf16 v[16:31], v[110:113], v[214:217], v[16:31]
	v_mfma_f32_32x32x16_bf16 v[0:15], v[110:113], v[218:221], v[0:15]
	global_load_lds_dwordx4 v254, s[28:29]
	s_add_u32 m0, m0, 0x1000
	v_mfma_f32_32x32x16_bf16 v[48:63], v[222:225], v[226:229], v[48:63]
	v_mfma_f32_32x32x16_bf16 v[32:47], v[222:225], v[230:233], v[32:47]
	global_load_lds_dwordx4 v254, s[30:31]
	s_add_u32 m0, m0, 0x1000
	v_mfma_f32_32x32x16_bf16 v[16:31], v[222:225], v[234:237], v[16:31]
	v_mfma_f32_32x32x16_bf16 v[0:15], v[222:225], v[238:241], v[0:15]
	global_load_lds_dwordx4 v254, s[34:35]
	s_setprio 0
	v_add_u32_e32 v254, 0x80, v254
	s_waitcnt vmcnt(8)
	s_barrier
	ds_read_b128 v[70:73], v158 offset:32768
	ds_read_b128 v[74:77], v159 offset:49152
	ds_read_b128 v[78:81], v159 offset:53248
	ds_read_b128 v[82:85], v159 offset:57344
	ds_read_b128 v[86:89], v159 offset:61440
	ds_read_b128 v[90:93], v160 offset:32768
	ds_read_b128 v[94:97], v161 offset:49152
	ds_read_b128 v[98:101], v161 offset:53248
	ds_read_b128 v[102:105], v161 offset:57344
	ds_read_b128 v[106:109], v161 offset:61440
	ds_read_b128 v[110:113], v162 offset:32768
	ds_read_b128 v[206:209], v163 offset:49152
	ds_read_b128 v[210:213], v163 offset:53248
	ds_read_b128 v[214:217], v163 offset:57344
	ds_read_b128 v[218:221], v163 offset:61440
	ds_read_b128 v[222:225], v164 offset:32768
	ds_read_b128 v[226:229], v165 offset:49152
	ds_read_b128 v[230:233], v165 offset:53248
	ds_read_b128 v[234:237], v165 offset:57344
	ds_read_b128 v[238:241], v165 offset:61440
	s_waitcnt lgkmcnt(0)
	s_barrier
	s_add_u32 m0, s36, 0x8000
	s_setprio 1
	v_mfma_f32_32x32x16_bf16 v[48:63], v[70:73], v[74:77], v[48:63]
	v_mfma_f32_32x32x16_bf16 v[32:47], v[70:73], v[78:81], v[32:47]
	global_load_lds_dwordx4 v254, s[18:19]
	s_add_u32 m0, m0, 0x1000
	v_mfma_f32_32x32x16_bf16 v[16:31], v[70:73], v[82:85], v[16:31]
	v_mfma_f32_32x32x16_bf16 v[0:15], v[70:73], v[86:89], v[0:15]
	global_load_lds_dwordx4 v254, s[20:21]
	s_add_u32 m0, m0, 0x1000
	v_mfma_f32_32x32x16_bf16 v[48:63], v[90:93], v[94:97], v[48:63]
	v_mfma_f32_32x32x16_bf16 v[32:47], v[90:93], v[98:101], v[32:47]
	global_load_lds_dwordx4 v254, s[22:23]
	s_add_u32 m0, m0, 0x1000
	v_mfma_f32_32x32x16_bf16 v[16:31], v[90:93], v[102:105], v[16:31]
	v_mfma_f32_32x32x16_bf16 v[0:15], v[90:93], v[106:109], v[0:15]
	global_load_lds_dwordx4 v254, s[24:25]
	s_add_u32 m0, m0, 0x1000
	v_mfma_f32_32x32x16_bf16 v[48:63], v[110:113], v[206:209], v[48:63]
	v_mfma_f32_32x32x16_bf16 v[32:47], v[110:113], v[210:213], v[32:47]
	global_load_lds_dwordx4 v254, s[26:27]
	s_add_u32 m0, m0, 0x1000
	v_mfma_f32_32x32x16_bf16 v[16:31], v[110:113], v[214:217], v[16:31]
	v_mfma_f32_32x32x16_bf16 v[0:15], v[110:113], v[218:221], v[0:15]
	global_load_lds_dwordx4 v254, s[28:29]
	s_add_u32 m0, m0, 0x1000
	v_mfma_f32_32x32x16_bf16 v[48:63], v[222:225], v[226:229], v[48:63]
	v_mfma_f32_32x32x16_bf16 v[32:47], v[222:225], v[230:233], v[32:47]
	global_load_lds_dwordx4 v254, s[30:31]
	s_add_u32 m0, m0, 0x1000
	v_mfma_f32_32x32x16_bf16 v[16:31], v[222:225], v[234:237], v[16:31]
	v_mfma_f32_32x32x16_bf16 v[0:15], v[222:225], v[238:241], v[0:15]
	global_load_lds_dwordx4 v254, s[34:35]
	s_setprio 0
	v_add_u32_e32 v254, 0x80, v254
	s_sub_u32 s37, s37, 1
	s_cmp_lg_u32 s37, 0
	s_cbranch_scc1 .Lgk_loop_p6
	s_waitcnt vmcnt(8)
	s_barrier
	ds_read_b128 v[70:73], v158
	ds_read_b128 v[74:77], v159 offset:16384
	ds_read_b128 v[78:81], v159 offset:20480
	ds_read_b128 v[82:85], v159 offset:24576
	ds_read_b128 v[86:89], v159 offset:28672
	ds_read_b128 v[90:93], v160
	ds_read_b128 v[94:97], v161 offset:16384
	ds_read_b128 v[98:101], v161 offset:20480
	ds_read_b128 v[102:105], v161 offset:24576
	ds_read_b128 v[106:109], v161 offset:28672
	ds_read_b128 v[110:113], v162
	ds_read_b128 v[206:209], v163 offset:16384
	ds_read_b128 v[210:213], v163 offset:20480
	ds_read_b128 v[214:217], v163 offset:24576
	ds_read_b128 v[218:221], v163 offset:28672
	ds_read_b128 v[222:225], v164
	ds_read_b128 v[226:229], v165 offset:16384
	ds_read_b128 v[230:233], v165 offset:20480
	ds_read_b128 v[234:237], v165 offset:24576
	ds_read_b128 v[238:241], v165 offset:28672
	s_waitcnt lgkmcnt(0)
	s_barrier
	s_setprio 1
	v_mfma_f32_32x32x16_bf16 v[48:63], v[70:73], v[74:77], v[48:63]
	v_mfma_f32_32x32x16_bf16 v[32:47], v[70:73], v[78:81], v[32:47]
	v_mfma_f32_32x32x16_bf16 v[16:31], v[70:73], v[82:85], v[16:31]
	v_mfma_f32_32x32x16_bf16 v[0:15], v[70:73], v[86:89], v[0:15]
	v_mfma_f32_32x32x16_bf16 v[48:63], v[90:93], v[94:97], v[48:63]
	v_mfma_f32_32x32x16_bf16 v[32:47], v[90:93], v[98:101], v[32:47]
	v_mfma_f32_32x32x16_bf16 v[16:31], v[90:93], v[102:105], v[16:31]
	v_mfma_f32_32x32x16_bf16 v[0:15], v[90:93], v[106:109], v[0:15]
	v_mfma_f32_32x32x16_bf16 v[48:63], v[110:113], v[206:209], v[48:63]
	v_mfma_f32_32x32x16_bf16 v[32:47], v[110:113], v[210:213], v[32:47]
	v_mfma_f32_32x32x16_bf16 v[16:31], v[110:113], v[214:217], v[16:31]
	v_mfma_f32_32x32x16_bf16 v[0:15], v[110:113], v[218:221], v[0:15]
	v_mfma_f32_32x32x16_bf16 v[48:63], v[222:225], v[226:229], v[48:63]
	v_mfma_f32_32x32x16_bf16 v[32:47], v[222:225], v[230:233], v[32:47]
	v_mfma_f32_32x32x16_bf16 v[16:31], v[222:225], v[234:237], v[16:31]
	v_mfma_f32_32x32x16_bf16 v[0:15], v[222:225], v[238:241], v[0:15]
	s_setprio 0
	s_waitcnt vmcnt(0)
	s_barrier
	ds_read_b128 v[70:73], v158 offset:32768
	ds_read_b128 v[74:77], v159 offset:49152
	ds_read_b128 v[78:81], v159 offset:53248
	ds_read_b128 v[82:85], v159 offset:57344
	ds_read_b128 v[86:89], v159 offset:61440
	ds_read_b128 v[90:93], v160 offset:32768
	ds_read_b128 v[94:97], v161 offset:49152
	ds_read_b128 v[98:101], v161 offset:53248
	ds_read_b128 v[102:105], v161 offset:57344
	ds_read_b128 v[106:109], v161 offset:61440
	ds_read_b128 v[110:113], v162 offset:32768
	ds_read_b128 v[206:209], v163 offset:49152
	ds_read_b128 v[210:213], v163 offset:53248
	ds_read_b128 v[214:217], v163 offset:57344
	ds_read_b128 v[218:221], v163 offset:61440
	ds_read_b128 v[222:225], v164 offset:32768
	ds_read_b128 v[226:229], v165 offset:49152
	ds_read_b128 v[230:233], v165 offset:53248
	ds_read_b128 v[234:237], v165 offset:57344
	ds_read_b128 v[238:241], v165 offset:61440
	s_waitcnt lgkmcnt(0)
	s_barrier
	s_setprio 1
	v_mfma_f32_32x32x16_bf16 v[48:63], v[70:73], v[74:77], v[48:63]
	v_mfma_f32_32x32x16_bf16 v[32:47], v[70:73], v[78:81], v[32:47]
	v_mfma_f32_32x32x16_bf16 v[16:31], v[70:73], v[82:85], v[16:31]
	v_mfma_f32_32x32x16_bf16 v[0:15], v[70:73], v[86:89], v[0:15]
	v_mfma_f32_32x32x16_bf16 v[48:63], v[90:93], v[94:97], v[48:63]
	v_mfma_f32_32x32x16_bf16 v[32:47], v[90:93], v[98:101], v[32:47]
	v_mfma_f32_32x32x16_bf16 v[16:31], v[90:93], v[102:105], v[16:31]
	v_mfma_f32_32x32x16_bf16 v[0:15], v[90:93], v[106:109], v[0:15]
	v_mfma_f32_32x32x16_bf16 v[48:63], v[110:113], v[206:209], v[48:63]
	v_mfma_f32_32x32x16_bf16 v[32:47], v[110:113], v[210:213], v[32:47]
	v_mfma_f32_32x32x16_bf16 v[16:31], v[110:113], v[214:217], v[16:31]
	v_mfma_f32_32x32x16_bf16 v[0:15], v[110:113], v[218:221], v[0:15]
	v_mfma_f32_32x32x16_bf16 v[48:63], v[222:225], v[226:229], v[48:63]
	v_mfma_f32_32x32x16_bf16 v[32:47], v[222:225], v[230:233], v[32:47]
	v_mfma_f32_32x32x16_bf16 v[16:31], v[222:225], v[234:237], v[16:31]
	v_mfma_f32_32x32x16_bf16 v[0:15], v[222:225], v[238:241], v[0:15]
	s_setprio 0
	s_branch .LBB0_707

.Lmap_done_0:
	s_lshl_b32 s60, s4, 7
	s_lshl_b32 s58, s76, 7
	s_ashr_i32 s61, s60, 31
	s_ashr_i32 s59, s58, 31
	s_lshl_b64 s[62:63], s[60:61], 11
	s_lshl_b64 s[64:65], s[58:59], 11
	s_lshl_b32 s38, s60, 11
	s_add_u32 s18, s14, s38
	s_addc_u32 s19, s15, 0
	s_add_u32 s18, s18, 0x679f000
	s_addc_u32 s19, s19, 0
	s_add_u32 s20, s18, 0x10000
	s_addc_u32 s21, s19, 0
	s_add_u32 s22, s20, 0x10000
	s_addc_u32 s23, s21, 0
	s_add_u32 s24, s22, 0x10000
	s_addc_u32 s25, s23, 0
	s_lshl_b32 s38, s58, 11
	s_add_u32 s26, s14, s38
	s_addc_u32 s27, s15, 0
	s_add_u32 s26, s26, 0x19a0000
	s_addc_u32 s27, s27, 0
	s_add_u32 s28, s26, 0x10000
	s_addc_u32 s29, s27, 0
	s_add_u32 s30, s28, 0x10000
	s_addc_u32 s31, s29, 0
	s_add_u32 s34, s30, 0x10000
	s_addc_u32 s35, s31, 0
	v_readfirstlane_b32 s36, v94
	v_mov_b32_e32 v254, v76
	s_mov_b32 m0, s36
	s_nop 0
	global_load_lds_dwordx4 v254, s[18:19]
	s_add_u32 m0, m0, 0x1000
	s_nop 0
	global_load_lds_dwordx4 v254, s[20:21]
	s_add_u32 m0, m0, 0x1000
	s_nop 0
	global_load_lds_dwordx4 v254, s[22:23]
	s_add_u32 m0, m0, 0x1000
	s_nop 0
	global_load_lds_dwordx4 v254, s[24:25]
	s_add_u32 m0, m0, 0x1000
	s_nop 0
	global_load_lds_dwordx4 v254, s[26:27]
	s_add_u32 m0, m0, 0x1000
	s_nop 0
	global_load_lds_dwordx4 v254, s[28:29]
	s_add_u32 m0, m0, 0x1000
	s_nop 0
	global_load_lds_dwordx4 v254, s[30:31]
	s_add_u32 m0, m0, 0x1000
	s_nop 0
	global_load_lds_dwordx4 v254, s[34:35]
	v_add_u32_e32 v254, 0x80, v254
	s_add_u32 m0, s36, 0x8000
	s_nop 0
	global_load_lds_dwordx4 v254, s[18:19]
	s_add_u32 m0, m0, 0x1000
	s_nop 0
	global_load_lds_dwordx4 v254, s[20:21]
	s_add_u32 m0, m0, 0x1000
	s_nop 0
	global_load_lds_dwordx4 v254, s[22:23]
	s_add_u32 m0, m0, 0x1000
	s_nop 0
	global_load_lds_dwordx4 v254, s[24:25]
	s_add_u32 m0, m0, 0x1000
	s_nop 0
	global_load_lds_dwordx4 v254, s[26:27]
	s_add_u32 m0, m0, 0x1000
	s_nop 0
	global_load_lds_dwordx4 v254, s[28:29]
	s_add_u32 m0, m0, 0x1000
	s_nop 0
	global_load_lds_dwordx4 v254, s[30:31]
	s_add_u32 m0, m0, 0x1000
	s_nop 0
	global_load_lds_dwordx4 v254, s[34:35]
	v_add_u32_e32 v254, 0x80, v254
	v_mov_b32_e32 v48, 0
	v_mov_b32_e32 v49, 0
	v_mov_b32_e32 v50, 0
	v_mov_b32_e32 v51, 0
	v_mov_b32_e32 v52, 0
	v_mov_b32_e32 v53, 0
	v_mov_b32_e32 v54, 0
	v_mov_b32_e32 v55, 0
	v_mov_b32_e32 v56, 0
	v_mov_b32_e32 v57, 0
	v_mov_b32_e32 v58, 0
	v_mov_b32_e32 v59, 0
	v_mov_b32_e32 v60, 0
	v_mov_b32_e32 v61, 0
	v_mov_b32_e32 v62, 0
	v_mov_b32_e32 v63, 0
	v_mov_b32_e32 v32, 0
	v_mov_b32_e32 v33, 0
	v_mov_b32_e32 v34, 0
	v_mov_b32_e32 v35, 0
	v_mov_b32_e32 v36, 0
	v_mov_b32_e32 v37, 0
	v_mov_b32_e32 v38, 0
	v_mov_b32_e32 v39, 0
	v_mov_b32_e32 v40, 0
	v_mov_b32_e32 v41, 0
	v_mov_b32_e32 v42, 0
	v_mov_b32_e32 v43, 0
	v_mov_b32_e32 v44, 0
	v_mov_b32_e32 v45, 0
	v_mov_b32_e32 v46, 0
	v_mov_b32_e32 v47, 0
	v_mov_b32_e32 v16, 0
	v_mov_b32_e32 v17, 0
	v_mov_b32_e32 v18, 0
	v_mov_b32_e32 v19, 0
	v_mov_b32_e32 v20, 0
	v_mov_b32_e32 v21, 0
	v_mov_b32_e32 v22, 0
	v_mov_b32_e32 v23, 0
	v_mov_b32_e32 v24, 0
	v_mov_b32_e32 v25, 0
	v_mov_b32_e32 v26, 0
	v_mov_b32_e32 v27, 0
	v_mov_b32_e32 v28, 0
	v_mov_b32_e32 v29, 0
	v_mov_b32_e32 v30, 0
	v_mov_b32_e32 v31, 0
	v_mov_b32_e32 v0, 0
	v_mov_b32_e32 v1, 0
	v_mov_b32_e32 v2, 0
	v_mov_b32_e32 v3, 0
	v_mov_b32_e32 v4, 0
	v_mov_b32_e32 v5, 0
	v_mov_b32_e32 v6, 0
	v_mov_b32_e32 v7, 0
	v_mov_b32_e32 v8, 0
	v_mov_b32_e32 v9, 0
	v_mov_b32_e32 v10, 0
	v_mov_b32_e32 v11, 0
	v_mov_b32_e32 v12, 0
	v_mov_b32_e32 v13, 0
	v_mov_b32_e32 v14, 0
	v_mov_b32_e32 v15, 0
	s_mov_b32 s37, 7

.LBB0_775:
	s_ashr_i32 s6, s3, 31
	s_lshr_b32 s6, s6, 26
	s_add_i32 s6, s3, s6
	s_ashr_i32 s58, s6, 6
	s_andn2_b32 s6, s6, 63
	s_sub_i32 s6, s3, s6
	s_ashr_i32 s59, s6, 31
	s_lshr_b32 s59, s59, 29
	s_add_i32 s59, s6, s59
	s_ashr_i32 s64, s59, 3
	s_and_b32 s59, s59, -8
	s_lshl_b32 s58, s58, 3
	s_sub_i32 s6, s6, s59
	s_add_i32 s6, s6, s58
	s_lshl_b32 s67, s6, 7
	s_lshl_b32 s68, s64, 7
	s_waitcnt lgkmcnt(0)
	s_mul_i32 s38, s6, 0xb0000
	s_add_u32 s18, s14, s38
	s_addc_u32 s19, s15, 0
	s_add_u32 s18, s18, 0x879f000
	s_addc_u32 s19, s19, 0
	s_add_u32 s20, s18, 0x2c000
	s_addc_u32 s21, s19, 0
	s_add_u32 s22, s20, 0x2c000
	s_addc_u32 s23, s21, 0
	s_add_u32 s24, s22, 0x2c000
	s_addc_u32 s25, s23, 0
	s_mul_i32 s38, s64, 0xb0000
	s_add_u32 s26, s14, s38
	s_addc_u32 s27, s15, 0
	s_add_u32 s26, s26, 0x45a0000
	s_addc_u32 s27, s27, 0
	s_add_u32 s28, s26, 0x2c000
	s_addc_u32 s29, s27, 0
	s_add_u32 s30, s28, 0x2c000
	s_addc_u32 s31, s29, 0
	s_add_u32 s34, s30, 0x2c000
	s_addc_u32 s35, s31, 0
	v_readfirstlane_b32 s36, v141
	v_mov_b32_e32 v254, v64
	s_mov_b32 m0, s36
	s_nop 0
	global_load_lds_dwordx4 v254, s[18:19]
	s_add_u32 m0, m0, 0x1000
	s_nop 0
	global_load_lds_dwordx4 v254, s[20:21]
	s_add_u32 m0, m0, 0x1000
	s_nop 0
	global_load_lds_dwordx4 v254, s[22:23]
	s_add_u32 m0, m0, 0x1000
	s_nop 0
	global_load_lds_dwordx4 v254, s[24:25]
	s_add_u32 m0, m0, 0x1000
	s_nop 0
	global_load_lds_dwordx4 v254, s[26:27]
	s_add_u32 m0, m0, 0x1000
	s_nop 0
	global_load_lds_dwordx4 v254, s[28:29]
	s_add_u32 m0, m0, 0x1000
	s_nop 0
	global_load_lds_dwordx4 v254, s[30:31]
	s_add_u32 m0, m0, 0x1000
	s_nop 0
	global_load_lds_dwordx4 v254, s[34:35]
	v_add_u32_e32 v254, 0x80, v254
	s_add_u32 m0, s36, 0x8000
	s_nop 0
	global_load_lds_dwordx4 v254, s[18:19]
	s_add_u32 m0, m0, 0x1000
	s_nop 0
	global_load_lds_dwordx4 v254, s[20:21]
	s_add_u32 m0, m0, 0x1000
	s_nop 0
	global_load_lds_dwordx4 v254, s[22:23]
	s_add_u32 m0, m0, 0x1000
	s_nop 0
	global_load_lds_dwordx4 v254, s[24:25]
	s_add_u32 m0, m0, 0x1000
	s_nop 0
	global_load_lds_dwordx4 v254, s[26:27]
	s_add_u32 m0, m0, 0x1000
	s_nop 0
	global_load_lds_dwordx4 v254, s[28:29]
	s_add_u32 m0, m0, 0x1000
	s_nop 0
	global_load_lds_dwordx4 v254, s[30:31]
	s_add_u32 m0, m0, 0x1000
	s_nop 0
	global_load_lds_dwordx4 v254, s[34:35]
	v_add_u32_e32 v254, 0x80, v254
	v_mov_b32_e32 v48, 0
	v_mov_b32_e32 v49, 0
	v_mov_b32_e32 v50, 0
	v_mov_b32_e32 v51, 0
	v_mov_b32_e32 v52, 0
	v_mov_b32_e32 v53, 0
	v_mov_b32_e32 v54, 0
	v_mov_b32_e32 v55, 0
	v_mov_b32_e32 v56, 0
	v_mov_b32_e32 v57, 0
	v_mov_b32_e32 v58, 0
	v_mov_b32_e32 v59, 0
	v_mov_b32_e32 v60, 0
	v_mov_b32_e32 v61, 0
	v_mov_b32_e32 v62, 0
	v_mov_b32_e32 v63, 0
	v_mov_b32_e32 v32, 0
	v_mov_b32_e32 v33, 0
	v_mov_b32_e32 v34, 0
	v_mov_b32_e32 v35, 0
	v_mov_b32_e32 v36, 0
	v_mov_b32_e32 v37, 0
	v_mov_b32_e32 v38, 0
	v_mov_b32_e32 v39, 0
	v_mov_b32_e32 v40, 0
	v_mov_b32_e32 v41, 0
	v_mov_b32_e32 v42, 0
	v_mov_b32_e32 v43, 0
	v_mov_b32_e32 v44, 0
	v_mov_b32_e32 v45, 0
	v_mov_b32_e32 v46, 0
	v_mov_b32_e32 v47, 0
	v_mov_b32_e32 v16, 0
	v_mov_b32_e32 v17, 0
	v_mov_b32_e32 v18, 0
	v_mov_b32_e32 v19, 0
	v_mov_b32_e32 v20, 0
	v_mov_b32_e32 v21, 0
	v_mov_b32_e32 v22, 0
	v_mov_b32_e32 v23, 0
	v_mov_b32_e32 v24, 0
	v_mov_b32_e32 v25, 0
	v_mov_b32_e32 v26, 0
	v_mov_b32_e32 v27, 0
	v_mov_b32_e32 v28, 0
	v_mov_b32_e32 v29, 0
	v_mov_b32_e32 v30, 0
	v_mov_b32_e32 v31, 0
	v_mov_b32_e32 v0, 0
	v_mov_b32_e32 v1, 0
	v_mov_b32_e32 v2, 0
	v_mov_b32_e32 v3, 0
	v_mov_b32_e32 v4, 0
	v_mov_b32_e32 v5, 0
	v_mov_b32_e32 v6, 0
	v_mov_b32_e32 v7, 0
	v_mov_b32_e32 v8, 0
	v_mov_b32_e32 v9, 0
	v_mov_b32_e32 v10, 0
	v_mov_b32_e32 v11, 0
	v_mov_b32_e32 v12, 0
	v_mov_b32_e32 v13, 0
	v_mov_b32_e32 v14, 0
	v_mov_b32_e32 v15, 0
	s_mov_b32 s37, 21
.Lgk_loop_p8:
	s_waitcnt vmcnt(8)
	s_barrier
	ds_read_b128 v[70:73], v157
	ds_read_b128 v[74:77], v158 offset:16384
	ds_read_b128 v[78:81], v158 offset:20480
	ds_read_b128 v[82:85], v158 offset:24576
	ds_read_b128 v[86:89], v158 offset:28672
	ds_read_b128 v[90:93], v159
	ds_read_b128 v[94:97], v160 offset:16384
	ds_read_b128 v[98:101], v160 offset:20480
	ds_read_b128 v[102:105], v160 offset:24576
	ds_read_b128 v[106:109], v160 offset:28672
	ds_read_b128 v[110:113], v161
	ds_read_b128 v[202:205], v162 offset:16384
	ds_read_b128 v[206:209], v162 offset:20480
	ds_read_b128 v[210:213], v162 offset:24576
	ds_read_b128 v[214:217], v162 offset:28672
	ds_read_b128 v[218:221], v163
	ds_read_b128 v[222:225], v164 offset:16384
	ds_read_b128 v[226:229], v164 offset:20480
	ds_read_b128 v[230:233], v164 offset:24576
	ds_read_b128 v[234:237], v164 offset:28672
	s_waitcnt lgkmcnt(0)
	s_barrier
	s_mov_b32 m0, s36
	s_setprio 1
	v_mfma_f32_32x32x16_bf16 v[48:63], v[70:73], v[74:77], v[48:63]
	v_mfma_f32_32x32x16_bf16 v[32:47], v[70:73], v[78:81], v[32:47]
	global_load_lds_dwordx4 v254, s[18:19]
	s_add_u32 m0, m0, 0x1000
	v_mfma_f32_32x32x16_bf16 v[16:31], v[70:73], v[82:85], v[16:31]
	v_mfma_f32_32x32x16_bf16 v[0:15], v[70:73], v[86:89], v[0:15]
	global_load_lds_dwordx4 v254, s[20:21]
	s_add_u32 m0, m0, 0x1000
	v_mfma_f32_32x32x16_bf16 v[48:63], v[90:93], v[94:97], v[48:63]
	v_mfma_f32_32x32x16_bf16 v[32:47], v[90:93], v[98:101], v[32:47]
	global_load_lds_dwordx4 v254, s[22:23]
	s_add_u32 m0, m0, 0x1000
	v_mfma_f32_32x32x16_bf16 v[16:31], v[90:93], v[102:105], v[16:31]
	v_mfma_f32_32x32x16_bf16 v[0:15], v[90:93], v[106:109], v[0:15]
	global_load_lds_dwordx4 v254, s[24:25]
	s_add_u32 m0, m0, 0x1000
	v_mfma_f32_32x32x16_bf16 v[48:63], v[110:113], v[202:205], v[48:63]
	v_mfma_f32_32x32x16_bf16 v[32:47], v[110:113], v[206:209], v[32:47]
	global_load_lds_dwordx4 v254, s[26:27]
	s_add_u32 m0, m0, 0x1000
	v_mfma_f32_32x32x16_bf16 v[16:31], v[110:113], v[210:213], v[16:31]
	v_mfma_f32_32x32x16_bf16 v[0:15], v[110:113], v[214:217], v[0:15]
	global_load_lds_dwordx4 v254, s[28:29]
	s_add_u32 m0, m0, 0x1000
	v_mfma_f32_32x32x16_bf16 v[48:63], v[218:221], v[222:225], v[48:63]
	v_mfma_f32_32x32x16_bf16 v[32:47], v[218:221], v[226:229], v[32:47]
	global_load_lds_dwordx4 v254, s[30:31]
	s_add_u32 m0, m0, 0x1000
	v_mfma_f32_32x32x16_bf16 v[16:31], v[218:221], v[230:233], v[16:31]
	v_mfma_f32_32x32x16_bf16 v[0:15], v[218:221], v[234:237], v[0:15]
	global_load_lds_dwordx4 v254, s[34:35]
	s_setprio 0
	v_add_u32_e32 v254, 0x80, v254
	s_waitcnt vmcnt(8)
	s_barrier
	ds_read_b128 v[70:73], v157 offset:32768
	ds_read_b128 v[74:77], v158 offset:49152
	ds_read_b128 v[78:81], v158 offset:53248
	ds_read_b128 v[82:85], v158 offset:57344
	ds_read_b128 v[86:89], v158 offset:61440
	ds_read_b128 v[90:93], v159 offset:32768
	ds_read_b128 v[94:97], v160 offset:49152
	ds_read_b128 v[98:101], v160 offset:53248
	ds_read_b128 v[102:105], v160 offset:57344
	ds_read_b128 v[106:109], v160 offset:61440
	ds_read_b128 v[110:113], v161 offset:32768
	ds_read_b128 v[202:205], v162 offset:49152
	ds_read_b128 v[206:209], v162 offset:53248
	ds_read_b128 v[210:213], v162 offset:57344
	ds_read_b128 v[214:217], v162 offset:61440
	ds_read_b128 v[218:221], v163 offset:32768
	ds_read_b128 v[222:225], v164 offset:49152
	ds_read_b128 v[226:229], v164 offset:53248
	ds_read_b128 v[230:233], v164 offset:57344
	ds_read_b128 v[234:237], v164 offset:61440
	s_waitcnt lgkmcnt(0)
	s_barrier
	s_add_u32 m0, s36, 0x8000
	s_setprio 1
	v_mfma_f32_32x32x16_bf16 v[48:63], v[70:73], v[74:77], v[48:63]
	v_mfma_f32_32x32x16_bf16 v[32:47], v[70:73], v[78:81], v[32:47]
	global_load_lds_dwordx4 v254, s[18:19]
	s_add_u32 m0, m0, 0x1000
	v_mfma_f32_32x32x16_bf16 v[16:31], v[70:73], v[82:85], v[16:31]
	v_mfma_f32_32x32x16_bf16 v[0:15], v[70:73], v[86:89], v[0:15]
	global_load_lds_dwordx4 v254, s[20:21]
	s_add_u32 m0, m0, 0x1000
	v_mfma_f32_32x32x16_bf16 v[48:63], v[90:93], v[94:97], v[48:63]
	v_mfma_f32_32x32x16_bf16 v[32:47], v[90:93], v[98:101], v[32:47]
	global_load_lds_dwordx4 v254, s[22:23]
	s_add_u32 m0, m0, 0x1000
	v_mfma_f32_32x32x16_bf16 v[16:31], v[90:93], v[102:105], v[16:31]
	v_mfma_f32_32x32x16_bf16 v[0:15], v[90:93], v[106:109], v[0:15]
	global_load_lds_dwordx4 v254, s[24:25]
	s_add_u32 m0, m0, 0x1000
	v_mfma_f32_32x32x16_bf16 v[48:63], v[110:113], v[202:205], v[48:63]
	v_mfma_f32_32x32x16_bf16 v[32:47], v[110:113], v[206:209], v[32:47]
	global_load_lds_dwordx4 v254, s[26:27]
	s_add_u32 m0, m0, 0x1000
	v_mfma_f32_32x32x16_bf16 v[16:31], v[110:113], v[210:213], v[16:31]
	v_mfma_f32_32x32x16_bf16 v[0:15], v[110:113], v[214:217], v[0:15]
	global_load_lds_dwordx4 v254, s[28:29]
	s_add_u32 m0, m0, 0x1000
	v_mfma_f32_32x32x16_bf16 v[48:63], v[218:221], v[222:225], v[48:63]
	v_mfma_f32_32x32x16_bf16 v[32:47], v[218:221], v[226:229], v[32:47]
	global_load_lds_dwordx4 v254, s[30:31]
	s_add_u32 m0, m0, 0x1000
	v_mfma_f32_32x32x16_bf16 v[16:31], v[218:221], v[230:233], v[16:31]
	v_mfma_f32_32x32x16_bf16 v[0:15], v[218:221], v[234:237], v[0:15]
	global_load_lds_dwordx4 v254, s[34:35]
	s_setprio 0
	v_add_u32_e32 v254, 0x80, v254
	s_sub_u32 s37, s37, 1
	s_cmp_lg_u32 s37, 0
	s_cbranch_scc1 .Lgk_loop_p8
	s_waitcnt vmcnt(8)
	s_barrier
	ds_read_b128 v[70:73], v157
	ds_read_b128 v[74:77], v158 offset:16384
	ds_read_b128 v[78:81], v158 offset:20480
	ds_read_b128 v[82:85], v158 offset:24576
	ds_read_b128 v[86:89], v158 offset:28672
	ds_read_b128 v[90:93], v159
	ds_read_b128 v[94:97], v160 offset:16384
	ds_read_b128 v[98:101], v160 offset:20480
	ds_read_b128 v[102:105], v160 offset:24576
	ds_read_b128 v[106:109], v160 offset:28672
	ds_read_b128 v[110:113], v161
	ds_read_b128 v[202:205], v162 offset:16384
	ds_read_b128 v[206:209], v162 offset:20480
	ds_read_b128 v[210:213], v162 offset:24576
	ds_read_b128 v[214:217], v162 offset:28672
	ds_read_b128 v[218:221], v163
	ds_read_b128 v[222:225], v164 offset:16384
	ds_read_b128 v[226:229], v164 offset:20480
	ds_read_b128 v[230:233], v164 offset:24576
	ds_read_b128 v[234:237], v164 offset:28672
	s_waitcnt lgkmcnt(0)
	s_barrier
	s_setprio 1
	v_mfma_f32_32x32x16_bf16 v[48:63], v[70:73], v[74:77], v[48:63]
	v_mfma_f32_32x32x16_bf16 v[32:47], v[70:73], v[78:81], v[32:47]
	v_mfma_f32_32x32x16_bf16 v[16:31], v[70:73], v[82:85], v[16:31]
	v_mfma_f32_32x32x16_bf16 v[0:15], v[70:73], v[86:89], v[0:15]
	v_mfma_f32_32x32x16_bf16 v[48:63], v[90:93], v[94:97], v[48:63]
	v_mfma_f32_32x32x16_bf16 v[32:47], v[90:93], v[98:101], v[32:47]
	v_mfma_f32_32x32x16_bf16 v[16:31], v[90:93], v[102:105], v[16:31]
	v_mfma_f32_32x32x16_bf16 v[0:15], v[90:93], v[106:109], v[0:15]
	v_mfma_f32_32x32x16_bf16 v[48:63], v[110:113], v[202:205], v[48:63]
	v_mfma_f32_32x32x16_bf16 v[32:47], v[110:113], v[206:209], v[32:47]
	v_mfma_f32_32x32x16_bf16 v[16:31], v[110:113], v[210:213], v[16:31]
	v_mfma_f32_32x32x16_bf16 v[0:15], v[110:113], v[214:217], v[0:15]
	v_mfma_f32_32x32x16_bf16 v[48:63], v[218:221], v[222:225], v[48:63]
	v_mfma_f32_32x32x16_bf16 v[32:47], v[218:221], v[226:229], v[32:47]
	v_mfma_f32_32x32x16_bf16 v[16:31], v[218:221], v[230:233], v[16:31]
	v_mfma_f32_32x32x16_bf16 v[0:15], v[218:221], v[234:237], v[0:15]
	s_setprio 0
	s_waitcnt vmcnt(0)
	s_barrier
	ds_read_b128 v[70:73], v157 offset:32768
	ds_read_b128 v[74:77], v158 offset:49152
	ds_read_b128 v[78:81], v158 offset:53248
	ds_read_b128 v[82:85], v158 offset:57344
	ds_read_b128 v[86:89], v158 offset:61440
	ds_read_b128 v[90:93], v159 offset:32768
	ds_read_b128 v[94:97], v160 offset:49152
	ds_read_b128 v[98:101], v160 offset:53248
	ds_read_b128 v[102:105], v160 offset:57344
	ds_read_b128 v[106:109], v160 offset:61440
	ds_read_b128 v[110:113], v161 offset:32768
	ds_read_b128 v[202:205], v162 offset:49152
	ds_read_b128 v[206:209], v162 offset:53248
	ds_read_b128 v[210:213], v162 offset:57344
	ds_read_b128 v[214:217], v162 offset:61440
	ds_read_b128 v[218:221], v163 offset:32768
	ds_read_b128 v[222:225], v164 offset:49152
	ds_read_b128 v[226:229], v164 offset:53248
	ds_read_b128 v[230:233], v164 offset:57344
	ds_read_b128 v[234:237], v164 offset:61440
	s_waitcnt lgkmcnt(0)
	s_barrier
	s_setprio 1
	v_mfma_f32_32x32x16_bf16 v[48:63], v[70:73], v[74:77], v[48:63]
	v_mfma_f32_32x32x16_bf16 v[32:47], v[70:73], v[78:81], v[32:47]
	v_mfma_f32_32x32x16_bf16 v[16:31], v[70:73], v[82:85], v[16:31]
	v_mfma_f32_32x32x16_bf16 v[0:15], v[70:73], v[86:89], v[0:15]
	v_mfma_f32_32x32x16_bf16 v[48:63], v[90:93], v[94:97], v[48:63]
	v_mfma_f32_32x32x16_bf16 v[32:47], v[90:93], v[98:101], v[32:47]
	v_mfma_f32_32x32x16_bf16 v[16:31], v[90:93], v[102:105], v[16:31]
	v_mfma_f32_32x32x16_bf16 v[0:15], v[90:93], v[106:109], v[0:15]
	v_mfma_f32_32x32x16_bf16 v[48:63], v[110:113], v[202:205], v[48:63]
	v_mfma_f32_32x32x16_bf16 v[32:47], v[110:113], v[206:209], v[32:47]
	v_mfma_f32_32x32x16_bf16 v[16:31], v[110:113], v[210:213], v[16:31]
	v_mfma_f32_32x32x16_bf16 v[0:15], v[110:113], v[214:217], v[0:15]
	v_mfma_f32_32x32x16_bf16 v[48:63], v[218:221], v[222:225], v[48:63]
	v_mfma_f32_32x32x16_bf16 v[32:47], v[218:221], v[226:229], v[32:47]
	v_mfma_f32_32x32x16_bf16 v[16:31], v[218:221], v[230:233], v[16:31]
	v_mfma_f32_32x32x16_bf16 v[0:15], v[218:221], v[234:237], v[0:15]
	s_setprio 0
	s_branch .LBB0_779

.LBB0_828:
	s_mul_hi_i32 s0, s3, 0x2aaaaaab
	s_lshr_b32 s1, s0, 31
	s_ashr_i32 s0, s0, 5
	s_add_i32 s0, s0, s1
	s_lshl_b32 s1, s0, 3
	s_mulk_i32 s0, 0xff40
	s_add_i32 s0, s0, s3
	s_ashr_i32 s4, s0, 31
	s_lshr_b32 s4, s4, 29
	s_add_i32 s4, s0, s4
	s_ashr_i32 s86, s4, 3
	s_and_b32 s4, s4, -8
	s_sub_i32 s8, s0, s4
	s_add_i32 s8, s8, s1
	s_lshl_b32 s68, s8, 7
	s_lshl_b32 s0, s86, 7
	s_ashr_i32 s69, s68, 31
	s_ashr_i32 s1, s0, 31
	s_lshl_b64 s[4:5], s[68:69], 11
	s_lshl_b64 s[70:71], s[0:1], 11
	s_lshl_b32 s48, s68, 11
	s_add_u32 s28, s14, s48
	s_addc_u32 s29, s15, 0
	s_add_u32 s28, s28, 0x679f000
	s_addc_u32 s29, s29, 0
	s_add_u32 s30, s28, 0x10000
	s_addc_u32 s31, s29, 0
	s_add_u32 s34, s30, 0x10000
	s_addc_u32 s35, s31, 0
	s_add_u32 s36, s34, 0x10000
	s_addc_u32 s37, s35, 0
	s_lshl_b32 s48, s0, 11
	s_add_u32 s38, s14, s48
	s_addc_u32 s39, s15, 0
	s_add_u32 s38, s38, 0x5a0000
	s_addc_u32 s39, s39, 0
	s_add_u32 s40, s38, 0x10000
	s_addc_u32 s41, s39, 0
	s_add_u32 s42, s40, 0x10000
	s_addc_u32 s43, s41, 0
	s_add_u32 s44, s42, 0x10000
	s_addc_u32 s45, s43, 0
	v_add_u32_e32 v255, v139, v141
	v_add_u32_e32 v188, v156, v141
	v_add_u32_e32 v189, v139, v157
	v_add_u32_e32 v190, v156, v157
	v_add_u32_e32 v191, v139, v158
	v_add_u32_e32 v192, v156, v158
	v_add_u32_e32 v193, v139, v159
	v_add_u32_e32 v194, v156, v159
	v_readfirstlane_b32 s46, v183
	v_mov_b32_e32 v254, v142
	s_mov_b32 m0, s46
	s_nop 0
	global_load_lds_dwordx4 v254, s[28:29]
	s_add_u32 m0, m0, 0x1000
	s_nop 0
	global_load_lds_dwordx4 v254, s[30:31]
	s_add_u32 m0, m0, 0x1000
	s_nop 0
	global_load_lds_dwordx4 v254, s[34:35]
	s_add_u32 m0, m0, 0x1000
	s_nop 0
	global_load_lds_dwordx4 v254, s[36:37]
	s_add_u32 m0, m0, 0x1000
	s_nop 0
	global_load_lds_dwordx4 v254, s[38:39]
	s_add_u32 m0, m0, 0x1000
	s_nop 0
	global_load_lds_dwordx4 v254, s[40:41]
	s_add_u32 m0, m0, 0x1000
	s_nop 0
	global_load_lds_dwordx4 v254, s[42:43]
	s_add_u32 m0, m0, 0x1000
	s_nop 0
	global_load_lds_dwordx4 v254, s[44:45]
	v_add_u32_e32 v254, 0x80, v254
	s_add_u32 m0, s46, 0x8000
	s_nop 0
	global_load_lds_dwordx4 v254, s[28:29]
	s_add_u32 m0, m0, 0x1000
	s_nop 0
	global_load_lds_dwordx4 v254, s[30:31]
	s_add_u32 m0, m0, 0x1000
	s_nop 0
	global_load_lds_dwordx4 v254, s[34:35]
	s_add_u32 m0, m0, 0x1000
	s_nop 0
	global_load_lds_dwordx4 v254, s[36:37]
	s_add_u32 m0, m0, 0x1000
	s_nop 0
	global_load_lds_dwordx4 v254, s[38:39]
	s_add_u32 m0, m0, 0x1000
	s_nop 0
	global_load_lds_dwordx4 v254, s[40:41]
	s_add_u32 m0, m0, 0x1000
	s_nop 0
	global_load_lds_dwordx4 v254, s[42:43]
	s_add_u32 m0, m0, 0x1000
	s_nop 0
	global_load_lds_dwordx4 v254, s[44:45]
	v_add_u32_e32 v254, 0x80, v254
	v_mov_b32_e32 v48, 0
	v_mov_b32_e32 v49, 0
	v_mov_b32_e32 v50, 0
	v_mov_b32_e32 v51, 0
	v_mov_b32_e32 v52, 0
	v_mov_b32_e32 v53, 0
	v_mov_b32_e32 v54, 0
	v_mov_b32_e32 v55, 0
	v_mov_b32_e32 v56, 0
	v_mov_b32_e32 v57, 0
	v_mov_b32_e32 v58, 0
	v_mov_b32_e32 v59, 0
	v_mov_b32_e32 v60, 0
	v_mov_b32_e32 v61, 0
	v_mov_b32_e32 v62, 0
	v_mov_b32_e32 v63, 0
	v_mov_b32_e32 v32, 0
	v_mov_b32_e32 v33, 0
	v_mov_b32_e32 v34, 0
	v_mov_b32_e32 v35, 0
	v_mov_b32_e32 v36, 0
	v_mov_b32_e32 v37, 0
	v_mov_b32_e32 v38, 0
	v_mov_b32_e32 v39, 0
	v_mov_b32_e32 v40, 0
	v_mov_b32_e32 v41, 0
	v_mov_b32_e32 v42, 0
	v_mov_b32_e32 v43, 0
	v_mov_b32_e32 v44, 0
	v_mov_b32_e32 v45, 0
	v_mov_b32_e32 v46, 0
	v_mov_b32_e32 v47, 0
	v_mov_b32_e32 v16, 0
	v_mov_b32_e32 v17, 0
	v_mov_b32_e32 v18, 0
	v_mov_b32_e32 v19, 0
	v_mov_b32_e32 v20, 0
	v_mov_b32_e32 v21, 0
	v_mov_b32_e32 v22, 0
	v_mov_b32_e32 v23, 0
	v_mov_b32_e32 v24, 0
	v_mov_b32_e32 v25, 0
	v_mov_b32_e32 v26, 0
	v_mov_b32_e32 v27, 0
	v_mov_b32_e32 v28, 0
	v_mov_b32_e32 v29, 0
	v_mov_b32_e32 v30, 0
	v_mov_b32_e32 v31, 0
	v_mov_b32_e32 v0, 0
	v_mov_b32_e32 v1, 0
	v_mov_b32_e32 v2, 0
	v_mov_b32_e32 v3, 0
	v_mov_b32_e32 v4, 0
	v_mov_b32_e32 v5, 0
	v_mov_b32_e32 v6, 0
	v_mov_b32_e32 v7, 0
	v_mov_b32_e32 v8, 0
	v_mov_b32_e32 v9, 0
	v_mov_b32_e32 v10, 0
	v_mov_b32_e32 v11, 0
	v_mov_b32_e32 v12, 0
	v_mov_b32_e32 v13, 0
	v_mov_b32_e32 v14, 0
	v_mov_b32_e32 v15, 0
	s_mov_b32 s47, 7
.Lgk_loop_p9:
	s_waitcnt vmcnt(8)
	s_barrier
	ds_read_b128 v[64:67], v255
	ds_read_b128 v[76:79], v188 offset:16384
	ds_read_b128 v[80:83], v188 offset:20480
	ds_read_b128 v[84:87], v188 offset:24576
	ds_read_b128 v[88:91], v188 offset:28672
	ds_read_b128 v[92:95], v189
	ds_read_b128 v[96:99], v190 offset:16384
	ds_read_b128 v[100:103], v190 offset:20480
	ds_read_b128 v[104:107], v190 offset:24576
	ds_read_b128 v[108:111], v190 offset:28672
	ds_read_b128 v[112:115], v191
	ds_read_b128 v[226:229], v192 offset:16384
	ds_read_b128 v[230:233], v192 offset:20480
	ds_read_b128 v[234:237], v192 offset:24576
	ds_read_b128 v[238:241], v192 offset:28672
	ds_read_b128 v[242:245], v193
	ds_read_b128 v[246:249], v194 offset:16384
	ds_read_b128 v[250:253], v194 offset:20480
	ds_read_b128 v[144:147], v194 offset:24576
	ds_read_b128 v[184:187], v194 offset:28672
	s_waitcnt lgkmcnt(0)
	s_barrier
	s_mov_b32 m0, s46
	s_setprio 1
	v_mfma_f32_32x32x16_bf16 v[48:63], v[64:67], v[76:79], v[48:63]
	v_mfma_f32_32x32x16_bf16 v[32:47], v[64:67], v[80:83], v[32:47]
	global_load_lds_dwordx4 v254, s[28:29]
	s_add_u32 m0, m0, 0x1000
	v_mfma_f32_32x32x16_bf16 v[16:31], v[64:67], v[84:87], v[16:31]
	v_mfma_f32_32x32x16_bf16 v[0:15], v[64:67], v[88:91], v[0:15]
	global_load_lds_dwordx4 v254, s[30:31]
	s_add_u32 m0, m0, 0x1000
	v_mfma_f32_32x32x16_bf16 v[48:63], v[92:95], v[96:99], v[48:63]
	v_mfma_f32_32x32x16_bf16 v[32:47], v[92:95], v[100:103], v[32:47]
	global_load_lds_dwordx4 v254, s[34:35]
	s_add_u32 m0, m0, 0x1000
	v_mfma_f32_32x32x16_bf16 v[16:31], v[92:95], v[104:107], v[16:31]
	v_mfma_f32_32x32x16_bf16 v[0:15], v[92:95], v[108:111], v[0:15]
	global_load_lds_dwordx4 v254, s[36:37]
	s_add_u32 m0, m0, 0x1000
	v_mfma_f32_32x32x16_bf16 v[48:63], v[112:115], v[226:229], v[48:63]
	v_mfma_f32_32x32x16_bf16 v[32:47], v[112:115], v[230:233], v[32:47]
	global_load_lds_dwordx4 v254, s[38:39]
	s_add_u32 m0, m0, 0x1000
	v_mfma_f32_32x32x16_bf16 v[16:31], v[112:115], v[234:237], v[16:31]
	v_mfma_f32_32x32x16_bf16 v[0:15], v[112:115], v[238:241], v[0:15]
	global_load_lds_dwordx4 v254, s[40:41]
	s_add_u32 m0, m0, 0x1000
	v_mfma_f32_32x32x16_bf16 v[48:63], v[242:245], v[246:249], v[48:63]
	v_mfma_f32_32x32x16_bf16 v[32:47], v[242:245], v[250:253], v[32:47]
	global_load_lds_dwordx4 v254, s[42:43]
	s_add_u32 m0, m0, 0x1000
	v_mfma_f32_32x32x16_bf16 v[16:31], v[242:245], v[144:147], v[16:31]
	v_mfma_f32_32x32x16_bf16 v[0:15], v[242:245], v[184:187], v[0:15]
	global_load_lds_dwordx4 v254, s[44:45]
	s_setprio 0
	v_add_u32_e32 v254, 0x80, v254
	s_waitcnt vmcnt(8)
	s_barrier
	ds_read_b128 v[64:67], v255 offset:32768
	ds_read_b128 v[76:79], v188 offset:49152
	ds_read_b128 v[80:83], v188 offset:53248
	ds_read_b128 v[84:87], v188 offset:57344
	ds_read_b128 v[88:91], v188 offset:61440
	ds_read_b128 v[92:95], v189 offset:32768
	ds_read_b128 v[96:99], v190 offset:49152
	ds_read_b128 v[100:103], v190 offset:53248
	ds_read_b128 v[104:107], v190 offset:57344
	ds_read_b128 v[108:111], v190 offset:61440
	ds_read_b128 v[112:115], v191 offset:32768
	ds_read_b128 v[226:229], v192 offset:49152
	ds_read_b128 v[230:233], v192 offset:53248
	ds_read_b128 v[234:237], v192 offset:57344
	ds_read_b128 v[238:241], v192 offset:61440
	ds_read_b128 v[242:245], v193 offset:32768
	ds_read_b128 v[246:249], v194 offset:49152
	ds_read_b128 v[250:253], v194 offset:53248
	ds_read_b128 v[144:147], v194 offset:57344
	ds_read_b128 v[184:187], v194 offset:61440
	s_waitcnt lgkmcnt(0)
	s_barrier
	s_add_u32 m0, s46, 0x8000
	s_setprio 1
	v_mfma_f32_32x32x16_bf16 v[48:63], v[64:67], v[76:79], v[48:63]
	v_mfma_f32_32x32x16_bf16 v[32:47], v[64:67], v[80:83], v[32:47]
	global_load_lds_dwordx4 v254, s[28:29]
	s_add_u32 m0, m0, 0x1000
	v_mfma_f32_32x32x16_bf16 v[16:31], v[64:67], v[84:87], v[16:31]
	v_mfma_f32_32x32x16_bf16 v[0:15], v[64:67], v[88:91], v[0:15]
	global_load_lds_dwordx4 v254, s[30:31]
	s_add_u32 m0, m0, 0x1000
	v_mfma_f32_32x32x16_bf16 v[48:63], v[92:95], v[96:99], v[48:63]
	v_mfma_f32_32x32x16_bf16 v[32:47], v[92:95], v[100:103], v[32:47]
	global_load_lds_dwordx4 v254, s[34:35]
	s_add_u32 m0, m0, 0x1000
	v_mfma_f32_32x32x16_bf16 v[16:31], v[92:95], v[104:107], v[16:31]
	v_mfma_f32_32x32x16_bf16 v[0:15], v[92:95], v[108:111], v[0:15]
	global_load_lds_dwordx4 v254, s[36:37]
	s_add_u32 m0, m0, 0x1000
	v_mfma_f32_32x32x16_bf16 v[48:63], v[112:115], v[226:229], v[48:63]
	v_mfma_f32_32x32x16_bf16 v[32:47], v[112:115], v[230:233], v[32:47]
	global_load_lds_dwordx4 v254, s[38:39]
	s_add_u32 m0, m0, 0x1000
	v_mfma_f32_32x32x16_bf16 v[16:31], v[112:115], v[234:237], v[16:31]
	v_mfma_f32_32x32x16_bf16 v[0:15], v[112:115], v[238:241], v[0:15]
	global_load_lds_dwordx4 v254, s[40:41]
	s_add_u32 m0, m0, 0x1000
	v_mfma_f32_32x32x16_bf16 v[48:63], v[242:245], v[246:249], v[48:63]
	v_mfma_f32_32x32x16_bf16 v[32:47], v[242:245], v[250:253], v[32:47]
	global_load_lds_dwordx4 v254, s[42:43]
	s_add_u32 m0, m0, 0x1000
	v_mfma_f32_32x32x16_bf16 v[16:31], v[242:245], v[144:147], v[16:31]
	v_mfma_f32_32x32x16_bf16 v[0:15], v[242:245], v[184:187], v[0:15]
	global_load_lds_dwordx4 v254, s[44:45]
	s_setprio 0
	v_add_u32_e32 v254, 0x80, v254
	s_sub_u32 s47, s47, 1
	s_cmp_lg_u32 s47, 0
	s_cbranch_scc1 .Lgk_loop_p9
	s_waitcnt vmcnt(8)
	s_barrier
	ds_read_b128 v[64:67], v255
	ds_read_b128 v[76:79], v188 offset:16384
	ds_read_b128 v[80:83], v188 offset:20480
	ds_read_b128 v[84:87], v188 offset:24576
	ds_read_b128 v[88:91], v188 offset:28672
	ds_read_b128 v[92:95], v189
	ds_read_b128 v[96:99], v190 offset:16384
	ds_read_b128 v[100:103], v190 offset:20480
	ds_read_b128 v[104:107], v190 offset:24576
	ds_read_b128 v[108:111], v190 offset:28672
	ds_read_b128 v[112:115], v191
	ds_read_b128 v[226:229], v192 offset:16384
	ds_read_b128 v[230:233], v192 offset:20480
	ds_read_b128 v[234:237], v192 offset:24576
	ds_read_b128 v[238:241], v192 offset:28672
	ds_read_b128 v[242:245], v193
	ds_read_b128 v[246:249], v194 offset:16384
	ds_read_b128 v[250:253], v194 offset:20480
	ds_read_b128 v[144:147], v194 offset:24576
	ds_read_b128 v[184:187], v194 offset:28672
	s_waitcnt lgkmcnt(0)
	s_barrier
	s_setprio 1
	v_mfma_f32_32x32x16_bf16 v[48:63], v[64:67], v[76:79], v[48:63]
	v_mfma_f32_32x32x16_bf16 v[32:47], v[64:67], v[80:83], v[32:47]
	v_mfma_f32_32x32x16_bf16 v[16:31], v[64:67], v[84:87], v[16:31]
	v_mfma_f32_32x32x16_bf16 v[0:15], v[64:67], v[88:91], v[0:15]
	v_mfma_f32_32x32x16_bf16 v[48:63], v[92:95], v[96:99], v[48:63]
	v_mfma_f32_32x32x16_bf16 v[32:47], v[92:95], v[100:103], v[32:47]
	v_mfma_f32_32x32x16_bf16 v[16:31], v[92:95], v[104:107], v[16:31]
	v_mfma_f32_32x32x16_bf16 v[0:15], v[92:95], v[108:111], v[0:15]
	v_mfma_f32_32x32x16_bf16 v[48:63], v[112:115], v[226:229], v[48:63]
	v_mfma_f32_32x32x16_bf16 v[32:47], v[112:115], v[230:233], v[32:47]
	v_mfma_f32_32x32x16_bf16 v[16:31], v[112:115], v[234:237], v[16:31]
	v_mfma_f32_32x32x16_bf16 v[0:15], v[112:115], v[238:241], v[0:15]
	v_mfma_f32_32x32x16_bf16 v[48:63], v[242:245], v[246:249], v[48:63]
	v_mfma_f32_32x32x16_bf16 v[32:47], v[242:245], v[250:253], v[32:47]
	v_mfma_f32_32x32x16_bf16 v[16:31], v[242:245], v[144:147], v[16:31]
	v_mfma_f32_32x32x16_bf16 v[0:15], v[242:245], v[184:187], v[0:15]
	s_setprio 0
	s_waitcnt vmcnt(0)
	s_barrier
	ds_read_b128 v[64:67], v255 offset:32768
	ds_read_b128 v[76:79], v188 offset:49152
	ds_read_b128 v[80:83], v188 offset:53248
	ds_read_b128 v[84:87], v188 offset:57344
	ds_read_b128 v[88:91], v188 offset:61440
	ds_read_b128 v[92:95], v189 offset:32768
	ds_read_b128 v[96:99], v190 offset:49152
	ds_read_b128 v[100:103], v190 offset:53248
	ds_read_b128 v[104:107], v190 offset:57344
	ds_read_b128 v[108:111], v190 offset:61440
	ds_read_b128 v[112:115], v191 offset:32768
	ds_read_b128 v[226:229], v192 offset:49152
	ds_read_b128 v[230:233], v192 offset:53248
	ds_read_b128 v[234:237], v192 offset:57344
	ds_read_b128 v[238:241], v192 offset:61440
	ds_read_b128 v[242:245], v193 offset:32768
	ds_read_b128 v[246:249], v194 offset:49152
	ds_read_b128 v[250:253], v194 offset:53248
	ds_read_b128 v[144:147], v194 offset:57344
	ds_read_b128 v[184:187], v194 offset:61440
	s_waitcnt lgkmcnt(0)
	s_barrier
	s_setprio 1
	v_mfma_f32_32x32x16_bf16 v[48:63], v[64:67], v[76:79], v[48:63]
	v_mfma_f32_32x32x16_bf16 v[32:47], v[64:67], v[80:83], v[32:47]
	v_mfma_f32_32x32x16_bf16 v[16:31], v[64:67], v[84:87], v[16:31]
	v_mfma_f32_32x32x16_bf16 v[0:15], v[64:67], v[88:91], v[0:15]
	v_mfma_f32_32x32x16_bf16 v[48:63], v[92:95], v[96:99], v[48:63]
	v_mfma_f32_32x32x16_bf16 v[32:47], v[92:95], v[100:103], v[32:47]
	v_mfma_f32_32x32x16_bf16 v[16:31], v[92:95], v[104:107], v[16:31]
	v_mfma_f32_32x32x16_bf16 v[0:15], v[92:95], v[108:111], v[0:15]
	v_mfma_f32_32x32x16_bf16 v[48:63], v[112:115], v[226:229], v[48:63]
	v_mfma_f32_32x32x16_bf16 v[32:47], v[112:115], v[230:233], v[32:47]
	v_mfma_f32_32x32x16_bf16 v[16:31], v[112:115], v[234:237], v[16:31]
	v_mfma_f32_32x32x16_bf16 v[0:15], v[112:115], v[238:241], v[0:15]
	v_mfma_f32_32x32x16_bf16 v[48:63], v[242:245], v[246:249], v[48:63]
	v_mfma_f32_32x32x16_bf16 v[32:47], v[242:245], v[250:253], v[32:47]
	v_mfma_f32_32x32x16_bf16 v[16:31], v[242:245], v[144:147], v[16:31]
	v_mfma_f32_32x32x16_bf16 v[0:15], v[242:245], v[184:187], v[0:15]
	s_setprio 0
	s_branch .LBB0_832

.LBB0_1046:
	s_ashr_i32 s6, s3, 31
	s_lshr_b32 s6, s6, 26
	s_add_i32 s6, s3, s6
	s_ashr_i32 s58, s6, 6
	s_andn2_b32 s6, s6, 63
	s_sub_i32 s6, s3, s6
	s_ashr_i32 s59, s6, 31
	s_lshr_b32 s59, s59, 29
	s_add_i32 s59, s6, s59
	s_ashr_i32 s64, s59, 3
	s_and_b32 s59, s59, -8
	s_lshl_b32 s58, s58, 3
	s_sub_i32 s6, s6, s59
	s_add_i32 s6, s6, s58
	s_lshl_b32 s66, s6, 7
	s_ashr_i32 s67, s66, 31
	s_lshl_b32 s68, s64, 7
	s_lshl_b64 s[58:59], s[66:67], 11
	s_ashr_i32 s69, s68, 31
	s_lshl_b32 s38, s66, 11
	s_add_u32 s18, s14, s38
	s_addc_u32 s19, s15, 0
	s_add_u32 s18, s18, 0xb79f000
	s_addc_u32 s19, s19, 0
	s_add_u32 s20, s18, 0x10000
	s_addc_u32 s21, s19, 0
	s_add_u32 s22, s20, 0x10000
	s_addc_u32 s23, s21, 0
	s_add_u32 s24, s22, 0x10000
	s_addc_u32 s25, s23, 0
	s_lshl_b32 s38, s68, 11
	s_add_u32 s26, s14, s38
	s_addc_u32 s27, s15, 0
	s_add_u32 s26, s26, 0xba0000
	s_addc_u32 s27, s27, 0
	s_add_u32 s28, s26, 0x10000
	s_addc_u32 s29, s27, 0
	s_add_u32 s30, s28, 0x10000
	s_addc_u32 s31, s29, 0
	s_add_u32 s34, s30, 0x10000
	s_addc_u32 s35, s31, 0
	v_readfirstlane_b32 s36, v140
	v_mov_b32_e32 v254, v64
	s_mov_b32 m0, s36
	s_nop 0
	global_load_lds_dwordx4 v254, s[18:19]
	s_add_u32 m0, m0, 0x1000
	s_nop 0
	global_load_lds_dwordx4 v254, s[20:21]
	s_add_u32 m0, m0, 0x1000
	s_nop 0
	global_load_lds_dwordx4 v254, s[22:23]
	s_add_u32 m0, m0, 0x1000
	s_nop 0
	global_load_lds_dwordx4 v254, s[24:25]
	s_add_u32 m0, m0, 0x1000
	s_nop 0
	global_load_lds_dwordx4 v254, s[26:27]
	s_add_u32 m0, m0, 0x1000
	s_nop 0
	global_load_lds_dwordx4 v254, s[28:29]
	s_add_u32 m0, m0, 0x1000
	s_nop 0
	global_load_lds_dwordx4 v254, s[30:31]
	s_add_u32 m0, m0, 0x1000
	s_nop 0
	global_load_lds_dwordx4 v254, s[34:35]
	v_add_u32_e32 v254, 0x80, v254
	s_add_u32 m0, s36, 0x8000
	s_nop 0
	global_load_lds_dwordx4 v254, s[18:19]
	s_add_u32 m0, m0, 0x1000
	s_nop 0
	global_load_lds_dwordx4 v254, s[20:21]
	s_add_u32 m0, m0, 0x1000
	s_nop 0
	global_load_lds_dwordx4 v254, s[22:23]
	s_add_u32 m0, m0, 0x1000
	s_nop 0
	global_load_lds_dwordx4 v254, s[24:25]
	s_add_u32 m0, m0, 0x1000
	s_nop 0
	global_load_lds_dwordx4 v254, s[26:27]
	s_add_u32 m0, m0, 0x1000
	s_nop 0
	global_load_lds_dwordx4 v254, s[28:29]
	s_add_u32 m0, m0, 0x1000
	s_nop 0
	global_load_lds_dwordx4 v254, s[30:31]
	s_add_u32 m0, m0, 0x1000
	s_nop 0
	global_load_lds_dwordx4 v254, s[34:35]
	v_add_u32_e32 v254, 0x80, v254
	v_mov_b32_e32 v48, 0
	v_mov_b32_e32 v49, 0
	v_mov_b32_e32 v50, 0
	v_mov_b32_e32 v51, 0
	v_mov_b32_e32 v52, 0
	v_mov_b32_e32 v53, 0
	v_mov_b32_e32 v54, 0
	v_mov_b32_e32 v55, 0
	v_mov_b32_e32 v56, 0
	v_mov_b32_e32 v57, 0
	v_mov_b32_e32 v58, 0
	v_mov_b32_e32 v59, 0
	v_mov_b32_e32 v60, 0
	v_mov_b32_e32 v61, 0
	v_mov_b32_e32 v62, 0
	v_mov_b32_e32 v63, 0
	v_mov_b32_e32 v32, 0
	v_mov_b32_e32 v33, 0
	v_mov_b32_e32 v34, 0
	v_mov_b32_e32 v35, 0
	v_mov_b32_e32 v36, 0
	v_mov_b32_e32 v37, 0
	v_mov_b32_e32 v38, 0
	v_mov_b32_e32 v39, 0
	v_mov_b32_e32 v40, 0
	v_mov_b32_e32 v41, 0
	v_mov_b32_e32 v42, 0
	v_mov_b32_e32 v43, 0
	v_mov_b32_e32 v44, 0
	v_mov_b32_e32 v45, 0
	v_mov_b32_e32 v46, 0
	v_mov_b32_e32 v47, 0
	v_mov_b32_e32 v16, 0
	v_mov_b32_e32 v17, 0
	v_mov_b32_e32 v18, 0
	v_mov_b32_e32 v19, 0
	v_mov_b32_e32 v20, 0
	v_mov_b32_e32 v21, 0
	v_mov_b32_e32 v22, 0
	v_mov_b32_e32 v23, 0
	v_mov_b32_e32 v24, 0
	v_mov_b32_e32 v25, 0
	v_mov_b32_e32 v26, 0
	v_mov_b32_e32 v27, 0
	v_mov_b32_e32 v28, 0
	v_mov_b32_e32 v29, 0
	v_mov_b32_e32 v30, 0
	v_mov_b32_e32 v31, 0
	v_mov_b32_e32 v0, 0
	v_mov_b32_e32 v1, 0
	v_mov_b32_e32 v2, 0
	v_mov_b32_e32 v3, 0
	v_mov_b32_e32 v4, 0
	v_mov_b32_e32 v5, 0
	v_mov_b32_e32 v6, 0
	v_mov_b32_e32 v7, 0
	v_mov_b32_e32 v8, 0
	v_mov_b32_e32 v9, 0
	v_mov_b32_e32 v10, 0
	v_mov_b32_e32 v11, 0
	v_mov_b32_e32 v12, 0
	v_mov_b32_e32 v13, 0
	v_mov_b32_e32 v14, 0
	v_mov_b32_e32 v15, 0
	s_mov_b32 s37, 7
.Lgk_loop_p11:
	s_waitcnt vmcnt(8)
	s_barrier
	ds_read_b128 v[70:73], v156
	ds_read_b128 v[74:77], v157 offset:16384
	ds_read_b128 v[78:81], v157 offset:20480
	ds_read_b128 v[82:85], v157 offset:24576
	ds_read_b128 v[86:89], v157 offset:28672
	ds_read_b128 v[90:93], v158
	ds_read_b128 v[94:97], v159 offset:16384
	ds_read_b128 v[98:101], v159 offset:20480
	ds_read_b128 v[102:105], v159 offset:24576
	ds_read_b128 v[106:109], v159 offset:28672
	ds_read_b128 v[110:113], v160
	ds_read_b128 v[202:205], v161 offset:16384
	ds_read_b128 v[206:209], v161 offset:20480
	ds_read_b128 v[210:213], v161 offset:24576
	ds_read_b128 v[214:217], v161 offset:28672
	ds_read_b128 v[218:221], v162
	ds_read_b128 v[222:225], v163 offset:16384
	ds_read_b128 v[226:229], v163 offset:20480
	ds_read_b128 v[230:233], v163 offset:24576
	ds_read_b128 v[234:237], v163 offset:28672
	s_waitcnt lgkmcnt(0)
	s_barrier
	s_mov_b32 m0, s36
	s_setprio 1
	v_mfma_f32_32x32x16_bf16 v[48:63], v[70:73], v[74:77], v[48:63]
	v_mfma_f32_32x32x16_bf16 v[32:47], v[70:73], v[78:81], v[32:47]
	global_load_lds_dwordx4 v254, s[18:19]
	s_add_u32 m0, m0, 0x1000
	v_mfma_f32_32x32x16_bf16 v[16:31], v[70:73], v[82:85], v[16:31]
	v_mfma_f32_32x32x16_bf16 v[0:15], v[70:73], v[86:89], v[0:15]
	global_load_lds_dwordx4 v254, s[20:21]
	s_add_u32 m0, m0, 0x1000
	v_mfma_f32_32x32x16_bf16 v[48:63], v[90:93], v[94:97], v[48:63]
	v_mfma_f32_32x32x16_bf16 v[32:47], v[90:93], v[98:101], v[32:47]
	global_load_lds_dwordx4 v254, s[22:23]
	s_add_u32 m0, m0, 0x1000
	v_mfma_f32_32x32x16_bf16 v[16:31], v[90:93], v[102:105], v[16:31]
	v_mfma_f32_32x32x16_bf16 v[0:15], v[90:93], v[106:109], v[0:15]
	global_load_lds_dwordx4 v254, s[24:25]
	s_add_u32 m0, m0, 0x1000
	v_mfma_f32_32x32x16_bf16 v[48:63], v[110:113], v[202:205], v[48:63]
	v_mfma_f32_32x32x16_bf16 v[32:47], v[110:113], v[206:209], v[32:47]
	global_load_lds_dwordx4 v254, s[26:27]
	s_add_u32 m0, m0, 0x1000
	v_mfma_f32_32x32x16_bf16 v[16:31], v[110:113], v[210:213], v[16:31]
	v_mfma_f32_32x32x16_bf16 v[0:15], v[110:113], v[214:217], v[0:15]
	global_load_lds_dwordx4 v254, s[28:29]
	s_add_u32 m0, m0, 0x1000
	v_mfma_f32_32x32x16_bf16 v[48:63], v[218:221], v[222:225], v[48:63]
	v_mfma_f32_32x32x16_bf16 v[32:47], v[218:221], v[226:229], v[32:47]
	global_load_lds_dwordx4 v254, s[30:31]
	s_add_u32 m0, m0, 0x1000
	v_mfma_f32_32x32x16_bf16 v[16:31], v[218:221], v[230:233], v[16:31]
	v_mfma_f32_32x32x16_bf16 v[0:15], v[218:221], v[234:237], v[0:15]
	global_load_lds_dwordx4 v254, s[34:35]
	s_setprio 0
	v_add_u32_e32 v254, 0x80, v254
	s_waitcnt vmcnt(8)
	s_barrier
	ds_read_b128 v[70:73], v156 offset:32768
	ds_read_b128 v[74:77], v157 offset:49152
	ds_read_b128 v[78:81], v157 offset:53248
	ds_read_b128 v[82:85], v157 offset:57344
	ds_read_b128 v[86:89], v157 offset:61440
	ds_read_b128 v[90:93], v158 offset:32768
	ds_read_b128 v[94:97], v159 offset:49152
	ds_read_b128 v[98:101], v159 offset:53248
	ds_read_b128 v[102:105], v159 offset:57344
	ds_read_b128 v[106:109], v159 offset:61440
	ds_read_b128 v[110:113], v160 offset:32768
	ds_read_b128 v[202:205], v161 offset:49152
	ds_read_b128 v[206:209], v161 offset:53248
	ds_read_b128 v[210:213], v161 offset:57344
	ds_read_b128 v[214:217], v161 offset:61440
	ds_read_b128 v[218:221], v162 offset:32768
	ds_read_b128 v[222:225], v163 offset:49152
	ds_read_b128 v[226:229], v163 offset:53248
	ds_read_b128 v[230:233], v163 offset:57344
	ds_read_b128 v[234:237], v163 offset:61440
	s_waitcnt lgkmcnt(0)
	s_barrier
	s_add_u32 m0, s36, 0x8000
	s_setprio 1
	v_mfma_f32_32x32x16_bf16 v[48:63], v[70:73], v[74:77], v[48:63]
	v_mfma_f32_32x32x16_bf16 v[32:47], v[70:73], v[78:81], v[32:47]
	global_load_lds_dwordx4 v254, s[18:19]
	s_add_u32 m0, m0, 0x1000
	v_mfma_f32_32x32x16_bf16 v[16:31], v[70:73], v[82:85], v[16:31]
	v_mfma_f32_32x32x16_bf16 v[0:15], v[70:73], v[86:89], v[0:15]
	global_load_lds_dwordx4 v254, s[20:21]
	s_add_u32 m0, m0, 0x1000
	v_mfma_f32_32x32x16_bf16 v[48:63], v[90:93], v[94:97], v[48:63]
	v_mfma_f32_32x32x16_bf16 v[32:47], v[90:93], v[98:101], v[32:47]
	global_load_lds_dwordx4 v254, s[22:23]
	s_add_u32 m0, m0, 0x1000
	v_mfma_f32_32x32x16_bf16 v[16:31], v[90:93], v[102:105], v[16:31]
	v_mfma_f32_32x32x16_bf16 v[0:15], v[90:93], v[106:109], v[0:15]
	global_load_lds_dwordx4 v254, s[24:25]
	s_add_u32 m0, m0, 0x1000
	v_mfma_f32_32x32x16_bf16 v[48:63], v[110:113], v[202:205], v[48:63]
	v_mfma_f32_32x32x16_bf16 v[32:47], v[110:113], v[206:209], v[32:47]
	global_load_lds_dwordx4 v254, s[26:27]
	s_add_u32 m0, m0, 0x1000
	v_mfma_f32_32x32x16_bf16 v[16:31], v[110:113], v[210:213], v[16:31]
	v_mfma_f32_32x32x16_bf16 v[0:15], v[110:113], v[214:217], v[0:15]
	global_load_lds_dwordx4 v254, s[28:29]
	s_add_u32 m0, m0, 0x1000
	v_mfma_f32_32x32x16_bf16 v[48:63], v[218:221], v[222:225], v[48:63]
	v_mfma_f32_32x32x16_bf16 v[32:47], v[218:221], v[226:229], v[32:47]
	global_load_lds_dwordx4 v254, s[30:31]
	s_add_u32 m0, m0, 0x1000
	v_mfma_f32_32x32x16_bf16 v[16:31], v[218:221], v[230:233], v[16:31]
	v_mfma_f32_32x32x16_bf16 v[0:15], v[218:221], v[234:237], v[0:15]
	global_load_lds_dwordx4 v254, s[34:35]
	s_setprio 0
	v_add_u32_e32 v254, 0x80, v254
	s_sub_u32 s37, s37, 1
	s_cmp_lg_u32 s37, 0
	s_cbranch_scc1 .Lgk_loop_p11
	s_waitcnt vmcnt(8)
	s_barrier
	ds_read_b128 v[70:73], v156
	ds_read_b128 v[74:77], v157 offset:16384
	ds_read_b128 v[78:81], v157 offset:20480
	ds_read_b128 v[82:85], v157 offset:24576
	ds_read_b128 v[86:89], v157 offset:28672
	ds_read_b128 v[90:93], v158
	ds_read_b128 v[94:97], v159 offset:16384
	ds_read_b128 v[98:101], v159 offset:20480
	ds_read_b128 v[102:105], v159 offset:24576
	ds_read_b128 v[106:109], v159 offset:28672
	ds_read_b128 v[110:113], v160
	ds_read_b128 v[202:205], v161 offset:16384
	ds_read_b128 v[206:209], v161 offset:20480
	ds_read_b128 v[210:213], v161 offset:24576
	ds_read_b128 v[214:217], v161 offset:28672
	ds_read_b128 v[218:221], v162
	ds_read_b128 v[222:225], v163 offset:16384
	ds_read_b128 v[226:229], v163 offset:20480
	ds_read_b128 v[230:233], v163 offset:24576
	ds_read_b128 v[234:237], v163 offset:28672
	s_waitcnt lgkmcnt(0)
	s_barrier
	s_setprio 1
	v_mfma_f32_32x32x16_bf16 v[48:63], v[70:73], v[74:77], v[48:63]
	v_mfma_f32_32x32x16_bf16 v[32:47], v[70:73], v[78:81], v[32:47]
	v_mfma_f32_32x32x16_bf16 v[16:31], v[70:73], v[82:85], v[16:31]
	v_mfma_f32_32x32x16_bf16 v[0:15], v[70:73], v[86:89], v[0:15]
	v_mfma_f32_32x32x16_bf16 v[48:63], v[90:93], v[94:97], v[48:63]
	v_mfma_f32_32x32x16_bf16 v[32:47], v[90:93], v[98:101], v[32:47]
	v_mfma_f32_32x32x16_bf16 v[16:31], v[90:93], v[102:105], v[16:31]
	v_mfma_f32_32x32x16_bf16 v[0:15], v[90:93], v[106:109], v[0:15]
	v_mfma_f32_32x32x16_bf16 v[48:63], v[110:113], v[202:205], v[48:63]
	v_mfma_f32_32x32x16_bf16 v[32:47], v[110:113], v[206:209], v[32:47]
	v_mfma_f32_32x32x16_bf16 v[16:31], v[110:113], v[210:213], v[16:31]
	v_mfma_f32_32x32x16_bf16 v[0:15], v[110:113], v[214:217], v[0:15]
	v_mfma_f32_32x32x16_bf16 v[48:63], v[218:221], v[222:225], v[48:63]
	v_mfma_f32_32x32x16_bf16 v[32:47], v[218:221], v[226:229], v[32:47]
	v_mfma_f32_32x32x16_bf16 v[16:31], v[218:221], v[230:233], v[16:31]
	v_mfma_f32_32x32x16_bf16 v[0:15], v[218:221], v[234:237], v[0:15]
	s_setprio 0
	s_waitcnt vmcnt(0)
	s_barrier
	ds_read_b128 v[70:73], v156 offset:32768
	ds_read_b128 v[74:77], v157 offset:49152
	ds_read_b128 v[78:81], v157 offset:53248
	ds_read_b128 v[82:85], v157 offset:57344
	ds_read_b128 v[86:89], v157 offset:61440
	ds_read_b128 v[90:93], v158 offset:32768
	ds_read_b128 v[94:97], v159 offset:49152
	ds_read_b128 v[98:101], v159 offset:53248
	ds_read_b128 v[102:105], v159 offset:57344
	ds_read_b128 v[106:109], v159 offset:61440
	ds_read_b128 v[110:113], v160 offset:32768
	ds_read_b128 v[202:205], v161 offset:49152
	ds_read_b128 v[206:209], v161 offset:53248
	ds_read_b128 v[210:213], v161 offset:57344
	ds_read_b128 v[214:217], v161 offset:61440
	ds_read_b128 v[218:221], v162 offset:32768
	ds_read_b128 v[222:225], v163 offset:49152
	ds_read_b128 v[226:229], v163 offset:53248
	ds_read_b128 v[230:233], v163 offset:57344
	ds_read_b128 v[234:237], v163 offset:61440
	s_waitcnt lgkmcnt(0)
	s_barrier
	s_setprio 1
	v_mfma_f32_32x32x16_bf16 v[48:63], v[70:73], v[74:77], v[48:63]
	v_mfma_f32_32x32x16_bf16 v[32:47], v[70:73], v[78:81], v[32:47]
	v_mfma_f32_32x32x16_bf16 v[16:31], v[70:73], v[82:85], v[16:31]
	v_mfma_f32_32x32x16_bf16 v[0:15], v[70:73], v[86:89], v[0:15]
	v_mfma_f32_32x32x16_bf16 v[48:63], v[90:93], v[94:97], v[48:63]
	v_mfma_f32_32x32x16_bf16 v[32:47], v[90:93], v[98:101], v[32:47]
	v_mfma_f32_32x32x16_bf16 v[16:31], v[90:93], v[102:105], v[16:31]
	v_mfma_f32_32x32x16_bf16 v[0:15], v[90:93], v[106:109], v[0:15]
	v_mfma_f32_32x32x16_bf16 v[48:63], v[110:113], v[202:205], v[48:63]
	v_mfma_f32_32x32x16_bf16 v[32:47], v[110:113], v[206:209], v[32:47]
	v_mfma_f32_32x32x16_bf16 v[16:31], v[110:113], v[210:213], v[16:31]
	v_mfma_f32_32x32x16_bf16 v[0:15], v[110:113], v[214:217], v[0:15]
	v_mfma_f32_32x32x16_bf16 v[48:63], v[218:221], v[222:225], v[48:63]
	v_mfma_f32_32x32x16_bf16 v[32:47], v[218:221], v[226:229], v[32:47]
	v_mfma_f32_32x32x16_bf16 v[16:31], v[218:221], v[230:233], v[16:31]
	v_mfma_f32_32x32x16_bf16 v[0:15], v[218:221], v[234:237], v[0:15]
	s_setprio 0
	s_branch .LBB0_1050

.Lmap_done_1:
	s_lshl_b32 s60, s4, 7
	s_lshl_b32 s58, s76, 7
	s_ashr_i32 s61, s60, 31
	s_ashr_i32 s59, s58, 31
	s_lshl_b64 s[62:63], s[60:61], 11
	s_lshl_b64 s[64:65], s[58:59], 11
	s_lshl_b32 s38, s60, 11
	s_add_u32 s18, s14, s38
	s_addc_u32 s19, s15, 0
	s_add_u32 s18, s18, 0x679f000
	s_addc_u32 s19, s19, 0
	s_add_u32 s20, s18, 0x10000
	s_addc_u32 s21, s19, 0
	s_add_u32 s22, s20, 0x10000
	s_addc_u32 s23, s21, 0
	s_add_u32 s24, s22, 0x10000
	s_addc_u32 s25, s23, 0
	s_lshl_b32 s38, s58, 11
	s_add_u32 s26, s14, s38
	s_addc_u32 s27, s15, 0
	s_add_u32 s26, s26, 0x24a0000
	s_addc_u32 s27, s27, 0
	s_add_u32 s28, s26, 0x10000
	s_addc_u32 s29, s27, 0
	s_add_u32 s30, s28, 0x10000
	s_addc_u32 s31, s29, 0
	s_add_u32 s34, s30, 0x10000
	s_addc_u32 s35, s31, 0
	v_readfirstlane_b32 s36, v94
	v_mov_b32_e32 v254, v76
	s_mov_b32 m0, s36
	s_nop 0
	global_load_lds_dwordx4 v254, s[18:19]
	s_add_u32 m0, m0, 0x1000
	s_nop 0
	global_load_lds_dwordx4 v254, s[20:21]
	s_add_u32 m0, m0, 0x1000
	s_nop 0
	global_load_lds_dwordx4 v254, s[22:23]
	s_add_u32 m0, m0, 0x1000
	s_nop 0
	global_load_lds_dwordx4 v254, s[24:25]
	s_add_u32 m0, m0, 0x1000
	s_nop 0
	global_load_lds_dwordx4 v254, s[26:27]
	s_add_u32 m0, m0, 0x1000
	s_nop 0
	global_load_lds_dwordx4 v254, s[28:29]
	s_add_u32 m0, m0, 0x1000
	s_nop 0
	global_load_lds_dwordx4 v254, s[30:31]
	s_add_u32 m0, m0, 0x1000
	s_nop 0
	global_load_lds_dwordx4 v254, s[34:35]
	v_add_u32_e32 v254, 0x80, v254
	s_add_u32 m0, s36, 0x8000
	s_nop 0
	global_load_lds_dwordx4 v254, s[18:19]
	s_add_u32 m0, m0, 0x1000
	s_nop 0
	global_load_lds_dwordx4 v254, s[20:21]
	s_add_u32 m0, m0, 0x1000
	s_nop 0
	global_load_lds_dwordx4 v254, s[22:23]
	s_add_u32 m0, m0, 0x1000
	s_nop 0
	global_load_lds_dwordx4 v254, s[24:25]
	s_add_u32 m0, m0, 0x1000
	s_nop 0
	global_load_lds_dwordx4 v254, s[26:27]
	s_add_u32 m0, m0, 0x1000
	s_nop 0
	global_load_lds_dwordx4 v254, s[28:29]
	s_add_u32 m0, m0, 0x1000
	s_nop 0
	global_load_lds_dwordx4 v254, s[30:31]
	s_add_u32 m0, m0, 0x1000
	s_nop 0
	global_load_lds_dwordx4 v254, s[34:35]
	v_add_u32_e32 v254, 0x80, v254
	v_mov_b32_e32 v48, 0
	v_mov_b32_e32 v49, 0
	v_mov_b32_e32 v50, 0
	v_mov_b32_e32 v51, 0
	v_mov_b32_e32 v52, 0
	v_mov_b32_e32 v53, 0
	v_mov_b32_e32 v54, 0
	v_mov_b32_e32 v55, 0
	v_mov_b32_e32 v56, 0
	v_mov_b32_e32 v57, 0
	v_mov_b32_e32 v58, 0
	v_mov_b32_e32 v59, 0
	v_mov_b32_e32 v60, 0
	v_mov_b32_e32 v61, 0
	v_mov_b32_e32 v62, 0
	v_mov_b32_e32 v63, 0
	v_mov_b32_e32 v32, 0
	v_mov_b32_e32 v33, 0
	v_mov_b32_e32 v34, 0
	v_mov_b32_e32 v35, 0
	v_mov_b32_e32 v36, 0
	v_mov_b32_e32 v37, 0
	v_mov_b32_e32 v38, 0
	v_mov_b32_e32 v39, 0
	v_mov_b32_e32 v40, 0
	v_mov_b32_e32 v41, 0
	v_mov_b32_e32 v42, 0
	v_mov_b32_e32 v43, 0
	v_mov_b32_e32 v44, 0
	v_mov_b32_e32 v45, 0
	v_mov_b32_e32 v46, 0
	v_mov_b32_e32 v47, 0
	v_mov_b32_e32 v16, 0
	v_mov_b32_e32 v17, 0
	v_mov_b32_e32 v18, 0
	v_mov_b32_e32 v19, 0
	v_mov_b32_e32 v20, 0
	v_mov_b32_e32 v21, 0
	v_mov_b32_e32 v22, 0
	v_mov_b32_e32 v23, 0
	v_mov_b32_e32 v24, 0
	v_mov_b32_e32 v25, 0
	v_mov_b32_e32 v26, 0
	v_mov_b32_e32 v27, 0
	v_mov_b32_e32 v28, 0
	v_mov_b32_e32 v29, 0
	v_mov_b32_e32 v30, 0
	v_mov_b32_e32 v31, 0
	v_mov_b32_e32 v0, 0
	v_mov_b32_e32 v1, 0
	v_mov_b32_e32 v2, 0
	v_mov_b32_e32 v3, 0
	v_mov_b32_e32 v4, 0
	v_mov_b32_e32 v5, 0
	v_mov_b32_e32 v6, 0
	v_mov_b32_e32 v7, 0
	v_mov_b32_e32 v8, 0
	v_mov_b32_e32 v9, 0
	v_mov_b32_e32 v10, 0
	v_mov_b32_e32 v11, 0
	v_mov_b32_e32 v12, 0
	v_mov_b32_e32 v13, 0
	v_mov_b32_e32 v14, 0
	v_mov_b32_e32 v15, 0
	s_mov_b32 s37, 7

.LBB0_1118:
	s_ashr_i32 s6, s3, 31
	s_lshr_b32 s6, s6, 26
	s_add_i32 s6, s3, s6
	s_ashr_i32 s58, s6, 6
	s_andn2_b32 s6, s6, 63
	s_sub_i32 s6, s3, s6
	s_ashr_i32 s59, s6, 31
	s_lshr_b32 s59, s59, 29
	s_add_i32 s59, s6, s59
	s_ashr_i32 s64, s59, 3
	s_and_b32 s59, s59, -8
	s_lshl_b32 s58, s58, 3
	s_sub_i32 s6, s6, s59
	s_add_i32 s6, s6, s58
	s_lshl_b32 s67, s6, 7
	s_lshl_b32 s68, s64, 7
	s_waitcnt lgkmcnt(0)
	s_mul_i32 s38, s6, 0xb0000
	s_add_u32 s18, s14, s38
	s_addc_u32 s19, s15, 0
	s_add_u32 s18, s18, 0x879f000
	s_addc_u32 s19, s19, 0
	s_add_u32 s20, s18, 0x2c000
	s_addc_u32 s21, s19, 0
	s_add_u32 s22, s20, 0x2c000
	s_addc_u32 s23, s21, 0
	s_add_u32 s24, s22, 0x2c000
	s_addc_u32 s25, s23, 0
	s_mul_i32 s38, s64, 0xb0000
	s_add_u32 s26, s14, s38
	s_addc_u32 s27, s15, 0
	s_add_u32 s26, s26, 0x4b20000
	s_addc_u32 s27, s27, 0
	s_add_u32 s28, s26, 0x2c000
	s_addc_u32 s29, s27, 0
	s_add_u32 s30, s28, 0x2c000
	s_addc_u32 s31, s29, 0
	s_add_u32 s34, s30, 0x2c000
	s_addc_u32 s35, s31, 0
	v_readfirstlane_b32 s36, v141
	v_mov_b32_e32 v254, v64
	s_mov_b32 m0, s36
	s_nop 0
	global_load_lds_dwordx4 v254, s[18:19]
	s_add_u32 m0, m0, 0x1000
	s_nop 0
	global_load_lds_dwordx4 v254, s[20:21]
	s_add_u32 m0, m0, 0x1000
	s_nop 0
	global_load_lds_dwordx4 v254, s[22:23]
	s_add_u32 m0, m0, 0x1000
	s_nop 0
	global_load_lds_dwordx4 v254, s[24:25]
	s_add_u32 m0, m0, 0x1000
	s_nop 0
	global_load_lds_dwordx4 v254, s[26:27]
	s_add_u32 m0, m0, 0x1000
	s_nop 0
	global_load_lds_dwordx4 v254, s[28:29]
	s_add_u32 m0, m0, 0x1000
	s_nop 0
	global_load_lds_dwordx4 v254, s[30:31]
	s_add_u32 m0, m0, 0x1000
	s_nop 0
	global_load_lds_dwordx4 v254, s[34:35]
	v_add_u32_e32 v254, 0x80, v254
	s_add_u32 m0, s36, 0x8000
	s_nop 0
	global_load_lds_dwordx4 v254, s[18:19]
	s_add_u32 m0, m0, 0x1000
	s_nop 0
	global_load_lds_dwordx4 v254, s[20:21]
	s_add_u32 m0, m0, 0x1000
	s_nop 0
	global_load_lds_dwordx4 v254, s[22:23]
	s_add_u32 m0, m0, 0x1000
	s_nop 0
	global_load_lds_dwordx4 v254, s[24:25]
	s_add_u32 m0, m0, 0x1000
	s_nop 0
	global_load_lds_dwordx4 v254, s[26:27]
	s_add_u32 m0, m0, 0x1000
	s_nop 0
	global_load_lds_dwordx4 v254, s[28:29]
	s_add_u32 m0, m0, 0x1000
	s_nop 0
	global_load_lds_dwordx4 v254, s[30:31]
	s_add_u32 m0, m0, 0x1000
	s_nop 0
	global_load_lds_dwordx4 v254, s[34:35]
	v_add_u32_e32 v254, 0x80, v254
	v_mov_b32_e32 v48, 0
	v_mov_b32_e32 v49, 0
	v_mov_b32_e32 v50, 0
	v_mov_b32_e32 v51, 0
	v_mov_b32_e32 v52, 0
	v_mov_b32_e32 v53, 0
	v_mov_b32_e32 v54, 0
	v_mov_b32_e32 v55, 0
	v_mov_b32_e32 v56, 0
	v_mov_b32_e32 v57, 0
	v_mov_b32_e32 v58, 0
	v_mov_b32_e32 v59, 0
	v_mov_b32_e32 v60, 0
	v_mov_b32_e32 v61, 0
	v_mov_b32_e32 v62, 0
	v_mov_b32_e32 v63, 0
	v_mov_b32_e32 v32, 0
	v_mov_b32_e32 v33, 0
	v_mov_b32_e32 v34, 0
	v_mov_b32_e32 v35, 0
	v_mov_b32_e32 v36, 0
	v_mov_b32_e32 v37, 0
	v_mov_b32_e32 v38, 0
	v_mov_b32_e32 v39, 0
	v_mov_b32_e32 v40, 0
	v_mov_b32_e32 v41, 0
	v_mov_b32_e32 v42, 0
	v_mov_b32_e32 v43, 0
	v_mov_b32_e32 v44, 0
	v_mov_b32_e32 v45, 0
	v_mov_b32_e32 v46, 0
	v_mov_b32_e32 v47, 0
	v_mov_b32_e32 v16, 0
	v_mov_b32_e32 v17, 0
	v_mov_b32_e32 v18, 0
	v_mov_b32_e32 v19, 0
	v_mov_b32_e32 v20, 0
	v_mov_b32_e32 v21, 0
	v_mov_b32_e32 v22, 0
	v_mov_b32_e32 v23, 0
	v_mov_b32_e32 v24, 0
	v_mov_b32_e32 v25, 0
	v_mov_b32_e32 v26, 0
	v_mov_b32_e32 v27, 0
	v_mov_b32_e32 v28, 0
	v_mov_b32_e32 v29, 0
	v_mov_b32_e32 v30, 0
	v_mov_b32_e32 v31, 0
	v_mov_b32_e32 v0, 0
	v_mov_b32_e32 v1, 0
	v_mov_b32_e32 v2, 0
	v_mov_b32_e32 v3, 0
	v_mov_b32_e32 v4, 0
	v_mov_b32_e32 v5, 0
	v_mov_b32_e32 v6, 0
	v_mov_b32_e32 v7, 0
	v_mov_b32_e32 v8, 0
	v_mov_b32_e32 v9, 0
	v_mov_b32_e32 v10, 0
	v_mov_b32_e32 v11, 0
	v_mov_b32_e32 v12, 0
	v_mov_b32_e32 v13, 0
	v_mov_b32_e32 v14, 0
	v_mov_b32_e32 v15, 0
	s_mov_b32 s37, 21

.LBB0_1171:
	s_mul_hi_i32 s0, s3, 0x2aaaaaab
	s_lshr_b32 s1, s0, 31
	s_ashr_i32 s0, s0, 4
	s_add_i32 s0, s0, s1
	s_mul_i32 s85, s0, 0xffffffa0
	s_add_i32 s85, s85, s3
	s_lshl_b32 s1, s0, 3
	s_ashr_i32 s0, s85, 31
	s_lshr_b32 s0, s0, 29
	s_add_i32 s0, s85, s0
	s_ashr_i32 s84, s0, 3
	s_and_b32 s0, s0, -8
	s_sub_i32 s8, s85, s0
	s_add_i32 s8, s8, s1
	s_lshl_b32 s66, s8, 7
	s_lshl_b32 s4, s84, 7
	s_ashr_i32 s67, s66, 31
	s_ashr_i32 s5, s4, 31
	s_lshl_b64 s[0:1], s[66:67], 11
	s_lshl_b64 s[68:69], s[4:5], 11
	s_lshl_b32 s48, s66, 11
	s_add_u32 s28, s14, s48
	s_addc_u32 s29, s15, 0
	s_add_u32 s28, s28, 0x679f000
	s_addc_u32 s29, s29, 0
	s_add_u32 s30, s28, 0x10000
	s_addc_u32 s31, s29, 0
	s_add_u32 s34, s30, 0x10000
	s_addc_u32 s35, s31, 0
	s_add_u32 s36, s34, 0x10000
	s_addc_u32 s37, s35, 0
	s_lshl_b32 s48, s4, 11
	s_add_u32 s38, s14, s48
	s_addc_u32 s39, s15, 0
	s_add_u32 s38, s38, 0xda0000
	s_addc_u32 s39, s39, 0
	s_add_u32 s40, s38, 0x10000
	s_addc_u32 s41, s39, 0
	s_add_u32 s42, s40, 0x10000
	s_addc_u32 s43, s41, 0
	s_add_u32 s44, s42, 0x10000
	s_addc_u32 s45, s43, 0
	v_add_u32_e32 v255, v109, v128
	v_add_u32_e32 v157, v129, v128
	v_add_u32_e32 v162, v109, v130
	v_add_u32_e32 v163, v129, v130
	v_add_u32_e32 v164, v109, v131
	v_add_u32_e32 v165, v129, v131
	v_add_u32_e32 v167, v109, v132
	v_add_u32_e32 v168, v129, v132
	v_readfirstlane_b32 s46, v156
	v_mov_b32_e32 v254, v110
	s_mov_b32 m0, s46
	s_nop 0
	global_load_lds_dwordx4 v254, s[28:29]
	s_add_u32 m0, m0, 0x1000
	s_nop 0
	global_load_lds_dwordx4 v254, s[30:31]
	s_add_u32 m0, m0, 0x1000
	s_nop 0
	global_load_lds_dwordx4 v254, s[34:35]
	s_add_u32 m0, m0, 0x1000
	s_nop 0
	global_load_lds_dwordx4 v254, s[36:37]
	s_add_u32 m0, m0, 0x1000
	s_nop 0
	global_load_lds_dwordx4 v254, s[38:39]
	s_add_u32 m0, m0, 0x1000
	s_nop 0
	global_load_lds_dwordx4 v254, s[40:41]
	s_add_u32 m0, m0, 0x1000
	s_nop 0
	global_load_lds_dwordx4 v254, s[42:43]
	s_add_u32 m0, m0, 0x1000
	s_nop 0
	global_load_lds_dwordx4 v254, s[44:45]
	v_add_u32_e32 v254, 0x80, v254
	s_add_u32 m0, s46, 0x8000
	s_nop 0
	global_load_lds_dwordx4 v254, s[28:29]
	s_add_u32 m0, m0, 0x1000
	s_nop 0
	global_load_lds_dwordx4 v254, s[30:31]
	s_add_u32 m0, m0, 0x1000
	s_nop 0
	global_load_lds_dwordx4 v254, s[34:35]
	s_add_u32 m0, m0, 0x1000
	s_nop 0
	global_load_lds_dwordx4 v254, s[36:37]
	s_add_u32 m0, m0, 0x1000
	s_nop 0
	global_load_lds_dwordx4 v254, s[38:39]
	s_add_u32 m0, m0, 0x1000
	s_nop 0
	global_load_lds_dwordx4 v254, s[40:41]
	s_add_u32 m0, m0, 0x1000
	s_nop 0
	global_load_lds_dwordx4 v254, s[42:43]
	s_add_u32 m0, m0, 0x1000
	s_nop 0
	global_load_lds_dwordx4 v254, s[44:45]
	v_add_u32_e32 v254, 0x80, v254
	v_mov_b32_e32 v48, 0
	v_mov_b32_e32 v49, 0
	v_mov_b32_e32 v50, 0
	v_mov_b32_e32 v51, 0
	v_mov_b32_e32 v52, 0
	v_mov_b32_e32 v53, 0
	v_mov_b32_e32 v54, 0
	v_mov_b32_e32 v55, 0
	v_mov_b32_e32 v56, 0
	v_mov_b32_e32 v57, 0
	v_mov_b32_e32 v58, 0
	v_mov_b32_e32 v59, 0
	v_mov_b32_e32 v60, 0
	v_mov_b32_e32 v61, 0
	v_mov_b32_e32 v62, 0
	v_mov_b32_e32 v63, 0
	v_mov_b32_e32 v32, 0
	v_mov_b32_e32 v33, 0
	v_mov_b32_e32 v34, 0
	v_mov_b32_e32 v35, 0
	v_mov_b32_e32 v36, 0
	v_mov_b32_e32 v37, 0
	v_mov_b32_e32 v38, 0
	v_mov_b32_e32 v39, 0
	v_mov_b32_e32 v40, 0
	v_mov_b32_e32 v41, 0
	v_mov_b32_e32 v42, 0
	v_mov_b32_e32 v43, 0
	v_mov_b32_e32 v44, 0
	v_mov_b32_e32 v45, 0
	v_mov_b32_e32 v46, 0
	v_mov_b32_e32 v47, 0
	v_mov_b32_e32 v16, 0
	v_mov_b32_e32 v17, 0
	v_mov_b32_e32 v18, 0
	v_mov_b32_e32 v19, 0
	v_mov_b32_e32 v20, 0
	v_mov_b32_e32 v21, 0
	v_mov_b32_e32 v22, 0
	v_mov_b32_e32 v23, 0
	v_mov_b32_e32 v24, 0
	v_mov_b32_e32 v25, 0
	v_mov_b32_e32 v26, 0
	v_mov_b32_e32 v27, 0
	v_mov_b32_e32 v28, 0
	v_mov_b32_e32 v29, 0
	v_mov_b32_e32 v30, 0
	v_mov_b32_e32 v31, 0
	v_mov_b32_e32 v0, 0
	v_mov_b32_e32 v1, 0
	v_mov_b32_e32 v2, 0
	v_mov_b32_e32 v3, 0
	v_mov_b32_e32 v4, 0
	v_mov_b32_e32 v5, 0
	v_mov_b32_e32 v6, 0
	v_mov_b32_e32 v7, 0
	v_mov_b32_e32 v8, 0
	v_mov_b32_e32 v9, 0
	v_mov_b32_e32 v10, 0
	v_mov_b32_e32 v11, 0
	v_mov_b32_e32 v12, 0
	v_mov_b32_e32 v13, 0
	v_mov_b32_e32 v14, 0
	v_mov_b32_e32 v15, 0
	s_mov_b32 s47, 7
.Lgk_loop_p14:
	s_waitcnt vmcnt(8)
	s_barrier
	ds_read_b128 v[64:67], v255
	ds_read_b128 v[76:79], v157 offset:16384
	ds_read_b128 v[80:83], v157 offset:20480
	ds_read_b128 v[84:87], v157 offset:24576
	ds_read_b128 v[88:91], v157 offset:28672
	ds_read_b128 v[92:95], v162
	ds_read_b128 v[96:99], v163 offset:16384
	ds_read_b128 v[100:103], v163 offset:20480
	ds_read_b128 v[118:121], v163 offset:24576
	ds_read_b128 v[122:125], v163 offset:28672
	ds_read_b128 v[172:175], v164
	ds_read_b128 v[226:229], v165 offset:16384
	ds_read_b128 v[230:233], v165 offset:20480
	ds_read_b128 v[234:237], v165 offset:24576
	ds_read_b128 v[238:241], v165 offset:28672
	ds_read_b128 v[242:245], v167
	ds_read_b128 v[246:249], v168 offset:16384
	ds_read_b128 v[250:253], v168 offset:20480
	ds_read_b128 v[112:115], v168 offset:24576
	ds_read_b128 v[158:161], v168 offset:28672
	s_waitcnt lgkmcnt(0)
	s_barrier
	s_mov_b32 m0, s46
	s_setprio 1
	v_mfma_f32_32x32x16_bf16 v[48:63], v[64:67], v[76:79], v[48:63]
	v_mfma_f32_32x32x16_bf16 v[32:47], v[64:67], v[80:83], v[32:47]
	global_load_lds_dwordx4 v254, s[28:29]
	s_add_u32 m0, m0, 0x1000
	v_mfma_f32_32x32x16_bf16 v[16:31], v[64:67], v[84:87], v[16:31]
	v_mfma_f32_32x32x16_bf16 v[0:15], v[64:67], v[88:91], v[0:15]
	global_load_lds_dwordx4 v254, s[30:31]
	s_add_u32 m0, m0, 0x1000
	v_mfma_f32_32x32x16_bf16 v[48:63], v[92:95], v[96:99], v[48:63]
	v_mfma_f32_32x32x16_bf16 v[32:47], v[92:95], v[100:103], v[32:47]
	global_load_lds_dwordx4 v254, s[34:35]
	s_add_u32 m0, m0, 0x1000
	v_mfma_f32_32x32x16_bf16 v[16:31], v[92:95], v[118:121], v[16:31]
	v_mfma_f32_32x32x16_bf16 v[0:15], v[92:95], v[122:125], v[0:15]
	global_load_lds_dwordx4 v254, s[36:37]
	s_add_u32 m0, m0, 0x1000
	v_mfma_f32_32x32x16_bf16 v[48:63], v[172:175], v[226:229], v[48:63]
	v_mfma_f32_32x32x16_bf16 v[32:47], v[172:175], v[230:233], v[32:47]
	global_load_lds_dwordx4 v254, s[38:39]
	s_add_u32 m0, m0, 0x1000
	v_mfma_f32_32x32x16_bf16 v[16:31], v[172:175], v[234:237], v[16:31]
	v_mfma_f32_32x32x16_bf16 v[0:15], v[172:175], v[238:241], v[0:15]
	global_load_lds_dwordx4 v254, s[40:41]
	s_add_u32 m0, m0, 0x1000
	v_mfma_f32_32x32x16_bf16 v[48:63], v[242:245], v[246:249], v[48:63]
	v_mfma_f32_32x32x16_bf16 v[32:47], v[242:245], v[250:253], v[32:47]
	global_load_lds_dwordx4 v254, s[42:43]
	s_add_u32 m0, m0, 0x1000
	v_mfma_f32_32x32x16_bf16 v[16:31], v[242:245], v[112:115], v[16:31]
	v_mfma_f32_32x32x16_bf16 v[0:15], v[242:245], v[158:161], v[0:15]
	global_load_lds_dwordx4 v254, s[44:45]
	s_setprio 0
	v_add_u32_e32 v254, 0x80, v254
	s_waitcnt vmcnt(8)
	s_barrier
	ds_read_b128 v[64:67], v255 offset:32768
	ds_read_b128 v[76:79], v157 offset:49152
	ds_read_b128 v[80:83], v157 offset:53248
	ds_read_b128 v[84:87], v157 offset:57344
	ds_read_b128 v[88:91], v157 offset:61440
	ds_read_b128 v[92:95], v162 offset:32768
	ds_read_b128 v[96:99], v163 offset:49152
	ds_read_b128 v[100:103], v163 offset:53248
	ds_read_b128 v[118:121], v163 offset:57344
	ds_read_b128 v[122:125], v163 offset:61440
	ds_read_b128 v[172:175], v164 offset:32768
	ds_read_b128 v[226:229], v165 offset:49152
	ds_read_b128 v[230:233], v165 offset:53248
	ds_read_b128 v[234:237], v165 offset:57344
	ds_read_b128 v[238:241], v165 offset:61440
	ds_read_b128 v[242:245], v167 offset:32768
	ds_read_b128 v[246:249], v168 offset:49152
	ds_read_b128 v[250:253], v168 offset:53248
	ds_read_b128 v[112:115], v168 offset:57344
	ds_read_b128 v[158:161], v168 offset:61440
	s_waitcnt lgkmcnt(0)
	s_barrier
	s_add_u32 m0, s46, 0x8000
	s_setprio 1
	v_mfma_f32_32x32x16_bf16 v[48:63], v[64:67], v[76:79], v[48:63]
	v_mfma_f32_32x32x16_bf16 v[32:47], v[64:67], v[80:83], v[32:47]
	global_load_lds_dwordx4 v254, s[28:29]
	s_add_u32 m0, m0, 0x1000
	v_mfma_f32_32x32x16_bf16 v[16:31], v[64:67], v[84:87], v[16:31]
	v_mfma_f32_32x32x16_bf16 v[0:15], v[64:67], v[88:91], v[0:15]
	global_load_lds_dwordx4 v254, s[30:31]
	s_add_u32 m0, m0, 0x1000
	v_mfma_f32_32x32x16_bf16 v[48:63], v[92:95], v[96:99], v[48:63]
	v_mfma_f32_32x32x16_bf16 v[32:47], v[92:95], v[100:103], v[32:47]
	global_load_lds_dwordx4 v254, s[34:35]
	s_add_u32 m0, m0, 0x1000
	v_mfma_f32_32x32x16_bf16 v[16:31], v[92:95], v[118:121], v[16:31]
	v_mfma_f32_32x32x16_bf16 v[0:15], v[92:95], v[122:125], v[0:15]
	global_load_lds_dwordx4 v254, s[36:37]
	s_add_u32 m0, m0, 0x1000
	v_mfma_f32_32x32x16_bf16 v[48:63], v[172:175], v[226:229], v[48:63]
	v_mfma_f32_32x32x16_bf16 v[32:47], v[172:175], v[230:233], v[32:47]
	global_load_lds_dwordx4 v254, s[38:39]
	s_add_u32 m0, m0, 0x1000
	v_mfma_f32_32x32x16_bf16 v[16:31], v[172:175], v[234:237], v[16:31]
	v_mfma_f32_32x32x16_bf16 v[0:15], v[172:175], v[238:241], v[0:15]
	global_load_lds_dwordx4 v254, s[40:41]
	s_add_u32 m0, m0, 0x1000
	v_mfma_f32_32x32x16_bf16 v[48:63], v[242:245], v[246:249], v[48:63]
	v_mfma_f32_32x32x16_bf16 v[32:47], v[242:245], v[250:253], v[32:47]
	global_load_lds_dwordx4 v254, s[42:43]
	s_add_u32 m0, m0, 0x1000
	v_mfma_f32_32x32x16_bf16 v[16:31], v[242:245], v[112:115], v[16:31]
	v_mfma_f32_32x32x16_bf16 v[0:15], v[242:245], v[158:161], v[0:15]
	global_load_lds_dwordx4 v254, s[44:45]
	s_setprio 0
	v_add_u32_e32 v254, 0x80, v254
	s_sub_u32 s47, s47, 1
	s_cmp_lg_u32 s47, 0
	s_cbranch_scc1 .Lgk_loop_p14
	s_waitcnt vmcnt(8)
	s_barrier
	ds_read_b128 v[64:67], v255
	ds_read_b128 v[76:79], v157 offset:16384
	ds_read_b128 v[80:83], v157 offset:20480
	ds_read_b128 v[84:87], v157 offset:24576
	ds_read_b128 v[88:91], v157 offset:28672
	ds_read_b128 v[92:95], v162
	ds_read_b128 v[96:99], v163 offset:16384
	ds_read_b128 v[100:103], v163 offset:20480
	ds_read_b128 v[118:121], v163 offset:24576
	ds_read_b128 v[122:125], v163 offset:28672
	ds_read_b128 v[172:175], v164
	ds_read_b128 v[226:229], v165 offset:16384
	ds_read_b128 v[230:233], v165 offset:20480
	ds_read_b128 v[234:237], v165 offset:24576
	ds_read_b128 v[238:241], v165 offset:28672
	ds_read_b128 v[242:245], v167
	ds_read_b128 v[246:249], v168 offset:16384
	ds_read_b128 v[250:253], v168 offset:20480
	ds_read_b128 v[112:115], v168 offset:24576
	ds_read_b128 v[158:161], v168 offset:28672
	s_waitcnt lgkmcnt(0)
	s_barrier
	s_setprio 1
	v_mfma_f32_32x32x16_bf16 v[48:63], v[64:67], v[76:79], v[48:63]
	v_mfma_f32_32x32x16_bf16 v[32:47], v[64:67], v[80:83], v[32:47]
	v_mfma_f32_32x32x16_bf16 v[16:31], v[64:67], v[84:87], v[16:31]
	v_mfma_f32_32x32x16_bf16 v[0:15], v[64:67], v[88:91], v[0:15]
	v_mfma_f32_32x32x16_bf16 v[48:63], v[92:95], v[96:99], v[48:63]
	v_mfma_f32_32x32x16_bf16 v[32:47], v[92:95], v[100:103], v[32:47]
	v_mfma_f32_32x32x16_bf16 v[16:31], v[92:95], v[118:121], v[16:31]
	v_mfma_f32_32x32x16_bf16 v[0:15], v[92:95], v[122:125], v[0:15]
	v_mfma_f32_32x32x16_bf16 v[48:63], v[172:175], v[226:229], v[48:63]
	v_mfma_f32_32x32x16_bf16 v[32:47], v[172:175], v[230:233], v[32:47]
	v_mfma_f32_32x32x16_bf16 v[16:31], v[172:175], v[234:237], v[16:31]
	v_mfma_f32_32x32x16_bf16 v[0:15], v[172:175], v[238:241], v[0:15]
	v_mfma_f32_32x32x16_bf16 v[48:63], v[242:245], v[246:249], v[48:63]
	v_mfma_f32_32x32x16_bf16 v[32:47], v[242:245], v[250:253], v[32:47]
	v_mfma_f32_32x32x16_bf16 v[16:31], v[242:245], v[112:115], v[16:31]
	v_mfma_f32_32x32x16_bf16 v[0:15], v[242:245], v[158:161], v[0:15]
	s_setprio 0
	s_waitcnt vmcnt(0)
	s_barrier
	ds_read_b128 v[64:67], v255 offset:32768
	ds_read_b128 v[76:79], v157 offset:49152
	ds_read_b128 v[80:83], v157 offset:53248
	ds_read_b128 v[84:87], v157 offset:57344
	ds_read_b128 v[88:91], v157 offset:61440
	ds_read_b128 v[92:95], v162 offset:32768
	ds_read_b128 v[96:99], v163 offset:49152
	ds_read_b128 v[100:103], v163 offset:53248
	ds_read_b128 v[118:121], v163 offset:57344
	ds_read_b128 v[122:125], v163 offset:61440
	ds_read_b128 v[172:175], v164 offset:32768
	ds_read_b128 v[226:229], v165 offset:49152
	ds_read_b128 v[230:233], v165 offset:53248
	ds_read_b128 v[234:237], v165 offset:57344
	ds_read_b128 v[238:241], v165 offset:61440
	ds_read_b128 v[242:245], v167 offset:32768
	ds_read_b128 v[246:249], v168 offset:49152
	ds_read_b128 v[250:253], v168 offset:53248
	ds_read_b128 v[112:115], v168 offset:57344
	ds_read_b128 v[158:161], v168 offset:61440
	s_waitcnt lgkmcnt(0)
	s_barrier
	s_setprio 1
	v_mfma_f32_32x32x16_bf16 v[48:63], v[64:67], v[76:79], v[48:63]
	v_mfma_f32_32x32x16_bf16 v[32:47], v[64:67], v[80:83], v[32:47]
	v_mfma_f32_32x32x16_bf16 v[16:31], v[64:67], v[84:87], v[16:31]
	v_mfma_f32_32x32x16_bf16 v[0:15], v[64:67], v[88:91], v[0:15]
	v_mfma_f32_32x32x16_bf16 v[48:63], v[92:95], v[96:99], v[48:63]
	v_mfma_f32_32x32x16_bf16 v[32:47], v[92:95], v[100:103], v[32:47]
	v_mfma_f32_32x32x16_bf16 v[16:31], v[92:95], v[118:121], v[16:31]
	v_mfma_f32_32x32x16_bf16 v[0:15], v[92:95], v[122:125], v[0:15]
	v_mfma_f32_32x32x16_bf16 v[48:63], v[172:175], v[226:229], v[48:63]
	v_mfma_f32_32x32x16_bf16 v[32:47], v[172:175], v[230:233], v[32:47]
	v_mfma_f32_32x32x16_bf16 v[16:31], v[172:175], v[234:237], v[16:31]
	v_mfma_f32_32x32x16_bf16 v[0:15], v[172:175], v[238:241], v[0:15]
	v_mfma_f32_32x32x16_bf16 v[48:63], v[242:245], v[246:249], v[48:63]
	v_mfma_f32_32x32x16_bf16 v[32:47], v[242:245], v[250:253], v[32:47]
	v_mfma_f32_32x32x16_bf16 v[16:31], v[242:245], v[112:115], v[16:31]
	v_mfma_f32_32x32x16_bf16 v[0:15], v[242:245], v[158:161], v[0:15]
	s_setprio 0
	s_branch .LBB0_1175

.LBB0_1322:
	s_ashr_i32 s6, s3, 31
	s_lshr_b32 s6, s6, 26
	s_add_i32 s6, s3, s6
	s_ashr_i32 s58, s6, 6
	s_andn2_b32 s6, s6, 63
	s_sub_i32 s6, s3, s6
	s_ashr_i32 s59, s6, 31
	s_lshr_b32 s59, s59, 29
	s_add_i32 s59, s6, s59
	s_ashr_i32 s64, s59, 3
	s_and_b32 s59, s59, -8
	s_lshl_b32 s58, s58, 3
	s_sub_i32 s6, s6, s59
	s_add_i32 s6, s6, s58
	s_lshl_b32 s66, s6, 7
	s_ashr_i32 s67, s66, 31
	s_lshl_b32 s68, s64, 7
	s_lshl_b64 s[58:59], s[66:67], 11
	s_ashr_i32 s69, s68, 31
	s_lshl_b32 s38, s66, 11
	s_add_u32 s18, s14, s38
	s_addc_u32 s19, s15, 0
	s_add_u32 s18, s18, 0xb79f000
	s_addc_u32 s19, s19, 0
	s_add_u32 s20, s18, 0x10000
	s_addc_u32 s21, s19, 0
	s_add_u32 s22, s20, 0x10000
	s_addc_u32 s23, s21, 0
	s_add_u32 s24, s22, 0x10000
	s_addc_u32 s25, s23, 0
	s_lshl_b32 s38, s68, 11
	s_add_u32 s26, s14, s38
	s_addc_u32 s27, s15, 0
	s_add_u32 s26, s26, 0x10a0000
	s_addc_u32 s27, s27, 0
	s_add_u32 s28, s26, 0x10000
	s_addc_u32 s29, s27, 0
	s_add_u32 s30, s28, 0x10000
	s_addc_u32 s31, s29, 0
	s_add_u32 s34, s30, 0x10000
	s_addc_u32 s35, s31, 0
	v_readfirstlane_b32 s36, v140
	v_mov_b32_e32 v254, v64
	s_mov_b32 m0, s36
	s_nop 0
	global_load_lds_dwordx4 v254, s[18:19]
	s_add_u32 m0, m0, 0x1000
	s_nop 0
	global_load_lds_dwordx4 v254, s[20:21]
	s_add_u32 m0, m0, 0x1000
	s_nop 0
	global_load_lds_dwordx4 v254, s[22:23]
	s_add_u32 m0, m0, 0x1000
	s_nop 0
	global_load_lds_dwordx4 v254, s[24:25]
	s_add_u32 m0, m0, 0x1000
	s_nop 0
	global_load_lds_dwordx4 v254, s[26:27]
	s_add_u32 m0, m0, 0x1000
	s_nop 0
	global_load_lds_dwordx4 v254, s[28:29]
	s_add_u32 m0, m0, 0x1000
	s_nop 0
	global_load_lds_dwordx4 v254, s[30:31]
	s_add_u32 m0, m0, 0x1000
	s_nop 0
	global_load_lds_dwordx4 v254, s[34:35]
	v_add_u32_e32 v254, 0x80, v254
	s_add_u32 m0, s36, 0x8000
	s_nop 0
	global_load_lds_dwordx4 v254, s[18:19]
	s_add_u32 m0, m0, 0x1000
	s_nop 0
	global_load_lds_dwordx4 v254, s[20:21]
	s_add_u32 m0, m0, 0x1000
	s_nop 0
	global_load_lds_dwordx4 v254, s[22:23]
	s_add_u32 m0, m0, 0x1000
	s_nop 0
	global_load_lds_dwordx4 v254, s[24:25]
	s_add_u32 m0, m0, 0x1000
	s_nop 0
	global_load_lds_dwordx4 v254, s[26:27]
	s_add_u32 m0, m0, 0x1000
	s_nop 0
	global_load_lds_dwordx4 v254, s[28:29]
	s_add_u32 m0, m0, 0x1000
	s_nop 0
	global_load_lds_dwordx4 v254, s[30:31]
	s_add_u32 m0, m0, 0x1000
	s_nop 0
	global_load_lds_dwordx4 v254, s[34:35]
	v_add_u32_e32 v254, 0x80, v254
	v_mov_b32_e32 v48, 0
	v_mov_b32_e32 v49, 0
	v_mov_b32_e32 v50, 0
	v_mov_b32_e32 v51, 0
	v_mov_b32_e32 v52, 0
	v_mov_b32_e32 v53, 0
	v_mov_b32_e32 v54, 0
	v_mov_b32_e32 v55, 0
	v_mov_b32_e32 v56, 0
	v_mov_b32_e32 v57, 0
	v_mov_b32_e32 v58, 0
	v_mov_b32_e32 v59, 0
	v_mov_b32_e32 v60, 0
	v_mov_b32_e32 v61, 0
	v_mov_b32_e32 v62, 0
	v_mov_b32_e32 v63, 0
	v_mov_b32_e32 v32, 0
	v_mov_b32_e32 v33, 0
	v_mov_b32_e32 v34, 0
	v_mov_b32_e32 v35, 0
	v_mov_b32_e32 v36, 0
	v_mov_b32_e32 v37, 0
	v_mov_b32_e32 v38, 0
	v_mov_b32_e32 v39, 0
	v_mov_b32_e32 v40, 0
	v_mov_b32_e32 v41, 0
	v_mov_b32_e32 v42, 0
	v_mov_b32_e32 v43, 0
	v_mov_b32_e32 v44, 0
	v_mov_b32_e32 v45, 0
	v_mov_b32_e32 v46, 0
	v_mov_b32_e32 v47, 0
	v_mov_b32_e32 v16, 0
	v_mov_b32_e32 v17, 0
	v_mov_b32_e32 v18, 0
	v_mov_b32_e32 v19, 0
	v_mov_b32_e32 v20, 0
	v_mov_b32_e32 v21, 0
	v_mov_b32_e32 v22, 0
	v_mov_b32_e32 v23, 0
	v_mov_b32_e32 v24, 0
	v_mov_b32_e32 v25, 0
	v_mov_b32_e32 v26, 0
	v_mov_b32_e32 v27, 0
	v_mov_b32_e32 v28, 0
	v_mov_b32_e32 v29, 0
	v_mov_b32_e32 v30, 0
	v_mov_b32_e32 v31, 0
	v_mov_b32_e32 v0, 0
	v_mov_b32_e32 v1, 0
	v_mov_b32_e32 v2, 0
	v_mov_b32_e32 v3, 0
	v_mov_b32_e32 v4, 0
	v_mov_b32_e32 v5, 0
	v_mov_b32_e32 v6, 0
	v_mov_b32_e32 v7, 0
	v_mov_b32_e32 v8, 0
	v_mov_b32_e32 v9, 0
	v_mov_b32_e32 v10, 0
	v_mov_b32_e32 v11, 0
	v_mov_b32_e32 v12, 0
	v_mov_b32_e32 v13, 0
	v_mov_b32_e32 v14, 0
	v_mov_b32_e32 v15, 0
	s_mov_b32 s37, 7

.Lmap_done_2:
	s_lshl_b32 s60, s4, 7
	s_lshl_b32 s58, s76, 7
	s_ashr_i32 s61, s60, 31
	s_ashr_i32 s59, s58, 31
	s_lshl_b64 s[62:63], s[60:61], 11
	s_lshl_b64 s[64:65], s[58:59], 11
	s_lshl_b32 s38, s60, 11
	s_add_u32 s18, s14, s38
	s_addc_u32 s19, s15, 0
	s_add_u32 s18, s18, 0x679f000
	s_addc_u32 s19, s19, 0
	s_add_u32 s20, s18, 0x10000
	s_addc_u32 s21, s19, 0
	s_add_u32 s22, s20, 0x10000
	s_addc_u32 s23, s21, 0
	s_add_u32 s24, s22, 0x10000
	s_addc_u32 s25, s23, 0
	s_lshl_b32 s38, s58, 11
	s_add_u32 s26, s14, s38
	s_addc_u32 s27, s15, 0
	s_add_u32 s26, s26, 0x2fa0000
	s_addc_u32 s27, s27, 0
	s_add_u32 s28, s26, 0x10000
	s_addc_u32 s29, s27, 0
	s_add_u32 s30, s28, 0x10000
	s_addc_u32 s31, s29, 0
	s_add_u32 s34, s30, 0x10000
	s_addc_u32 s35, s31, 0
	v_readfirstlane_b32 s36, v94
	v_mov_b32_e32 v254, v76
	s_mov_b32 m0, s36
	s_nop 0
	global_load_lds_dwordx4 v254, s[18:19]
	s_add_u32 m0, m0, 0x1000
	s_nop 0
	global_load_lds_dwordx4 v254, s[20:21]
	s_add_u32 m0, m0, 0x1000
	s_nop 0
	global_load_lds_dwordx4 v254, s[22:23]
	s_add_u32 m0, m0, 0x1000
	s_nop 0
	global_load_lds_dwordx4 v254, s[24:25]
	s_add_u32 m0, m0, 0x1000
	s_nop 0
	global_load_lds_dwordx4 v254, s[26:27]
	s_add_u32 m0, m0, 0x1000
	s_nop 0
	global_load_lds_dwordx4 v254, s[28:29]
	s_add_u32 m0, m0, 0x1000
	s_nop 0
	global_load_lds_dwordx4 v254, s[30:31]
	s_add_u32 m0, m0, 0x1000
	s_nop 0
	global_load_lds_dwordx4 v254, s[34:35]
	v_add_u32_e32 v254, 0x80, v254
	s_add_u32 m0, s36, 0x8000
	s_nop 0
	global_load_lds_dwordx4 v254, s[18:19]
	s_add_u32 m0, m0, 0x1000
	s_nop 0
	global_load_lds_dwordx4 v254, s[20:21]
	s_add_u32 m0, m0, 0x1000
	s_nop 0
	global_load_lds_dwordx4 v254, s[22:23]
	s_add_u32 m0, m0, 0x1000
	s_nop 0
	global_load_lds_dwordx4 v254, s[24:25]
	s_add_u32 m0, m0, 0x1000
	s_nop 0
	global_load_lds_dwordx4 v254, s[26:27]
	s_add_u32 m0, m0, 0x1000
	s_nop 0
	global_load_lds_dwordx4 v254, s[28:29]
	s_add_u32 m0, m0, 0x1000
	s_nop 0
	global_load_lds_dwordx4 v254, s[30:31]
	s_add_u32 m0, m0, 0x1000
	s_nop 0
	global_load_lds_dwordx4 v254, s[34:35]
	v_add_u32_e32 v254, 0x80, v254
	v_mov_b32_e32 v48, 0
	v_mov_b32_e32 v49, 0
	v_mov_b32_e32 v50, 0
	v_mov_b32_e32 v51, 0
	v_mov_b32_e32 v52, 0
	v_mov_b32_e32 v53, 0
	v_mov_b32_e32 v54, 0
	v_mov_b32_e32 v55, 0
	v_mov_b32_e32 v56, 0
	v_mov_b32_e32 v57, 0
	v_mov_b32_e32 v58, 0
	v_mov_b32_e32 v59, 0
	v_mov_b32_e32 v60, 0
	v_mov_b32_e32 v61, 0
	v_mov_b32_e32 v62, 0
	v_mov_b32_e32 v63, 0
	v_mov_b32_e32 v32, 0
	v_mov_b32_e32 v33, 0
	v_mov_b32_e32 v34, 0
	v_mov_b32_e32 v35, 0
	v_mov_b32_e32 v36, 0
	v_mov_b32_e32 v37, 0
	v_mov_b32_e32 v38, 0
	v_mov_b32_e32 v39, 0
	v_mov_b32_e32 v40, 0
	v_mov_b32_e32 v41, 0
	v_mov_b32_e32 v42, 0
	v_mov_b32_e32 v43, 0
	v_mov_b32_e32 v44, 0
	v_mov_b32_e32 v45, 0
	v_mov_b32_e32 v46, 0
	v_mov_b32_e32 v47, 0
	v_mov_b32_e32 v16, 0
	v_mov_b32_e32 v17, 0
	v_mov_b32_e32 v18, 0
	v_mov_b32_e32 v19, 0
	v_mov_b32_e32 v20, 0
	v_mov_b32_e32 v21, 0
	v_mov_b32_e32 v22, 0
	v_mov_b32_e32 v23, 0
	v_mov_b32_e32 v24, 0
	v_mov_b32_e32 v25, 0
	v_mov_b32_e32 v26, 0
	v_mov_b32_e32 v27, 0
	v_mov_b32_e32 v28, 0
	v_mov_b32_e32 v29, 0
	v_mov_b32_e32 v30, 0
	v_mov_b32_e32 v31, 0
	v_mov_b32_e32 v0, 0
	v_mov_b32_e32 v1, 0
	v_mov_b32_e32 v2, 0
	v_mov_b32_e32 v3, 0
	v_mov_b32_e32 v4, 0
	v_mov_b32_e32 v5, 0
	v_mov_b32_e32 v6, 0
	v_mov_b32_e32 v7, 0
	v_mov_b32_e32 v8, 0
	v_mov_b32_e32 v9, 0
	v_mov_b32_e32 v10, 0
	v_mov_b32_e32 v11, 0
	v_mov_b32_e32 v12, 0
	v_mov_b32_e32 v13, 0
	v_mov_b32_e32 v14, 0
	v_mov_b32_e32 v15, 0
	s_mov_b32 s37, 7

.LBB0_1394:
	s_ashr_i32 s6, s3, 31
	s_lshr_b32 s6, s6, 26
	s_add_i32 s6, s3, s6
	s_ashr_i32 s58, s6, 6
	s_andn2_b32 s6, s6, 63
	s_sub_i32 s6, s3, s6
	s_ashr_i32 s59, s6, 31
	s_lshr_b32 s59, s59, 29
	s_add_i32 s59, s6, s59
	s_ashr_i32 s64, s59, 3
	s_and_b32 s59, s59, -8
	s_lshl_b32 s58, s58, 3
	s_sub_i32 s6, s6, s59
	s_add_i32 s6, s6, s58
	s_lshl_b32 s67, s6, 7
	s_lshl_b32 s68, s64, 7
	s_waitcnt lgkmcnt(0)
	s_mul_i32 s38, s6, 0xb0000
	s_add_u32 s18, s14, s38
	s_addc_u32 s19, s15, 0
	s_add_u32 s18, s18, 0x879f000
	s_addc_u32 s19, s19, 0
	s_add_u32 s20, s18, 0x2c000
	s_addc_u32 s21, s19, 0
	s_add_u32 s22, s20, 0x2c000
	s_addc_u32 s23, s21, 0
	s_add_u32 s24, s22, 0x2c000
	s_addc_u32 s25, s23, 0
	s_mul_i32 s38, s64, 0xb0000
	s_add_u32 s26, s14, s38
	s_addc_u32 s27, s15, 0
	s_add_u32 s26, s26, 0x50a0000
	s_addc_u32 s27, s27, 0
	s_add_u32 s28, s26, 0x2c000
	s_addc_u32 s29, s27, 0
	s_add_u32 s30, s28, 0x2c000
	s_addc_u32 s31, s29, 0
	s_add_u32 s34, s30, 0x2c000
	s_addc_u32 s35, s31, 0
	v_readfirstlane_b32 s36, v141
	v_mov_b32_e32 v254, v64
	s_mov_b32 m0, s36
	s_nop 0
	global_load_lds_dwordx4 v254, s[18:19]
	s_add_u32 m0, m0, 0x1000
	s_nop 0
	global_load_lds_dwordx4 v254, s[20:21]
	s_add_u32 m0, m0, 0x1000
	s_nop 0
	global_load_lds_dwordx4 v254, s[22:23]
	s_add_u32 m0, m0, 0x1000
	s_nop 0
	global_load_lds_dwordx4 v254, s[24:25]
	s_add_u32 m0, m0, 0x1000
	s_nop 0
	global_load_lds_dwordx4 v254, s[26:27]
	s_add_u32 m0, m0, 0x1000
	s_nop 0
	global_load_lds_dwordx4 v254, s[28:29]
	s_add_u32 m0, m0, 0x1000
	s_nop 0
	global_load_lds_dwordx4 v254, s[30:31]
	s_add_u32 m0, m0, 0x1000
	s_nop 0
	global_load_lds_dwordx4 v254, s[34:35]
	v_add_u32_e32 v254, 0x80, v254
	s_add_u32 m0, s36, 0x8000
	s_nop 0
	global_load_lds_dwordx4 v254, s[18:19]
	s_add_u32 m0, m0, 0x1000
	s_nop 0
	global_load_lds_dwordx4 v254, s[20:21]
	s_add_u32 m0, m0, 0x1000
	s_nop 0
	global_load_lds_dwordx4 v254, s[22:23]
	s_add_u32 m0, m0, 0x1000
	s_nop 0
	global_load_lds_dwordx4 v254, s[24:25]
	s_add_u32 m0, m0, 0x1000
	s_nop 0
	global_load_lds_dwordx4 v254, s[26:27]
	s_add_u32 m0, m0, 0x1000
	s_nop 0
	global_load_lds_dwordx4 v254, s[28:29]
	s_add_u32 m0, m0, 0x1000
	s_nop 0
	global_load_lds_dwordx4 v254, s[30:31]
	s_add_u32 m0, m0, 0x1000
	s_nop 0
	global_load_lds_dwordx4 v254, s[34:35]
	v_add_u32_e32 v254, 0x80, v254
	v_mov_b32_e32 v48, 0
	v_mov_b32_e32 v49, 0
	v_mov_b32_e32 v50, 0
	v_mov_b32_e32 v51, 0
	v_mov_b32_e32 v52, 0
	v_mov_b32_e32 v53, 0
	v_mov_b32_e32 v54, 0
	v_mov_b32_e32 v55, 0
	v_mov_b32_e32 v56, 0
	v_mov_b32_e32 v57, 0
	v_mov_b32_e32 v58, 0
	v_mov_b32_e32 v59, 0
	v_mov_b32_e32 v60, 0
	v_mov_b32_e32 v61, 0
	v_mov_b32_e32 v62, 0
	v_mov_b32_e32 v63, 0
	v_mov_b32_e32 v32, 0
	v_mov_b32_e32 v33, 0
	v_mov_b32_e32 v34, 0
	v_mov_b32_e32 v35, 0
	v_mov_b32_e32 v36, 0
	v_mov_b32_e32 v37, 0
	v_mov_b32_e32 v38, 0
	v_mov_b32_e32 v39, 0
	v_mov_b32_e32 v40, 0
	v_mov_b32_e32 v41, 0
	v_mov_b32_e32 v42, 0
	v_mov_b32_e32 v43, 0
	v_mov_b32_e32 v44, 0
	v_mov_b32_e32 v45, 0
	v_mov_b32_e32 v46, 0
	v_mov_b32_e32 v47, 0
	v_mov_b32_e32 v16, 0
	v_mov_b32_e32 v17, 0
	v_mov_b32_e32 v18, 0
	v_mov_b32_e32 v19, 0
	v_mov_b32_e32 v20, 0
	v_mov_b32_e32 v21, 0
	v_mov_b32_e32 v22, 0
	v_mov_b32_e32 v23, 0
	v_mov_b32_e32 v24, 0
	v_mov_b32_e32 v25, 0
	v_mov_b32_e32 v26, 0
	v_mov_b32_e32 v27, 0
	v_mov_b32_e32 v28, 0
	v_mov_b32_e32 v29, 0
	v_mov_b32_e32 v30, 0
	v_mov_b32_e32 v31, 0
	v_mov_b32_e32 v0, 0
	v_mov_b32_e32 v1, 0
	v_mov_b32_e32 v2, 0
	v_mov_b32_e32 v3, 0
	v_mov_b32_e32 v4, 0
	v_mov_b32_e32 v5, 0
	v_mov_b32_e32 v6, 0
	v_mov_b32_e32 v7, 0
	v_mov_b32_e32 v8, 0
	v_mov_b32_e32 v9, 0
	v_mov_b32_e32 v10, 0
	v_mov_b32_e32 v11, 0
	v_mov_b32_e32 v12, 0
	v_mov_b32_e32 v13, 0
	v_mov_b32_e32 v14, 0
	v_mov_b32_e32 v15, 0
	s_mov_b32 s37, 21

.LBB0_1446:
	s_ashr_i32 s4, s3, 31
	s_lshr_b32 s4, s4, 25
	s_add_i32 s4, s3, s4
	s_ashr_i32 s60, s4, 7
	s_and_b32 s4, s4, 0xffffff80
	s_sub_i32 s77, s3, s4
	s_ashr_i32 s4, s77, 31
	s_lshr_b32 s4, s4, 29
	s_add_i32 s61, s77, s4
	s_and_b32 s4, s61, -8
	s_lshl_b32 s60, s60, 3
	s_sub_i32 s4, s77, s4
	s_add_i32 s4, s4, s60
	s_lshl_b32 s60, s61, 4
	s_lshl_b32 s62, s4, 7
	s_and_b32 s60, s60, 0xffffff80
	s_ashr_i32 s63, s62, 31
	s_ashr_i32 s61, s60, 31
	s_lshl_b64 s[64:65], s[62:63], 11
	s_lshl_b64 s[66:67], s[60:61], 11
	s_lshl_b32 s40, s62, 11
	s_add_u32 s20, s14, s40
	s_addc_u32 s21, s15, 0
	s_add_u32 s20, s20, 0x679f000
	s_addc_u32 s21, s21, 0
	s_add_u32 s22, s20, 0x10000
	s_addc_u32 s23, s21, 0
	s_add_u32 s24, s22, 0x10000
	s_addc_u32 s25, s23, 0
	s_add_u32 s26, s24, 0x10000
	s_addc_u32 s27, s25, 0
	s_lshl_b32 s40, s60, 11
	s_add_u32 s28, s14, s40
	s_addc_u32 s29, s15, 0
	s_add_u32 s28, s28, 0x12a0000
	s_addc_u32 s29, s29, 0
	s_add_u32 s30, s28, 0x10000
	s_addc_u32 s31, s29, 0
	s_add_u32 s34, s30, 0x10000
	s_addc_u32 s35, s31, 0
	s_add_u32 s36, s34, 0x10000
	s_addc_u32 s37, s35, 0
	v_readfirstlane_b32 s38, v97
	v_mov_b32_e32 v254, v76
	s_mov_b32 m0, s38
	s_nop 0
	global_load_lds_dwordx4 v254, s[20:21]
	s_add_u32 m0, m0, 0x1000
	s_nop 0
	global_load_lds_dwordx4 v254, s[22:23]
	s_add_u32 m0, m0, 0x1000
	s_nop 0
	global_load_lds_dwordx4 v254, s[24:25]
	s_add_u32 m0, m0, 0x1000
	s_nop 0
	global_load_lds_dwordx4 v254, s[26:27]
	s_add_u32 m0, m0, 0x1000
	s_nop 0
	global_load_lds_dwordx4 v254, s[28:29]
	s_add_u32 m0, m0, 0x1000
	s_nop 0
	global_load_lds_dwordx4 v254, s[30:31]
	s_add_u32 m0, m0, 0x1000
	s_nop 0
	global_load_lds_dwordx4 v254, s[34:35]
	s_add_u32 m0, m0, 0x1000
	s_nop 0
	global_load_lds_dwordx4 v254, s[36:37]
	v_add_u32_e32 v254, 0x80, v254
	s_add_u32 m0, s38, 0x8000
	s_nop 0
	global_load_lds_dwordx4 v254, s[20:21]
	s_add_u32 m0, m0, 0x1000
	s_nop 0
	global_load_lds_dwordx4 v254, s[22:23]
	s_add_u32 m0, m0, 0x1000
	s_nop 0
	global_load_lds_dwordx4 v254, s[24:25]
	s_add_u32 m0, m0, 0x1000
	s_nop 0
	global_load_lds_dwordx4 v254, s[26:27]
	s_add_u32 m0, m0, 0x1000
	s_nop 0
	global_load_lds_dwordx4 v254, s[28:29]
	s_add_u32 m0, m0, 0x1000
	s_nop 0
	global_load_lds_dwordx4 v254, s[30:31]
	s_add_u32 m0, m0, 0x1000
	s_nop 0
	global_load_lds_dwordx4 v254, s[34:35]
	s_add_u32 m0, m0, 0x1000
	s_nop 0
	global_load_lds_dwordx4 v254, s[36:37]
	v_add_u32_e32 v254, 0x80, v254
	v_mov_b32_e32 v48, 0
	v_mov_b32_e32 v49, 0
	v_mov_b32_e32 v50, 0
	v_mov_b32_e32 v51, 0
	v_mov_b32_e32 v52, 0
	v_mov_b32_e32 v53, 0
	v_mov_b32_e32 v54, 0
	v_mov_b32_e32 v55, 0
	v_mov_b32_e32 v56, 0
	v_mov_b32_e32 v57, 0
	v_mov_b32_e32 v58, 0
	v_mov_b32_e32 v59, 0
	v_mov_b32_e32 v60, 0
	v_mov_b32_e32 v61, 0
	v_mov_b32_e32 v62, 0
	v_mov_b32_e32 v63, 0
	v_mov_b32_e32 v32, 0
	v_mov_b32_e32 v33, 0
	v_mov_b32_e32 v34, 0
	v_mov_b32_e32 v35, 0
	v_mov_b32_e32 v36, 0
	v_mov_b32_e32 v37, 0
	v_mov_b32_e32 v38, 0
	v_mov_b32_e32 v39, 0
	v_mov_b32_e32 v40, 0
	v_mov_b32_e32 v41, 0
	v_mov_b32_e32 v42, 0
	v_mov_b32_e32 v43, 0
	v_mov_b32_e32 v44, 0
	v_mov_b32_e32 v45, 0
	v_mov_b32_e32 v46, 0
	v_mov_b32_e32 v47, 0
	v_mov_b32_e32 v16, 0
	v_mov_b32_e32 v17, 0
	v_mov_b32_e32 v18, 0
	v_mov_b32_e32 v19, 0
	v_mov_b32_e32 v20, 0
	v_mov_b32_e32 v21, 0
	v_mov_b32_e32 v22, 0
	v_mov_b32_e32 v23, 0
	v_mov_b32_e32 v24, 0
	v_mov_b32_e32 v25, 0
	v_mov_b32_e32 v26, 0
	v_mov_b32_e32 v27, 0
	v_mov_b32_e32 v28, 0
	v_mov_b32_e32 v29, 0
	v_mov_b32_e32 v30, 0
	v_mov_b32_e32 v31, 0
	v_mov_b32_e32 v0, 0
	v_mov_b32_e32 v1, 0
	v_mov_b32_e32 v2, 0
	v_mov_b32_e32 v3, 0
	v_mov_b32_e32 v4, 0
	v_mov_b32_e32 v5, 0
	v_mov_b32_e32 v6, 0
	v_mov_b32_e32 v7, 0
	v_mov_b32_e32 v8, 0
	v_mov_b32_e32 v9, 0
	v_mov_b32_e32 v10, 0
	v_mov_b32_e32 v11, 0
	v_mov_b32_e32 v12, 0
	v_mov_b32_e32 v13, 0
	v_mov_b32_e32 v14, 0
	v_mov_b32_e32 v15, 0
	s_mov_b32 s39, 7
.Lgk_loop_p19:
	s_waitcnt vmcnt(8)
	s_barrier
	ds_read_b128 v[64:67], v113
	ds_read_b128 v[68:71], v114 offset:16384
	ds_read_b128 v[72:75], v114 offset:20480
	ds_read_b128 v[82:85], v114 offset:24576
	ds_read_b128 v[86:89], v114 offset:28672
	ds_read_b128 v[90:93], v115
	ds_read_b128 v[122:125], v116 offset:16384
	ds_read_b128 v[126:129], v116 offset:20480
	ds_read_b128 v[130:133], v116 offset:24576
	ds_read_b128 v[134:137], v116 offset:28672
	ds_read_b128 v[138:141], v117
	ds_read_b128 v[218:221], v118 offset:16384
	ds_read_b128 v[222:225], v118 offset:20480
	ds_read_b128 v[226:229], v118 offset:24576
	ds_read_b128 v[230:233], v118 offset:28672
	ds_read_b128 v[234:237], v119
	ds_read_b128 v[238:241], v120 offset:16384
	ds_read_b128 v[242:245], v120 offset:20480
	ds_read_b128 v[246:249], v120 offset:24576
	ds_read_b128 v[250:253], v120 offset:28672
	s_waitcnt lgkmcnt(0)
	s_barrier
	s_mov_b32 m0, s38
	s_setprio 1
	v_mfma_f32_32x32x16_bf16 v[48:63], v[64:67], v[68:71], v[48:63]
	v_mfma_f32_32x32x16_bf16 v[32:47], v[64:67], v[72:75], v[32:47]
	global_load_lds_dwordx4 v254, s[20:21]
	s_add_u32 m0, m0, 0x1000
	v_mfma_f32_32x32x16_bf16 v[16:31], v[64:67], v[82:85], v[16:31]
	v_mfma_f32_32x32x16_bf16 v[0:15], v[64:67], v[86:89], v[0:15]
	global_load_lds_dwordx4 v254, s[22:23]
	s_add_u32 m0, m0, 0x1000
	v_mfma_f32_32x32x16_bf16 v[48:63], v[90:93], v[122:125], v[48:63]
	v_mfma_f32_32x32x16_bf16 v[32:47], v[90:93], v[126:129], v[32:47]
	global_load_lds_dwordx4 v254, s[24:25]
	s_add_u32 m0, m0, 0x1000
	v_mfma_f32_32x32x16_bf16 v[16:31], v[90:93], v[130:133], v[16:31]
	v_mfma_f32_32x32x16_bf16 v[0:15], v[90:93], v[134:137], v[0:15]
	global_load_lds_dwordx4 v254, s[26:27]
	s_add_u32 m0, m0, 0x1000
	v_mfma_f32_32x32x16_bf16 v[48:63], v[138:141], v[218:221], v[48:63]
	v_mfma_f32_32x32x16_bf16 v[32:47], v[138:141], v[222:225], v[32:47]
	global_load_lds_dwordx4 v254, s[28:29]
	s_add_u32 m0, m0, 0x1000
	v_mfma_f32_32x32x16_bf16 v[16:31], v[138:141], v[226:229], v[16:31]
	v_mfma_f32_32x32x16_bf16 v[0:15], v[138:141], v[230:233], v[0:15]
	global_load_lds_dwordx4 v254, s[30:31]
	s_add_u32 m0, m0, 0x1000
	v_mfma_f32_32x32x16_bf16 v[48:63], v[234:237], v[238:241], v[48:63]
	v_mfma_f32_32x32x16_bf16 v[32:47], v[234:237], v[242:245], v[32:47]
	global_load_lds_dwordx4 v254, s[34:35]
	s_add_u32 m0, m0, 0x1000
	v_mfma_f32_32x32x16_bf16 v[16:31], v[234:237], v[246:249], v[16:31]
	v_mfma_f32_32x32x16_bf16 v[0:15], v[234:237], v[250:253], v[0:15]
	global_load_lds_dwordx4 v254, s[36:37]
	s_setprio 0
	v_add_u32_e32 v254, 0x80, v254
	s_waitcnt vmcnt(8)
	s_barrier
	ds_read_b128 v[64:67], v113 offset:32768
	ds_read_b128 v[68:71], v114 offset:49152
	ds_read_b128 v[72:75], v114 offset:53248
	ds_read_b128 v[82:85], v114 offset:57344
	ds_read_b128 v[86:89], v114 offset:61440
	ds_read_b128 v[90:93], v115 offset:32768
	ds_read_b128 v[122:125], v116 offset:49152
	ds_read_b128 v[126:129], v116 offset:53248
	ds_read_b128 v[130:133], v116 offset:57344
	ds_read_b128 v[134:137], v116 offset:61440
	ds_read_b128 v[138:141], v117 offset:32768
	ds_read_b128 v[218:221], v118 offset:49152
	ds_read_b128 v[222:225], v118 offset:53248
	ds_read_b128 v[226:229], v118 offset:57344
	ds_read_b128 v[230:233], v118 offset:61440
	ds_read_b128 v[234:237], v119 offset:32768
	ds_read_b128 v[238:241], v120 offset:49152
	ds_read_b128 v[242:245], v120 offset:53248
	ds_read_b128 v[246:249], v120 offset:57344
	ds_read_b128 v[250:253], v120 offset:61440
	s_waitcnt lgkmcnt(0)
	s_barrier
	s_add_u32 m0, s38, 0x8000
	s_setprio 1
	v_mfma_f32_32x32x16_bf16 v[48:63], v[64:67], v[68:71], v[48:63]
	v_mfma_f32_32x32x16_bf16 v[32:47], v[64:67], v[72:75], v[32:47]
	global_load_lds_dwordx4 v254, s[20:21]
	s_add_u32 m0, m0, 0x1000
	v_mfma_f32_32x32x16_bf16 v[16:31], v[64:67], v[82:85], v[16:31]
	v_mfma_f32_32x32x16_bf16 v[0:15], v[64:67], v[86:89], v[0:15]
	global_load_lds_dwordx4 v254, s[22:23]
	s_add_u32 m0, m0, 0x1000
	v_mfma_f32_32x32x16_bf16 v[48:63], v[90:93], v[122:125], v[48:63]
	v_mfma_f32_32x32x16_bf16 v[32:47], v[90:93], v[126:129], v[32:47]
	global_load_lds_dwordx4 v254, s[24:25]
	s_add_u32 m0, m0, 0x1000
	v_mfma_f32_32x32x16_bf16 v[16:31], v[90:93], v[130:133], v[16:31]
	v_mfma_f32_32x32x16_bf16 v[0:15], v[90:93], v[134:137], v[0:15]
	global_load_lds_dwordx4 v254, s[26:27]
	s_add_u32 m0, m0, 0x1000
	v_mfma_f32_32x32x16_bf16 v[48:63], v[138:141], v[218:221], v[48:63]
	v_mfma_f32_32x32x16_bf16 v[32:47], v[138:141], v[222:225], v[32:47]
	global_load_lds_dwordx4 v254, s[28:29]
	s_add_u32 m0, m0, 0x1000
	v_mfma_f32_32x32x16_bf16 v[16:31], v[138:141], v[226:229], v[16:31]
	v_mfma_f32_32x32x16_bf16 v[0:15], v[138:141], v[230:233], v[0:15]
	global_load_lds_dwordx4 v254, s[30:31]
	s_add_u32 m0, m0, 0x1000
	v_mfma_f32_32x32x16_bf16 v[48:63], v[234:237], v[238:241], v[48:63]
	v_mfma_f32_32x32x16_bf16 v[32:47], v[234:237], v[242:245], v[32:47]
	global_load_lds_dwordx4 v254, s[34:35]
	s_add_u32 m0, m0, 0x1000
	v_mfma_f32_32x32x16_bf16 v[16:31], v[234:237], v[246:249], v[16:31]
	v_mfma_f32_32x32x16_bf16 v[0:15], v[234:237], v[250:253], v[0:15]
	global_load_lds_dwordx4 v254, s[36:37]
	s_setprio 0
	v_add_u32_e32 v254, 0x80, v254
	s_sub_u32 s39, s39, 1
	s_cmp_lg_u32 s39, 0
	s_cbranch_scc1 .Lgk_loop_p19
	s_waitcnt vmcnt(8)
	s_barrier
	ds_read_b128 v[64:67], v113
	ds_read_b128 v[68:71], v114 offset:16384
	ds_read_b128 v[72:75], v114 offset:20480
	ds_read_b128 v[82:85], v114 offset:24576
	ds_read_b128 v[86:89], v114 offset:28672
	ds_read_b128 v[90:93], v115
	ds_read_b128 v[122:125], v116 offset:16384
	ds_read_b128 v[126:129], v116 offset:20480
	ds_read_b128 v[130:133], v116 offset:24576
	ds_read_b128 v[134:137], v116 offset:28672
	ds_read_b128 v[138:141], v117
	ds_read_b128 v[218:221], v118 offset:16384
	ds_read_b128 v[222:225], v118 offset:20480
	ds_read_b128 v[226:229], v118 offset:24576
	ds_read_b128 v[230:233], v118 offset:28672
	ds_read_b128 v[234:237], v119
	ds_read_b128 v[238:241], v120 offset:16384
	ds_read_b128 v[242:245], v120 offset:20480
	ds_read_b128 v[246:249], v120 offset:24576
	ds_read_b128 v[250:253], v120 offset:28672
	s_waitcnt lgkmcnt(0)
	s_barrier
	s_setprio 1
	v_mfma_f32_32x32x16_bf16 v[48:63], v[64:67], v[68:71], v[48:63]
	v_mfma_f32_32x32x16_bf16 v[32:47], v[64:67], v[72:75], v[32:47]
	v_mfma_f32_32x32x16_bf16 v[16:31], v[64:67], v[82:85], v[16:31]
	v_mfma_f32_32x32x16_bf16 v[0:15], v[64:67], v[86:89], v[0:15]
	v_mfma_f32_32x32x16_bf16 v[48:63], v[90:93], v[122:125], v[48:63]
	v_mfma_f32_32x32x16_bf16 v[32:47], v[90:93], v[126:129], v[32:47]
	v_mfma_f32_32x32x16_bf16 v[16:31], v[90:93], v[130:133], v[16:31]
	v_mfma_f32_32x32x16_bf16 v[0:15], v[90:93], v[134:137], v[0:15]
	v_mfma_f32_32x32x16_bf16 v[48:63], v[138:141], v[218:221], v[48:63]
	v_mfma_f32_32x32x16_bf16 v[32:47], v[138:141], v[222:225], v[32:47]
	v_mfma_f32_32x32x16_bf16 v[16:31], v[138:141], v[226:229], v[16:31]
	v_mfma_f32_32x32x16_bf16 v[0:15], v[138:141], v[230:233], v[0:15]
	v_mfma_f32_32x32x16_bf16 v[48:63], v[234:237], v[238:241], v[48:63]
	v_mfma_f32_32x32x16_bf16 v[32:47], v[234:237], v[242:245], v[32:47]
	v_mfma_f32_32x32x16_bf16 v[16:31], v[234:237], v[246:249], v[16:31]
	v_mfma_f32_32x32x16_bf16 v[0:15], v[234:237], v[250:253], v[0:15]
	s_setprio 0
	s_waitcnt vmcnt(0)
	s_barrier
	ds_read_b128 v[64:67], v113 offset:32768
	ds_read_b128 v[68:71], v114 offset:49152
	ds_read_b128 v[72:75], v114 offset:53248
	ds_read_b128 v[82:85], v114 offset:57344
	ds_read_b128 v[86:89], v114 offset:61440
	ds_read_b128 v[90:93], v115 offset:32768
	ds_read_b128 v[122:125], v116 offset:49152
	ds_read_b128 v[126:129], v116 offset:53248
	ds_read_b128 v[130:133], v116 offset:57344
	ds_read_b128 v[134:137], v116 offset:61440
	ds_read_b128 v[138:141], v117 offset:32768
	ds_read_b128 v[218:221], v118 offset:49152
	ds_read_b128 v[222:225], v118 offset:53248
	ds_read_b128 v[226:229], v118 offset:57344
	ds_read_b128 v[230:233], v118 offset:61440
	ds_read_b128 v[234:237], v119 offset:32768
	ds_read_b128 v[238:241], v120 offset:49152
	ds_read_b128 v[242:245], v120 offset:53248
	ds_read_b128 v[246:249], v120 offset:57344
	ds_read_b128 v[250:253], v120 offset:61440
	s_waitcnt lgkmcnt(0)
	s_barrier
	s_setprio 1
	v_mfma_f32_32x32x16_bf16 v[48:63], v[64:67], v[68:71], v[48:63]
	v_mfma_f32_32x32x16_bf16 v[32:47], v[64:67], v[72:75], v[32:47]
	v_mfma_f32_32x32x16_bf16 v[16:31], v[64:67], v[82:85], v[16:31]
	v_mfma_f32_32x32x16_bf16 v[0:15], v[64:67], v[86:89], v[0:15]
	v_mfma_f32_32x32x16_bf16 v[48:63], v[90:93], v[122:125], v[48:63]
	v_mfma_f32_32x32x16_bf16 v[32:47], v[90:93], v[126:129], v[32:47]
	v_mfma_f32_32x32x16_bf16 v[16:31], v[90:93], v[130:133], v[16:31]
	v_mfma_f32_32x32x16_bf16 v[0:15], v[90:93], v[134:137], v[0:15]
	v_mfma_f32_32x32x16_bf16 v[48:63], v[138:141], v[218:221], v[48:63]
	v_mfma_f32_32x32x16_bf16 v[32:47], v[138:141], v[222:225], v[32:47]
	v_mfma_f32_32x32x16_bf16 v[16:31], v[138:141], v[226:229], v[16:31]
	v_mfma_f32_32x32x16_bf16 v[0:15], v[138:141], v[230:233], v[0:15]
	v_mfma_f32_32x32x16_bf16 v[48:63], v[234:237], v[238:241], v[48:63]
	v_mfma_f32_32x32x16_bf16 v[32:47], v[234:237], v[242:245], v[32:47]
	v_mfma_f32_32x32x16_bf16 v[16:31], v[234:237], v[246:249], v[16:31]
	v_mfma_f32_32x32x16_bf16 v[0:15], v[234:237], v[250:253], v[0:15]
	s_setprio 0
	s_branch .LBB0_1450

.LBB0_1565:
	s_ashr_i32 s6, s3, 31
	s_lshr_b32 s6, s6, 26
	s_add_i32 s6, s3, s6
	s_ashr_i32 s58, s6, 6
	s_andn2_b32 s6, s6, 63
	s_sub_i32 s6, s3, s6
	s_ashr_i32 s59, s6, 31
	s_lshr_b32 s59, s59, 29
	s_add_i32 s59, s6, s59
	s_ashr_i32 s64, s59, 3
	s_and_b32 s59, s59, -8
	s_lshl_b32 s58, s58, 3
	s_sub_i32 s6, s6, s59
	s_add_i32 s6, s6, s58
	s_lshl_b32 s66, s6, 7
	s_ashr_i32 s67, s66, 31
	s_lshl_b32 s68, s64, 7
	s_lshl_b64 s[58:59], s[66:67], 11
	s_ashr_i32 s69, s68, 31
	s_lshl_b32 s38, s66, 11
	s_add_u32 s18, s14, s38
	s_addc_u32 s19, s15, 0
	s_add_u32 s18, s18, 0xdf9f000
	s_addc_u32 s19, s19, 0
	s_add_u32 s20, s18, 0x10000
	s_addc_u32 s21, s19, 0
	s_add_u32 s22, s20, 0x10000
	s_addc_u32 s23, s21, 0
	s_add_u32 s24, s22, 0x10000
	s_addc_u32 s25, s23, 0
	s_lshl_b32 s38, s68, 11
	s_add_u32 s26, s14, s38
	s_addc_u32 s27, s15, 0
	s_add_u32 s26, s26, 0x17a0000
	s_addc_u32 s27, s27, 0
	s_add_u32 s28, s26, 0x10000
	s_addc_u32 s29, s27, 0
	s_add_u32 s30, s28, 0x10000
	s_addc_u32 s31, s29, 0
	s_add_u32 s34, s30, 0x10000
	s_addc_u32 s35, s31, 0
	v_readfirstlane_b32 s36, v140
	v_mov_b32_e32 v254, v64
	s_mov_b32 m0, s36
	s_nop 0
	global_load_lds_dwordx4 v254, s[18:19]
	s_add_u32 m0, m0, 0x1000
	s_nop 0
	global_load_lds_dwordx4 v254, s[20:21]
	s_add_u32 m0, m0, 0x1000
	s_nop 0
	global_load_lds_dwordx4 v254, s[22:23]
	s_add_u32 m0, m0, 0x1000
	s_nop 0
	global_load_lds_dwordx4 v254, s[24:25]
	s_add_u32 m0, m0, 0x1000
	s_nop 0
	global_load_lds_dwordx4 v254, s[26:27]
	s_add_u32 m0, m0, 0x1000
	s_nop 0
	global_load_lds_dwordx4 v254, s[28:29]
	s_add_u32 m0, m0, 0x1000
	s_nop 0
	global_load_lds_dwordx4 v254, s[30:31]
	s_add_u32 m0, m0, 0x1000
	s_nop 0
	global_load_lds_dwordx4 v254, s[34:35]
	v_add_u32_e32 v254, 0x80, v254
	s_add_u32 m0, s36, 0x8000
	s_nop 0
	global_load_lds_dwordx4 v254, s[18:19]
	s_add_u32 m0, m0, 0x1000
	s_nop 0
	global_load_lds_dwordx4 v254, s[20:21]
	s_add_u32 m0, m0, 0x1000
	s_nop 0
	global_load_lds_dwordx4 v254, s[22:23]
	s_add_u32 m0, m0, 0x1000
	s_nop 0
	global_load_lds_dwordx4 v254, s[24:25]
	s_add_u32 m0, m0, 0x1000
	s_nop 0
	global_load_lds_dwordx4 v254, s[26:27]
	s_add_u32 m0, m0, 0x1000
	s_nop 0
	global_load_lds_dwordx4 v254, s[28:29]
	s_add_u32 m0, m0, 0x1000
	s_nop 0
	global_load_lds_dwordx4 v254, s[30:31]
	s_add_u32 m0, m0, 0x1000
	s_nop 0
	global_load_lds_dwordx4 v254, s[34:35]
	v_add_u32_e32 v254, 0x80, v254
	v_mov_b32_e32 v48, 0
	v_mov_b32_e32 v49, 0
	v_mov_b32_e32 v50, 0
	v_mov_b32_e32 v51, 0
	v_mov_b32_e32 v52, 0
	v_mov_b32_e32 v53, 0
	v_mov_b32_e32 v54, 0
	v_mov_b32_e32 v55, 0
	v_mov_b32_e32 v56, 0
	v_mov_b32_e32 v57, 0
	v_mov_b32_e32 v58, 0
	v_mov_b32_e32 v59, 0
	v_mov_b32_e32 v60, 0
	v_mov_b32_e32 v61, 0
	v_mov_b32_e32 v62, 0
	v_mov_b32_e32 v63, 0
	v_mov_b32_e32 v32, 0
	v_mov_b32_e32 v33, 0
	v_mov_b32_e32 v34, 0
	v_mov_b32_e32 v35, 0
	v_mov_b32_e32 v36, 0
	v_mov_b32_e32 v37, 0
	v_mov_b32_e32 v38, 0
	v_mov_b32_e32 v39, 0
	v_mov_b32_e32 v40, 0
	v_mov_b32_e32 v41, 0
	v_mov_b32_e32 v42, 0
	v_mov_b32_e32 v43, 0
	v_mov_b32_e32 v44, 0
	v_mov_b32_e32 v45, 0
	v_mov_b32_e32 v46, 0
	v_mov_b32_e32 v47, 0
	v_mov_b32_e32 v16, 0
	v_mov_b32_e32 v17, 0
	v_mov_b32_e32 v18, 0
	v_mov_b32_e32 v19, 0
	v_mov_b32_e32 v20, 0
	v_mov_b32_e32 v21, 0
	v_mov_b32_e32 v22, 0
	v_mov_b32_e32 v23, 0
	v_mov_b32_e32 v24, 0
	v_mov_b32_e32 v25, 0
	v_mov_b32_e32 v26, 0
	v_mov_b32_e32 v27, 0
	v_mov_b32_e32 v28, 0
	v_mov_b32_e32 v29, 0
	v_mov_b32_e32 v30, 0
	v_mov_b32_e32 v31, 0
	v_mov_b32_e32 v0, 0
	v_mov_b32_e32 v1, 0
	v_mov_b32_e32 v2, 0
	v_mov_b32_e32 v3, 0
	v_mov_b32_e32 v4, 0
	v_mov_b32_e32 v5, 0
	v_mov_b32_e32 v6, 0
	v_mov_b32_e32 v7, 0
	v_mov_b32_e32 v8, 0
	v_mov_b32_e32 v9, 0
	v_mov_b32_e32 v10, 0
	v_mov_b32_e32 v11, 0
	v_mov_b32_e32 v12, 0
	v_mov_b32_e32 v13, 0
	v_mov_b32_e32 v14, 0
	v_mov_b32_e32 v15, 0
	s_mov_b32 s37, 7

.Lmap_done_3:
	s_lshl_b32 s60, s4, 7
	s_lshl_b32 s58, s76, 7
	s_ashr_i32 s61, s60, 31
	s_ashr_i32 s59, s58, 31
	s_lshl_b64 s[62:63], s[60:61], 11
	s_lshl_b64 s[64:65], s[58:59], 11
	s_lshl_b32 s38, s60, 11
	s_add_u32 s18, s14, s38
	s_addc_u32 s19, s15, 0
	s_add_u32 s18, s18, 0x679f000
	s_addc_u32 s19, s19, 0
	s_add_u32 s20, s18, 0x10000
	s_addc_u32 s21, s19, 0
	s_add_u32 s22, s20, 0x10000
	s_addc_u32 s23, s21, 0
	s_add_u32 s24, s22, 0x10000
	s_addc_u32 s25, s23, 0
	s_lshl_b32 s38, s58, 11
	s_add_u32 s26, s14, s38
	s_addc_u32 s27, s15, 0
	s_add_u32 s26, s26, 0x3aa0000
	s_addc_u32 s27, s27, 0
	s_add_u32 s28, s26, 0x10000
	s_addc_u32 s29, s27, 0
	s_add_u32 s30, s28, 0x10000
	s_addc_u32 s31, s29, 0
	s_add_u32 s34, s30, 0x10000
	s_addc_u32 s35, s31, 0
	v_readfirstlane_b32 s36, v94
	v_mov_b32_e32 v254, v76
	s_mov_b32 m0, s36
	s_nop 0
	global_load_lds_dwordx4 v254, s[18:19]
	s_add_u32 m0, m0, 0x1000
	s_nop 0
	global_load_lds_dwordx4 v254, s[20:21]
	s_add_u32 m0, m0, 0x1000
	s_nop 0
	global_load_lds_dwordx4 v254, s[22:23]
	s_add_u32 m0, m0, 0x1000
	s_nop 0
	global_load_lds_dwordx4 v254, s[24:25]
	s_add_u32 m0, m0, 0x1000
	s_nop 0
	global_load_lds_dwordx4 v254, s[26:27]
	s_add_u32 m0, m0, 0x1000
	s_nop 0
	global_load_lds_dwordx4 v254, s[28:29]
	s_add_u32 m0, m0, 0x1000
	s_nop 0
	global_load_lds_dwordx4 v254, s[30:31]
	s_add_u32 m0, m0, 0x1000
	s_nop 0
	global_load_lds_dwordx4 v254, s[34:35]
	v_add_u32_e32 v254, 0x80, v254
	s_add_u32 m0, s36, 0x8000
	s_nop 0
	global_load_lds_dwordx4 v254, s[18:19]
	s_add_u32 m0, m0, 0x1000
	s_nop 0
	global_load_lds_dwordx4 v254, s[20:21]
	s_add_u32 m0, m0, 0x1000
	s_nop 0
	global_load_lds_dwordx4 v254, s[22:23]
	s_add_u32 m0, m0, 0x1000
	s_nop 0
	global_load_lds_dwordx4 v254, s[24:25]
	s_add_u32 m0, m0, 0x1000
	s_nop 0
	global_load_lds_dwordx4 v254, s[26:27]
	s_add_u32 m0, m0, 0x1000
	s_nop 0
	global_load_lds_dwordx4 v254, s[28:29]
	s_add_u32 m0, m0, 0x1000
	s_nop 0
	global_load_lds_dwordx4 v254, s[30:31]
	s_add_u32 m0, m0, 0x1000
	s_nop 0
	global_load_lds_dwordx4 v254, s[34:35]
	v_add_u32_e32 v254, 0x80, v254
	v_mov_b32_e32 v48, 0
	v_mov_b32_e32 v49, 0
	v_mov_b32_e32 v50, 0
	v_mov_b32_e32 v51, 0
	v_mov_b32_e32 v52, 0
	v_mov_b32_e32 v53, 0
	v_mov_b32_e32 v54, 0
	v_mov_b32_e32 v55, 0
	v_mov_b32_e32 v56, 0
	v_mov_b32_e32 v57, 0
	v_mov_b32_e32 v58, 0
	v_mov_b32_e32 v59, 0
	v_mov_b32_e32 v60, 0
	v_mov_b32_e32 v61, 0
	v_mov_b32_e32 v62, 0
	v_mov_b32_e32 v63, 0
	v_mov_b32_e32 v32, 0
	v_mov_b32_e32 v33, 0
	v_mov_b32_e32 v34, 0
	v_mov_b32_e32 v35, 0
	v_mov_b32_e32 v36, 0
	v_mov_b32_e32 v37, 0
	v_mov_b32_e32 v38, 0
	v_mov_b32_e32 v39, 0
	v_mov_b32_e32 v40, 0
	v_mov_b32_e32 v41, 0
	v_mov_b32_e32 v42, 0
	v_mov_b32_e32 v43, 0
	v_mov_b32_e32 v44, 0
	v_mov_b32_e32 v45, 0
	v_mov_b32_e32 v46, 0
	v_mov_b32_e32 v47, 0
	v_mov_b32_e32 v16, 0
	v_mov_b32_e32 v17, 0
	v_mov_b32_e32 v18, 0
	v_mov_b32_e32 v19, 0
	v_mov_b32_e32 v20, 0
	v_mov_b32_e32 v21, 0
	v_mov_b32_e32 v22, 0
	v_mov_b32_e32 v23, 0
	v_mov_b32_e32 v24, 0
	v_mov_b32_e32 v25, 0
	v_mov_b32_e32 v26, 0
	v_mov_b32_e32 v27, 0
	v_mov_b32_e32 v28, 0
	v_mov_b32_e32 v29, 0
	v_mov_b32_e32 v30, 0
	v_mov_b32_e32 v31, 0
	v_mov_b32_e32 v0, 0
	v_mov_b32_e32 v1, 0
	v_mov_b32_e32 v2, 0
	v_mov_b32_e32 v3, 0
	v_mov_b32_e32 v4, 0
	v_mov_b32_e32 v5, 0
	v_mov_b32_e32 v6, 0
	v_mov_b32_e32 v7, 0
	v_mov_b32_e32 v8, 0
	v_mov_b32_e32 v9, 0
	v_mov_b32_e32 v10, 0
	v_mov_b32_e32 v11, 0
	v_mov_b32_e32 v12, 0
	v_mov_b32_e32 v13, 0
	v_mov_b32_e32 v14, 0
	v_mov_b32_e32 v15, 0
	s_mov_b32 s37, 7

.LBB0_1637:
	s_ashr_i32 s2, s10, 31
	s_lshr_b32 s2, s2, 26
	s_add_i32 s2, s10, s2
	s_ashr_i32 s11, s2, 6
	s_andn2_b32 s2, s2, 63
	s_sub_i32 s2, s10, s2
	s_ashr_i32 s16, s2, 31
	s_lshr_b32 s16, s16, 29
	s_add_i32 s16, s2, s16
	s_and_b32 s52, s16, -8
	s_lshl_b32 s11, s11, 3
	s_sub_i32 s2, s2, s52
	s_add_i32 s2, s2, s11
	s_lshl_b32 s16, s16, 4
	s_lshl_b32 s11, s2, 7
	s_and_b32 s16, s16, 0xffffff80
	s_mul_i32 s38, s2, 0xb0000
	s_add_u32 s18, s14, s38
	s_addc_u32 s19, s15, 0
	s_add_u32 s18, s18, 0x879f000
	s_addc_u32 s19, s19, 0
	s_add_u32 s20, s18, 0x2c000
	s_addc_u32 s21, s19, 0
	s_add_u32 s22, s20, 0x2c000
	s_addc_u32 s23, s21, 0
	s_add_u32 s24, s22, 0x2c000
	s_addc_u32 s25, s23, 0
	s_mul_i32 s38, s16, 0x1600
	s_add_u32 s26, s14, s38
	s_addc_u32 s27, s15, 0
	s_add_u32 s26, s26, 0x5620000
	s_addc_u32 s27, s27, 0
	s_add_u32 s28, s26, 0x2c000
	s_addc_u32 s29, s27, 0
	s_add_u32 s30, s28, 0x2c000
	s_addc_u32 s31, s29, 0
	s_add_u32 s34, s30, 0x2c000
	s_addc_u32 s35, s31, 0
	v_readfirstlane_b32 s36, v77
	v_mov_b32_e32 v254, v64
	s_mov_b32 m0, s36
	s_nop 0
	global_load_lds_dwordx4 v254, s[18:19]
	s_add_u32 m0, m0, 0x1000
	s_nop 0
	global_load_lds_dwordx4 v254, s[20:21]
	s_add_u32 m0, m0, 0x1000
	s_nop 0
	global_load_lds_dwordx4 v254, s[22:23]
	s_add_u32 m0, m0, 0x1000
	s_nop 0
	global_load_lds_dwordx4 v254, s[24:25]
	s_add_u32 m0, m0, 0x1000
	s_nop 0
	global_load_lds_dwordx4 v254, s[26:27]
	s_add_u32 m0, m0, 0x1000
	s_nop 0
	global_load_lds_dwordx4 v254, s[28:29]
	s_add_u32 m0, m0, 0x1000
	s_nop 0
	global_load_lds_dwordx4 v254, s[30:31]
	s_add_u32 m0, m0, 0x1000
	s_nop 0
	global_load_lds_dwordx4 v254, s[34:35]
	v_add_u32_e32 v254, 0x80, v254
	s_add_u32 m0, s36, 0x8000
	s_nop 0
	global_load_lds_dwordx4 v254, s[18:19]
	s_add_u32 m0, m0, 0x1000
	s_nop 0
	global_load_lds_dwordx4 v254, s[20:21]
	s_add_u32 m0, m0, 0x1000
	s_nop 0
	global_load_lds_dwordx4 v254, s[22:23]
	s_add_u32 m0, m0, 0x1000
	s_nop 0
	global_load_lds_dwordx4 v254, s[24:25]
	s_add_u32 m0, m0, 0x1000
	s_nop 0
	global_load_lds_dwordx4 v254, s[26:27]
	s_add_u32 m0, m0, 0x1000
	s_nop 0
	global_load_lds_dwordx4 v254, s[28:29]
	s_add_u32 m0, m0, 0x1000
	s_nop 0
	global_load_lds_dwordx4 v254, s[30:31]
	s_add_u32 m0, m0, 0x1000
	s_nop 0
	global_load_lds_dwordx4 v254, s[34:35]
	v_add_u32_e32 v254, 0x80, v254
	v_mov_b32_e32 v48, 0
	v_mov_b32_e32 v49, 0
	v_mov_b32_e32 v50, 0
	v_mov_b32_e32 v51, 0
	v_mov_b32_e32 v52, 0
	v_mov_b32_e32 v53, 0
	v_mov_b32_e32 v54, 0
	v_mov_b32_e32 v55, 0
	v_mov_b32_e32 v56, 0
	v_mov_b32_e32 v57, 0
	v_mov_b32_e32 v58, 0
	v_mov_b32_e32 v59, 0
	v_mov_b32_e32 v60, 0
	v_mov_b32_e32 v61, 0
	v_mov_b32_e32 v62, 0
	v_mov_b32_e32 v63, 0
	v_mov_b32_e32 v32, 0
	v_mov_b32_e32 v33, 0
	v_mov_b32_e32 v34, 0
	v_mov_b32_e32 v35, 0
	v_mov_b32_e32 v36, 0
	v_mov_b32_e32 v37, 0
	v_mov_b32_e32 v38, 0
	v_mov_b32_e32 v39, 0
	v_mov_b32_e32 v40, 0
	v_mov_b32_e32 v41, 0
	v_mov_b32_e32 v42, 0
	v_mov_b32_e32 v43, 0
	v_mov_b32_e32 v44, 0
	v_mov_b32_e32 v45, 0
	v_mov_b32_e32 v46, 0
	v_mov_b32_e32 v47, 0
	v_mov_b32_e32 v16, 0
	v_mov_b32_e32 v17, 0
	v_mov_b32_e32 v18, 0
	v_mov_b32_e32 v19, 0
	v_mov_b32_e32 v20, 0
	v_mov_b32_e32 v21, 0
	v_mov_b32_e32 v22, 0
	v_mov_b32_e32 v23, 0
	v_mov_b32_e32 v24, 0
	v_mov_b32_e32 v25, 0
	v_mov_b32_e32 v26, 0
	v_mov_b32_e32 v27, 0
	v_mov_b32_e32 v28, 0
	v_mov_b32_e32 v29, 0
	v_mov_b32_e32 v30, 0
	v_mov_b32_e32 v31, 0
	v_mov_b32_e32 v0, 0
	v_mov_b32_e32 v1, 0
	v_mov_b32_e32 v2, 0
	v_mov_b32_e32 v3, 0
	v_mov_b32_e32 v4, 0
	v_mov_b32_e32 v5, 0
	v_mov_b32_e32 v6, 0
	v_mov_b32_e32 v7, 0
	v_mov_b32_e32 v8, 0
	v_mov_b32_e32 v9, 0
	v_mov_b32_e32 v10, 0
	v_mov_b32_e32 v11, 0
	v_mov_b32_e32 v12, 0
	v_mov_b32_e32 v13, 0
	v_mov_b32_e32 v14, 0
	v_mov_b32_e32 v15, 0
	s_mov_b32 s37, 21
.Lgk_loop_p26:
	s_waitcnt vmcnt(8)
	s_barrier
	ds_read_b128 v[70:73], v93
	ds_read_b128 v[102:105], v94 offset:16384
	ds_read_b128 v[106:109], v94 offset:20480
	ds_read_b128 v[110:113], v94 offset:24576
	ds_read_b128 v[114:117], v94 offset:28672
	ds_read_b128 v[118:121], v95
	ds_read_b128 v[122:125], v96 offset:16384
	ds_read_b128 v[126:129], v96 offset:20480
	ds_read_b128 v[130:133], v96 offset:24576
	ds_read_b128 v[134:137], v96 offset:28672
	ds_read_b128 v[138:141], v97
	ds_read_b128 v[162:165], v98 offset:16384
	ds_read_b128 v[166:169], v98 offset:20480
	ds_read_b128 v[170:173], v98 offset:24576
	ds_read_b128 v[174:177], v98 offset:28672
	ds_read_b128 v[178:181], v99
	ds_read_b128 v[182:185], v100 offset:16384
	ds_read_b128 v[186:189], v100 offset:20480
	ds_read_b128 v[190:193], v100 offset:24576
	ds_read_b128 v[194:197], v100 offset:28672
	s_waitcnt lgkmcnt(0)
	s_barrier
	s_mov_b32 m0, s36
	s_setprio 1
	v_mfma_f32_32x32x16_bf16 v[48:63], v[70:73], v[102:105], v[48:63]
	v_mfma_f32_32x32x16_bf16 v[32:47], v[70:73], v[106:109], v[32:47]
	global_load_lds_dwordx4 v254, s[18:19]
	s_add_u32 m0, m0, 0x1000
	v_mfma_f32_32x32x16_bf16 v[16:31], v[70:73], v[110:113], v[16:31]
	v_mfma_f32_32x32x16_bf16 v[0:15], v[70:73], v[114:117], v[0:15]
	global_load_lds_dwordx4 v254, s[20:21]
	s_add_u32 m0, m0, 0x1000
	v_mfma_f32_32x32x16_bf16 v[48:63], v[118:121], v[122:125], v[48:63]
	v_mfma_f32_32x32x16_bf16 v[32:47], v[118:121], v[126:129], v[32:47]
	global_load_lds_dwordx4 v254, s[22:23]
	s_add_u32 m0, m0, 0x1000
	v_mfma_f32_32x32x16_bf16 v[16:31], v[118:121], v[130:133], v[16:31]
	v_mfma_f32_32x32x16_bf16 v[0:15], v[118:121], v[134:137], v[0:15]
	global_load_lds_dwordx4 v254, s[24:25]
	s_add_u32 m0, m0, 0x1000
	v_mfma_f32_32x32x16_bf16 v[48:63], v[138:141], v[162:165], v[48:63]
	v_mfma_f32_32x32x16_bf16 v[32:47], v[138:141], v[166:169], v[32:47]
	global_load_lds_dwordx4 v254, s[26:27]
	s_add_u32 m0, m0, 0x1000
	v_mfma_f32_32x32x16_bf16 v[16:31], v[138:141], v[170:173], v[16:31]
	v_mfma_f32_32x32x16_bf16 v[0:15], v[138:141], v[174:177], v[0:15]
	global_load_lds_dwordx4 v254, s[28:29]
	s_add_u32 m0, m0, 0x1000
	v_mfma_f32_32x32x16_bf16 v[48:63], v[178:181], v[182:185], v[48:63]
	v_mfma_f32_32x32x16_bf16 v[32:47], v[178:181], v[186:189], v[32:47]
	global_load_lds_dwordx4 v254, s[30:31]
	s_add_u32 m0, m0, 0x1000
	v_mfma_f32_32x32x16_bf16 v[16:31], v[178:181], v[190:193], v[16:31]
	v_mfma_f32_32x32x16_bf16 v[0:15], v[178:181], v[194:197], v[0:15]
	global_load_lds_dwordx4 v254, s[34:35]
	s_setprio 0
	v_add_u32_e32 v254, 0x80, v254
	s_waitcnt vmcnt(8)
	s_barrier
	ds_read_b128 v[70:73], v93 offset:32768
	ds_read_b128 v[102:105], v94 offset:49152
	ds_read_b128 v[106:109], v94 offset:53248
	ds_read_b128 v[110:113], v94 offset:57344
	ds_read_b128 v[114:117], v94 offset:61440
	ds_read_b128 v[118:121], v95 offset:32768
	ds_read_b128 v[122:125], v96 offset:49152
	ds_read_b128 v[126:129], v96 offset:53248
	ds_read_b128 v[130:133], v96 offset:57344
	ds_read_b128 v[134:137], v96 offset:61440
	ds_read_b128 v[138:141], v97 offset:32768
	ds_read_b128 v[162:165], v98 offset:49152
	ds_read_b128 v[166:169], v98 offset:53248
	ds_read_b128 v[170:173], v98 offset:57344
	ds_read_b128 v[174:177], v98 offset:61440
	ds_read_b128 v[178:181], v99 offset:32768
	ds_read_b128 v[182:185], v100 offset:49152
	ds_read_b128 v[186:189], v100 offset:53248
	ds_read_b128 v[190:193], v100 offset:57344
	ds_read_b128 v[194:197], v100 offset:61440
	s_waitcnt lgkmcnt(0)
	s_barrier
	s_add_u32 m0, s36, 0x8000
	s_setprio 1
	v_mfma_f32_32x32x16_bf16 v[48:63], v[70:73], v[102:105], v[48:63]
	v_mfma_f32_32x32x16_bf16 v[32:47], v[70:73], v[106:109], v[32:47]
	global_load_lds_dwordx4 v254, s[18:19]
	s_add_u32 m0, m0, 0x1000
	v_mfma_f32_32x32x16_bf16 v[16:31], v[70:73], v[110:113], v[16:31]
	v_mfma_f32_32x32x16_bf16 v[0:15], v[70:73], v[114:117], v[0:15]
	global_load_lds_dwordx4 v254, s[20:21]
	s_add_u32 m0, m0, 0x1000
	v_mfma_f32_32x32x16_bf16 v[48:63], v[118:121], v[122:125], v[48:63]
	v_mfma_f32_32x32x16_bf16 v[32:47], v[118:121], v[126:129], v[32:47]
	global_load_lds_dwordx4 v254, s[22:23]
	s_add_u32 m0, m0, 0x1000
	v_mfma_f32_32x32x16_bf16 v[16:31], v[118:121], v[130:133], v[16:31]
	v_mfma_f32_32x32x16_bf16 v[0:15], v[118:121], v[134:137], v[0:15]
	global_load_lds_dwordx4 v254, s[24:25]
	s_add_u32 m0, m0, 0x1000
	v_mfma_f32_32x32x16_bf16 v[48:63], v[138:141], v[162:165], v[48:63]
	v_mfma_f32_32x32x16_bf16 v[32:47], v[138:141], v[166:169], v[32:47]
	global_load_lds_dwordx4 v254, s[26:27]
	s_add_u32 m0, m0, 0x1000
	v_mfma_f32_32x32x16_bf16 v[16:31], v[138:141], v[170:173], v[16:31]
	v_mfma_f32_32x32x16_bf16 v[0:15], v[138:141], v[174:177], v[0:15]
	global_load_lds_dwordx4 v254, s[28:29]
	s_add_u32 m0, m0, 0x1000
	v_mfma_f32_32x32x16_bf16 v[48:63], v[178:181], v[182:185], v[48:63]
	v_mfma_f32_32x32x16_bf16 v[32:47], v[178:181], v[186:189], v[32:47]
	global_load_lds_dwordx4 v254, s[30:31]
	s_add_u32 m0, m0, 0x1000
	v_mfma_f32_32x32x16_bf16 v[16:31], v[178:181], v[190:193], v[16:31]
	v_mfma_f32_32x32x16_bf16 v[0:15], v[178:181], v[194:197], v[0:15]
	global_load_lds_dwordx4 v254, s[34:35]
	s_setprio 0
	v_add_u32_e32 v254, 0x80, v254
	s_sub_u32 s37, s37, 1
	s_cmp_lg_u32 s37, 0
	s_cbranch_scc1 .Lgk_loop_p26
	s_waitcnt vmcnt(8)
	s_barrier
	ds_read_b128 v[70:73], v93
	ds_read_b128 v[102:105], v94 offset:16384
	ds_read_b128 v[106:109], v94 offset:20480
	ds_read_b128 v[110:113], v94 offset:24576
	ds_read_b128 v[114:117], v94 offset:28672
	ds_read_b128 v[118:121], v95
	ds_read_b128 v[122:125], v96 offset:16384
	ds_read_b128 v[126:129], v96 offset:20480
	ds_read_b128 v[130:133], v96 offset:24576
	ds_read_b128 v[134:137], v96 offset:28672
	ds_read_b128 v[138:141], v97
	ds_read_b128 v[162:165], v98 offset:16384
	ds_read_b128 v[166:169], v98 offset:20480
	ds_read_b128 v[170:173], v98 offset:24576
	ds_read_b128 v[174:177], v98 offset:28672
	ds_read_b128 v[178:181], v99
	ds_read_b128 v[182:185], v100 offset:16384
	ds_read_b128 v[186:189], v100 offset:20480
	ds_read_b128 v[190:193], v100 offset:24576
	ds_read_b128 v[194:197], v100 offset:28672
	s_waitcnt lgkmcnt(0)
	s_barrier
	s_setprio 1
	v_mfma_f32_32x32x16_bf16 v[48:63], v[70:73], v[102:105], v[48:63]
	v_mfma_f32_32x32x16_bf16 v[32:47], v[70:73], v[106:109], v[32:47]
	v_mfma_f32_32x32x16_bf16 v[16:31], v[70:73], v[110:113], v[16:31]
	v_mfma_f32_32x32x16_bf16 v[0:15], v[70:73], v[114:117], v[0:15]
	v_mfma_f32_32x32x16_bf16 v[48:63], v[118:121], v[122:125], v[48:63]
	v_mfma_f32_32x32x16_bf16 v[32:47], v[118:121], v[126:129], v[32:47]
	v_mfma_f32_32x32x16_bf16 v[16:31], v[118:121], v[130:133], v[16:31]
	v_mfma_f32_32x32x16_bf16 v[0:15], v[118:121], v[134:137], v[0:15]
	v_mfma_f32_32x32x16_bf16 v[48:63], v[138:141], v[162:165], v[48:63]
	v_mfma_f32_32x32x16_bf16 v[32:47], v[138:141], v[166:169], v[32:47]
	v_mfma_f32_32x32x16_bf16 v[16:31], v[138:141], v[170:173], v[16:31]
	v_mfma_f32_32x32x16_bf16 v[0:15], v[138:141], v[174:177], v[0:15]
	v_mfma_f32_32x32x16_bf16 v[48:63], v[178:181], v[182:185], v[48:63]
	v_mfma_f32_32x32x16_bf16 v[32:47], v[178:181], v[186:189], v[32:47]
	v_mfma_f32_32x32x16_bf16 v[16:31], v[178:181], v[190:193], v[16:31]
	v_mfma_f32_32x32x16_bf16 v[0:15], v[178:181], v[194:197], v[0:15]
	s_setprio 0
	s_waitcnt vmcnt(0)
	s_barrier
	ds_read_b128 v[70:73], v93 offset:32768
	ds_read_b128 v[102:105], v94 offset:49152
	ds_read_b128 v[106:109], v94 offset:53248
	ds_read_b128 v[110:113], v94 offset:57344
	ds_read_b128 v[114:117], v94 offset:61440
	ds_read_b128 v[118:121], v95 offset:32768
	ds_read_b128 v[122:125], v96 offset:49152
	ds_read_b128 v[126:129], v96 offset:53248
	ds_read_b128 v[130:133], v96 offset:57344
	ds_read_b128 v[134:137], v96 offset:61440
	ds_read_b128 v[138:141], v97 offset:32768
	ds_read_b128 v[162:165], v98 offset:49152
	ds_read_b128 v[166:169], v98 offset:53248
	ds_read_b128 v[170:173], v98 offset:57344
	ds_read_b128 v[174:177], v98 offset:61440
	ds_read_b128 v[178:181], v99 offset:32768
	ds_read_b128 v[182:185], v100 offset:49152
	ds_read_b128 v[186:189], v100 offset:53248
	ds_read_b128 v[190:193], v100 offset:57344
	ds_read_b128 v[194:197], v100 offset:61440
	s_waitcnt lgkmcnt(0)
	s_barrier
	s_setprio 1
	v_mfma_f32_32x32x16_bf16 v[48:63], v[70:73], v[102:105], v[48:63]
	v_mfma_f32_32x32x16_bf16 v[32:47], v[70:73], v[106:109], v[32:47]
	v_mfma_f32_32x32x16_bf16 v[16:31], v[70:73], v[110:113], v[16:31]
	v_mfma_f32_32x32x16_bf16 v[0:15], v[70:73], v[114:117], v[0:15]
	v_mfma_f32_32x32x16_bf16 v[48:63], v[118:121], v[122:125], v[48:63]
	v_mfma_f32_32x32x16_bf16 v[32:47], v[118:121], v[126:129], v[32:47]
	v_mfma_f32_32x32x16_bf16 v[16:31], v[118:121], v[130:133], v[16:31]
	v_mfma_f32_32x32x16_bf16 v[0:15], v[118:121], v[134:137], v[0:15]
	v_mfma_f32_32x32x16_bf16 v[48:63], v[138:141], v[162:165], v[48:63]
	v_mfma_f32_32x32x16_bf16 v[32:47], v[138:141], v[166:169], v[32:47]
	v_mfma_f32_32x32x16_bf16 v[16:31], v[138:141], v[170:173], v[16:31]
	v_mfma_f32_32x32x16_bf16 v[0:15], v[138:141], v[174:177], v[0:15]
	v_mfma_f32_32x32x16_bf16 v[48:63], v[178:181], v[182:185], v[48:63]
	v_mfma_f32_32x32x16_bf16 v[32:47], v[178:181], v[186:189], v[32:47]
	v_mfma_f32_32x32x16_bf16 v[16:31], v[178:181], v[190:193], v[16:31]
	v_mfma_f32_32x32x16_bf16 v[0:15], v[178:181], v[194:197], v[0:15]
	s_setprio 0
	s_branch .LBB0_1636
